# speedup vs baseline: 1.0200x; 1.0042x over previous
; DEVFI float bf2f(bfraw h) { return __uint_as_float(((unsigned)h) << 16); }
; DEVFI bfraw f2bf(float x) { unsigned u = __float_as_uint(x); u += 0x7fffu + ((u >> 16) & 1u); return (bfraw)(u >> 16); }
; __global__ void __launch_bounds__(512) mega(Params p) {
;     ...
;         for (int bi = bid; bi < 128 * 8; bi += nb) {
;           int tz = tid; asm volatile("" : "+v"(tz));
;           const int ew = __builtin_amdgcn_readfirstlane(tz >> 6), lz = tz & 63, fr = tz & 15, fq = (tz >> 4) & 3;
;           const int head = bi & 7, chunk = bi >> 3;
;           const float lgf = lgt_[head], lgb = lgt_[8 + head];
;           const bfraw* vt = rvt_ + ((long)(chunk * 8 + head) * 128) * 128;
;           const bfraw* kt = rkt_ + ((long)(chunk * 8 + head) * 128) * 128;
;           __syncthreads();
; #pragma unroll
;           for (int g = 0; g < 4; ++g) { const int blk = g * 8 + ew, row = blk * 4 + (lz >> 4), c = (lz ^ row) & 15;
;             __builtin_amdgcn_global_load_lds((const unsigned*)(vt + row * 128 + c * 8), (unsigned*)(shm + blk * 1024), 16, 0, 0); }
;           bf16x8 Af[4], Ab[4];
; #pragma unroll
;           for (int sx = 0; sx < 4; ++sx) { const bf16x8 raw = *(const bf16x8*)(kt + (ew * 16 + fr) * 128 + sx * 32 + fq * 8);
; #pragma unroll
;             for (int i = 0; i < 8; ++i) { const int mm = sx * 32 + fq * 8 + i; const float x = bf2f((bfraw)raw[i]);
;               Af[sx][i] = (short)f2bf(x * __expf(lgf * (float)(127 - mm))); Ab[sx][i] = (short)f2bf(x * __expf(lgb * (float)mm)); } }
.LBB0_2423:
	v_mov_b32_e32 v2, v8
	s_nop 0
	v_readfirstlane_b32 s17, v2
	s_ashr_i32 s18, s17, 6
	s_and_b32 s17, s15, 7
	s_lshl_b32 s17, s17, 2
	v_bfe_u32 v5, v2, 4, 2
	v_mov_b32_e32 v0, s17
	s_lshl_b32 s17, s18, 2
	global_load_dword v11, v0, s[6:7]
	global_load_dword v10, v0, s[6:7] offset:32
	v_or_b32_e32 v0, s17, v5
	v_bitop3_b32 v3, v0, 15, v2 bitop3:0x48
	v_lshlrev_b32_e32 v0, 7, v5
	v_lshl_or_b32 v0, s18, 9, v0
	v_ashrrev_i32_e32 v1, 31, v0
	v_lshlrev_b64 v[0:1], 1, v[0:1]
	s_add_u32 s20, s12, s70
	v_lshl_or_b32 v0, v3, 4, v0
	s_addc_u32 s21, s14, s71
	v_lshl_add_u64 v[0:1], s[20:21], 0, v[0:1]
	s_lshl_b32 m0, s18, 10
	s_add_i32 s19, s18, 8
	s_barrier
	global_load_lds_dwordx4 v[0:1], off
	v_lshl_or_b32 v0, s19, 2, v5
	s_add_i32 s22, s17, 32
	v_bitop3_b32 v3, v0, 15, v2 bitop3:0x48
	v_or_b32_e32 v0, s22, v5
	v_lshlrev_b32_e32 v0, 7, v0
	v_ashrrev_i32_e32 v1, 31, v0
	v_lshlrev_b64 v[0:1], 1, v[0:1]
	v_lshl_or_b32 v0, v3, 4, v0
	v_lshl_add_u64 v[0:1], s[20:21], 0, v[0:1]
	s_lshl_b32 m0, s19, 10
	s_add_i32 s19, s18, 16
	global_load_lds_dwordx4 v[0:1], off
	v_lshl_or_b32 v0, s19, 2, v5
	s_add_i32 s22, s17, 64
	v_bitop3_b32 v3, v0, 15, v2 bitop3:0x48
	v_or_b32_e32 v0, s22, v5
	v_lshlrev_b32_e32 v0, 7, v0
	v_ashrrev_i32_e32 v1, 31, v0
	v_lshlrev_b64 v[0:1], 1, v[0:1]
	v_lshl_or_b32 v0, v3, 4, v0
	v_lshl_add_u64 v[0:1], s[20:21], 0, v[0:1]
	s_lshl_b32 m0, s19, 10
	s_add_i32 s19, s18, 24
	global_load_lds_dwordx4 v[0:1], off
	v_lshl_or_b32 v0, s19, 2, v5
	s_addk_i32 s17, 0x60
	v_bitop3_b32 v3, v0, 15, v2 bitop3:0x48
	v_or_b32_e32 v0, s17, v5
	v_lshlrev_b32_e32 v0, 7, v0
	v_ashrrev_i32_e32 v1, 31, v0
	v_lshlrev_b64 v[0:1], 1, v[0:1]
	v_lshl_or_b32 v0, v3, 4, v0
	v_lshl_add_u64 v[0:1], s[20:21], 0, v[0:1]
	s_lshl_b32 m0, s19, 10
	v_and_b32_e32 v12, 15, v2
	global_load_lds_dwordx4 v[0:1], off
	v_lshlrev_b32_e32 v0, 7, v12
	v_lshl_or_b32 v0, s18, 11, v0
	v_ashrrev_i32_e32 v1, 31, v0
	v_lshlrev_b64 v[0:1], 1, v[0:1]
	s_add_u32 s20, s8, s70
	v_lshl_or_b32 v0, v5, 4, v0
	s_addc_u32 s21, s9, s71
	v_lshl_add_u64 v[0:1], s[20:21], 0, v[0:1]
	s_mov_b32 s17, 0x15720000
	v_add_co_u32_e32 v6, vcc, s17, v0
	v_lshrrev_b32_e32 v9, 4, v2
	s_nop 0
	v_addc_co_u32_e32 v7, vcc, 0, v1, vcc
	global_load_dwordx4 v[0:3], v[6:7], off
	v_lshlrev_b32_e32 v4, 3, v5
	v_xor_b32_e32 v13, 0x7f, v4
	v_cvt_f32_ubyte0_e32 v13, v13
	v_xor_b32_e32 v15, 0x7e, v4
	v_cvt_f32_ubyte0_e32 v15, v15
	v_lshlrev_b32_e32 v176, 8, v12
	s_waitcnt vmcnt(0)
	v_mul_f32_e32 v13, v11, v13
	v_mul_f32_e32 v13, 0x3fb8aa3b, v13
	v_exp_f32_e32 v14, v13
	v_cvt_f32_ubyte0_e32 v13, v4
	v_mul_f32_e32 v13, v10, v13
	v_mul_f32_e32 v13, 0x3fb8aa3b, v13
	v_exp_f32_e32 v16, v13
	v_or_b32_e32 v13, 1, v4
	v_cvt_f32_ubyte0_e32 v13, v13
	v_mul_f32_e32 v15, v11, v15
	v_mul_f32_e32 v13, v10, v13
	v_mul_f32_e32 v15, 0x3fb8aa3b, v15
	v_mul_f32_e32 v13, 0x3fb8aa3b, v13
	v_exp_f32_e32 v15, v15
	v_exp_f32_e32 v17, v13
	v_xor_b32_e32 v13, 0x7d, v4
	v_cvt_f32_ubyte0_e32 v13, v13
	v_mul_f32_e32 v13, v11, v13
	v_mul_f32_e32 v13, 0x3fb8aa3b, v13
	v_and_b32_e32 v19, 0xffff0000, v0
	v_lshlrev_b32_e32 v18, 16, v0
	v_or_b32_e32 v0, 2, v4
	v_cvt_f32_ubyte0_e32 v0, v0
	v_mul_f32_e32 v0, v10, v0
	v_mul_f32_e32 v0, 0x3fb8aa3b, v0
	v_pk_mul_f32 v[24:25], v[16:17], v[18:19]
	v_pk_mul_f32 v[14:15], v[14:15], v[18:19]
	v_exp_f32_e32 v16, v13
	v_exp_f32_e32 v18, v0
	v_or_b32_e32 v0, 3, v4
	v_xor_b32_e32 v13, 0x7c, v4
	v_cvt_f32_ubyte0_e32 v13, v13
	v_cvt_f32_ubyte0_e32 v0, v0
	v_mul_f32_e32 v13, v11, v13
	v_mul_f32_e32 v0, v10, v0
	v_mul_f32_e32 v13, 0x3fb8aa3b, v13
	v_mul_f32_e32 v0, 0x3fb8aa3b, v0
	v_exp_f32_e32 v17, v13
	v_exp_f32_e32 v19, v0
	v_or_b32_e32 v13, 4, v4
	v_cvt_f32_ubyte0_e32 v13, v13
	v_mul_f32_e32 v13, v10, v13
	v_and_b32_e32 v21, 0xffff0000, v1
	v_lshlrev_b32_e32 v20, 16, v1
	v_mul_f32_e32 v13, 0x3fb8aa3b, v13
	v_pk_mul_f32 v[0:1], v[18:19], v[20:21]
	v_pk_mul_f32 v[16:17], v[16:17], v[20:21]
	v_xor_b32_e32 v18, 0x7b, v4
	v_exp_f32_e32 v20, v13
	v_or_b32_e32 v13, 5, v4
	v_xor_b32_e32 v19, 0x7a, v4
	v_cvt_f32_ubyte0_e32 v18, v18
	v_cvt_f32_ubyte0_e32 v19, v19
	v_cvt_f32_ubyte0_e32 v13, v13
	v_mul_f32_e32 v18, v11, v18
	v_mul_f32_e32 v19, v11, v19
	v_mul_f32_e32 v13, v10, v13
	v_mul_f32_e32 v18, 0x3fb8aa3b, v18
	v_mul_f32_e32 v19, 0x3fb8aa3b, v19
	v_mul_f32_e32 v13, 0x3fb8aa3b, v13
	v_exp_f32_e32 v18, v18
	v_exp_f32_e32 v19, v19
	v_exp_f32_e32 v21, v13
	v_and_b32_e32 v23, 0xffff0000, v2
	v_lshlrev_b32_e32 v22, 16, v2
	v_or_b32_e32 v2, 6, v4
	v_xor_b32_e32 v13, 0x79, v4
	v_cvt_f32_ubyte0_e32 v13, v13
	v_cvt_f32_ubyte0_e32 v2, v2
	v_mul_f32_e32 v13, v11, v13
	v_mul_f32_e32 v2, v10, v2
	v_mul_f32_e32 v13, 0x3fb8aa3b, v13
	v_mul_f32_e32 v2, 0x3fb8aa3b, v2
	v_pk_mul_f32 v[26:27], v[20:21], v[22:23]
	v_pk_mul_f32 v[18:19], v[18:19], v[22:23]
	v_exp_f32_e32 v20, v13
	v_exp_f32_e32 v22, v2
	v_or_b32_e32 v2, 7, v4
	v_xor_b32_e32 v13, 0x78, v4
	v_cvt_f32_ubyte0_e32 v13, v13
	v_cvt_f32_ubyte0_e32 v2, v2
	v_mul_f32_e32 v13, v11, v13
	v_mul_f32_e32 v2, v10, v2
	v_mul_f32_e32 v13, 0x3fb8aa3b, v13
	v_mul_f32_e32 v2, 0x3fb8aa3b, v2
	v_exp_f32_e32 v21, v13
	v_exp_f32_e32 v23, v2
	v_and_b32_e32 v29, 0xffff0000, v3
	v_lshlrev_b32_e32 v28, 16, v3
	v_pk_mul_f32 v[2:3], v[22:23], v[28:29]
	v_pk_mul_f32 v[22:23], v[20:21], v[28:29]
	v_cvt_pk_bf16_f32 v13, v14, v14
	v_cvt_pk_bf16_f32 v14, v15, v15
	v_cvt_pk_bf16_f32 v15, v16, v16
	v_cvt_pk_bf16_f32 v16, v17, v17
	v_cvt_pk_bf16_f32 v17, v18, v18
	v_cvt_pk_bf16_f32 v19, v19, v19
	v_cvt_pk_bf16_f32 v21, v22, v22
	v_cvt_pk_bf16_f32 v23, v23, v23
	v_cvt_pk_bf16_f32 v18, v24, v24
	v_cvt_pk_bf16_f32 v20, v25, v25
	v_cvt_pk_bf16_f32 v22, v0, v0
	v_cvt_pk_bf16_f32 v24, v1, v1
	v_cvt_pk_bf16_f32 v25, v26, v26
	v_cvt_pk_bf16_f32 v26, v27, v27
	v_cvt_pk_bf16_f32 v27, v2, v2
	v_cvt_pk_bf16_f32 v28, v3, v3
	global_load_dwordx4 v[0:3], v[6:7], off offset:64
	v_or_b32_e32 v29, 32, v4
	v_cvt_f32_ubyte0_e32 v29, v29
	v_mul_f32_e32 v29, v10, v29
	v_mul_f32_e32 v29, 0x3fb8aa3b, v29
	v_xor_b32_e32 v30, 0x5f, v4
	v_exp_f32_e32 v32, v29
	v_or_b32_e32 v29, 33, v4
	v_xor_b32_e32 v31, 0x5e, v4
	v_cvt_f32_ubyte0_e32 v30, v30
	v_cvt_f32_ubyte0_e32 v31, v31
	v_cvt_f32_ubyte0_e32 v29, v29
	v_mul_f32_e32 v30, v11, v30
	v_mul_f32_e32 v31, v11, v31
	v_mul_f32_e32 v29, v10, v29
	v_mul_f32_e32 v30, 0x3fb8aa3b, v30
	v_mul_f32_e32 v31, 0x3fb8aa3b, v31
	v_mul_f32_e32 v29, 0x3fb8aa3b, v29
	v_exp_f32_e32 v30, v30
	v_exp_f32_e32 v31, v31
	v_exp_f32_e32 v33, v29
	v_xor_b32_e32 v29, 0x5d, v4
	v_cvt_f32_ubyte0_e32 v29, v29
	v_mul_f32_e32 v29, v11, v29
	v_mul_f32_e32 v29, 0x3fb8aa3b, v29
	s_waitcnt vmcnt(0)
; DEVFI float bf2f(bfraw h) { return __uint_as_float(((unsigned)h) << 16); }
; DEVFI bfraw f2bf(float x) { unsigned u = __float_as_uint(x); u += 0x7fffu + ((u >> 16) & 1u); return (bfraw)(u >> 16); }
; __global__ void __launch_bounds__(512) mega(Params p) {
;     ...
;           for (int sx = 0; sx < 4; ++sx) { const bf16x8 raw = *(const bf16x8*)(kt + (ew * 16 + fr) * 128 + sx * 32 + fq * 8);
; #pragma unroll
;             for (int i = 0; i < 8; ++i) { const int mm = sx * 32 + fq * 8 + i; const float x = bf2f((bfraw)raw[i]);
;               Af[sx][i] = (short)f2bf(x * __expf(lgf * (float)(127 - mm))); Ab[sx][i] = (short)f2bf(x * __expf(lgb * (float)mm)); } }
	v_and_b32_e32 v35, 0xffff0000, v0
	v_lshlrev_b32_e32 v34, 16, v0
	v_or_b32_e32 v0, 34, v4
	v_cvt_f32_ubyte0_e32 v0, v0
	v_mul_f32_e32 v0, v10, v0
	v_mul_f32_e32 v0, 0x3fb8aa3b, v0
	v_pk_mul_f32 v[40:41], v[32:33], v[34:35]
	v_pk_mul_f32 v[30:31], v[30:31], v[34:35]
	v_exp_f32_e32 v32, v29
	v_exp_f32_e32 v34, v0
	v_or_b32_e32 v0, 35, v4
	v_xor_b32_e32 v29, 0x5c, v4
	v_cvt_f32_ubyte0_e32 v29, v29
	v_cvt_f32_ubyte0_e32 v0, v0
	v_mul_f32_e32 v29, v11, v29
	v_mul_f32_e32 v0, v10, v0
	v_mul_f32_e32 v29, 0x3fb8aa3b, v29
	v_mul_f32_e32 v0, 0x3fb8aa3b, v0
	v_exp_f32_e32 v33, v29
	v_exp_f32_e32 v35, v0
	v_or_b32_e32 v29, 36, v4
	v_cvt_f32_ubyte0_e32 v29, v29
	v_mul_f32_e32 v29, v10, v29
	v_and_b32_e32 v37, 0xffff0000, v1
	v_lshlrev_b32_e32 v36, 16, v1
	v_mul_f32_e32 v29, 0x3fb8aa3b, v29
	v_pk_mul_f32 v[0:1], v[34:35], v[36:37]
	v_pk_mul_f32 v[32:33], v[32:33], v[36:37]
	v_xor_b32_e32 v34, 0x5b, v4
	v_exp_f32_e32 v36, v29
	v_or_b32_e32 v29, 37, v4
	v_xor_b32_e32 v35, 0x5a, v4
	v_cvt_f32_ubyte0_e32 v34, v34
	v_cvt_f32_ubyte0_e32 v35, v35
	v_cvt_f32_ubyte0_e32 v29, v29
	v_mul_f32_e32 v34, v11, v34
	v_mul_f32_e32 v35, v11, v35
	v_mul_f32_e32 v29, v10, v29
	v_mul_f32_e32 v34, 0x3fb8aa3b, v34
	v_mul_f32_e32 v35, 0x3fb8aa3b, v35
	v_mul_f32_e32 v29, 0x3fb8aa3b, v29
	v_exp_f32_e32 v34, v34
	v_exp_f32_e32 v35, v35
	v_exp_f32_e32 v37, v29
	v_and_b32_e32 v39, 0xffff0000, v2
	v_lshlrev_b32_e32 v38, 16, v2
	v_or_b32_e32 v2, 38, v4
	v_xor_b32_e32 v29, 0x59, v4
	v_cvt_f32_ubyte0_e32 v29, v29
	v_cvt_f32_ubyte0_e32 v2, v2
	v_mul_f32_e32 v29, v11, v29
	v_mul_f32_e32 v2, v10, v2
	v_mul_f32_e32 v29, 0x3fb8aa3b, v29
	v_mul_f32_e32 v2, 0x3fb8aa3b, v2
	v_pk_mul_f32 v[42:43], v[36:37], v[38:39]
	v_pk_mul_f32 v[34:35], v[34:35], v[38:39]
	v_exp_f32_e32 v36, v29
	v_exp_f32_e32 v38, v2
	v_or_b32_e32 v2, 39, v4
	v_xor_b32_e32 v29, 0x58, v4
	v_cvt_f32_ubyte0_e32 v29, v29
	v_cvt_f32_ubyte0_e32 v2, v2
	v_mul_f32_e32 v29, v11, v29
	v_mul_f32_e32 v2, v10, v2
	v_mul_f32_e32 v29, 0x3fb8aa3b, v29
	v_mul_f32_e32 v2, 0x3fb8aa3b, v2
	v_exp_f32_e32 v37, v29
	v_exp_f32_e32 v39, v2
	v_and_b32_e32 v45, 0xffff0000, v3
	v_lshlrev_b32_e32 v44, 16, v3
	v_pk_mul_f32 v[2:3], v[38:39], v[44:45]
	v_pk_mul_f32 v[38:39], v[36:37], v[44:45]
	v_cvt_pk_bf16_f32 v29, v30, v30
	v_cvt_pk_bf16_f32 v30, v31, v31
	v_cvt_pk_bf16_f32 v31, v32, v32
	v_cvt_pk_bf16_f32 v32, v33, v33
	v_cvt_pk_bf16_f32 v33, v34, v34
	v_cvt_pk_bf16_f32 v34, v35, v35
	v_cvt_pk_bf16_f32 v37, v38, v38
	v_cvt_pk_bf16_f32 v38, v39, v39
	v_cvt_pk_bf16_f32 v35, v40, v40
	v_cvt_pk_bf16_f32 v36, v41, v41
	v_cvt_pk_bf16_f32 v39, v0, v0
	v_cvt_pk_bf16_f32 v40, v1, v1
	v_cvt_pk_bf16_f32 v41, v42, v42
	v_cvt_pk_bf16_f32 v42, v43, v43
	v_cvt_pk_bf16_f32 v43, v2, v2
	v_cvt_pk_bf16_f32 v44, v3, v3
	global_load_dwordx4 v[0:3], v[6:7], off offset:128
	v_or_b32_e32 v45, 64, v4
	v_cvt_f32_ubyte0_e32 v45, v45
	v_mul_f32_e32 v45, v10, v45
	v_mul_f32_e32 v45, 0x3fb8aa3b, v45
	v_xor_b32_e32 v46, 63, v4
	v_exp_f32_e32 v48, v45
	v_or_b32_e32 v45, 0x41, v4
	v_xor_b32_e32 v47, 62, v4
	v_cvt_f32_ubyte0_e32 v46, v46
	v_cvt_f32_ubyte0_e32 v47, v47
	v_cvt_f32_ubyte0_e32 v45, v45
	v_mul_f32_e32 v46, v11, v46
	v_mul_f32_e32 v47, v11, v47
	v_mul_f32_e32 v45, v10, v45
	v_mul_f32_e32 v46, 0x3fb8aa3b, v46
	v_mul_f32_e32 v47, 0x3fb8aa3b, v47
	v_mul_f32_e32 v45, 0x3fb8aa3b, v45
	v_exp_f32_e32 v46, v46
	v_exp_f32_e32 v47, v47
	v_exp_f32_e32 v49, v45
	v_xor_b32_e32 v45, 61, v4
	v_cvt_f32_ubyte0_e32 v45, v45
	v_mul_f32_e32 v45, v11, v45
	v_mul_f32_e32 v45, 0x3fb8aa3b, v45
	s_waitcnt vmcnt(0)
	v_and_b32_e32 v51, 0xffff0000, v0
	v_lshlrev_b32_e32 v50, 16, v0
	v_or_b32_e32 v0, 0x42, v4
	v_cvt_f32_ubyte0_e32 v0, v0
	v_mul_f32_e32 v0, v10, v0
	v_mul_f32_e32 v0, 0x3fb8aa3b, v0
	v_pk_mul_f32 v[56:57], v[48:49], v[50:51]
	v_pk_mul_f32 v[46:47], v[46:47], v[50:51]
	v_exp_f32_e32 v48, v45
	v_exp_f32_e32 v50, v0
	v_or_b32_e32 v0, 0x43, v4
	v_xor_b32_e32 v45, 60, v4
	v_cvt_f32_ubyte0_e32 v45, v45
	v_cvt_f32_ubyte0_e32 v0, v0
	v_mul_f32_e32 v45, v11, v45
	v_mul_f32_e32 v0, v10, v0
	v_mul_f32_e32 v45, 0x3fb8aa3b, v45
	v_mul_f32_e32 v0, 0x3fb8aa3b, v0
	v_exp_f32_e32 v49, v45
	v_exp_f32_e32 v51, v0
	v_or_b32_e32 v45, 0x44, v4
	v_cvt_f32_ubyte0_e32 v45, v45
	v_mul_f32_e32 v45, v10, v45
	v_and_b32_e32 v53, 0xffff0000, v1
	v_lshlrev_b32_e32 v52, 16, v1
	v_mul_f32_e32 v45, 0x3fb8aa3b, v45
	v_pk_mul_f32 v[0:1], v[50:51], v[52:53]
	v_pk_mul_f32 v[48:49], v[48:49], v[52:53]
	v_xor_b32_e32 v50, 59, v4
	v_exp_f32_e32 v52, v45
	v_or_b32_e32 v45, 0x45, v4
	v_xor_b32_e32 v51, 58, v4
	v_cvt_f32_ubyte0_e32 v50, v50
	v_cvt_f32_ubyte0_e32 v51, v51
	v_cvt_f32_ubyte0_e32 v45, v45
	v_mul_f32_e32 v50, v11, v50
	v_mul_f32_e32 v51, v11, v51
	v_mul_f32_e32 v45, v10, v45
	v_mul_f32_e32 v50, 0x3fb8aa3b, v50
	v_mul_f32_e32 v51, 0x3fb8aa3b, v51
	v_mul_f32_e32 v45, 0x3fb8aa3b, v45
	v_exp_f32_e32 v50, v50
	v_exp_f32_e32 v51, v51
	v_exp_f32_e32 v53, v45
	v_and_b32_e32 v55, 0xffff0000, v2
	v_lshlrev_b32_e32 v54, 16, v2
	v_or_b32_e32 v2, 0x46, v4
	v_xor_b32_e32 v45, 57, v4
	v_cvt_f32_ubyte0_e32 v45, v45
	v_cvt_f32_ubyte0_e32 v2, v2
	v_mul_f32_e32 v45, v11, v45
	v_mul_f32_e32 v2, v10, v2
	v_mul_f32_e32 v45, 0x3fb8aa3b, v45
	v_mul_f32_e32 v2, 0x3fb8aa3b, v2
	v_pk_mul_f32 v[58:59], v[52:53], v[54:55]
	v_pk_mul_f32 v[50:51], v[50:51], v[54:55]
	v_exp_f32_e32 v52, v45
	v_exp_f32_e32 v54, v2
	v_or_b32_e32 v2, 0x47, v4
	v_xor_b32_e32 v45, 56, v4
	v_cvt_f32_ubyte0_e32 v45, v45
	v_cvt_f32_ubyte0_e32 v2, v2
	v_mul_f32_e32 v45, v11, v45
	v_mul_f32_e32 v2, v10, v2
	v_mul_f32_e32 v45, 0x3fb8aa3b, v45
	v_mul_f32_e32 v2, 0x3fb8aa3b, v2
	v_exp_f32_e32 v53, v45
	v_exp_f32_e32 v55, v2
	v_and_b32_e32 v61, 0xffff0000, v3
	v_lshlrev_b32_e32 v60, 16, v3
	v_pk_mul_f32 v[2:3], v[54:55], v[60:61]
	v_pk_mul_f32 v[54:55], v[52:53], v[60:61]
	v_cvt_pk_bf16_f32 v45, v46, v46
	v_cvt_pk_bf16_f32 v46, v47, v47
	v_cvt_pk_bf16_f32 v47, v48, v48
	v_cvt_pk_bf16_f32 v48, v49, v49
	v_cvt_pk_bf16_f32 v49, v50, v50
	v_cvt_pk_bf16_f32 v50, v51, v51
	v_cvt_pk_bf16_f32 v53, v54, v54
	v_cvt_pk_bf16_f32 v54, v55, v55
	v_cvt_pk_bf16_f32 v51, v56, v56
	v_cvt_pk_bf16_f32 v52, v57, v57
	v_cvt_pk_bf16_f32 v55, v0, v0
	v_cvt_pk_bf16_f32 v56, v1, v1
	v_cvt_pk_bf16_f32 v57, v58, v58
	v_cvt_pk_bf16_f32 v58, v59, v59
	v_cvt_pk_bf16_f32 v59, v2, v2
	v_cvt_pk_bf16_f32 v60, v3, v3
	global_load_dwordx4 v[0:3], v[6:7], off offset:192
	v_or_b32_e32 v7, 0x60, v4
	v_cvt_f32_ubyte0_e32 v7, v7
	v_mul_f32_e32 v7, v10, v7
	v_mul_f32_e32 v7, 0x3fb8aa3b, v7
	v_xor_b32_e32 v6, 31, v4
	v_exp_f32_e32 v62, v7
	v_or_b32_e32 v61, 0x61, v4
	v_xor_b32_e32 v7, 30, v4
	v_cvt_f32_ubyte0_e32 v6, v6
	v_cvt_f32_ubyte0_e32 v7, v7
	v_cvt_f32_ubyte0_e32 v61, v61
	v_mul_f32_e32 v6, v11, v6
	v_mul_f32_e32 v7, v11, v7
	v_mul_f32_e32 v61, v10, v61
	v_mul_f32_e32 v6, 0x3fb8aa3b, v6
	v_mul_f32_e32 v7, 0x3fb8aa3b, v7
	v_mul_f32_e32 v61, 0x3fb8aa3b, v61
	v_exp_f32_e32 v6, v6
	v_exp_f32_e32 v7, v7
	v_exp_f32_e32 v63, v61
	v_xor_b32_e32 v61, 29, v4
	v_cvt_f32_ubyte0_e32 v61, v61
	v_mul_f32_e32 v61, v11, v61
	v_mul_f32_e32 v61, 0x3fb8aa3b, v61
	s_waitcnt vmcnt(0)
; DEVFI float bf2f(bfraw h) { return __uint_as_float(((unsigned)h) << 16); }
; DEVFI bfraw f2bf(float x) { unsigned u = __float_as_uint(x); u += 0x7fffu + ((u >> 16) & 1u); return (bfraw)(u >> 16); }
; #define SBAR() __builtin_amdgcn_sched_barrier(0)
; #define WAIT_V0() asm volatile("s_waitcnt vmcnt(0)" ::: "memory")
; __global__ void __launch_bounds__(512) mega(Params p) {
;     ...
;           for (int sx = 0; sx < 4; ++sx) { const bf16x8 raw = *(const bf16x8*)(kt + (ew * 16 + fr) * 128 + sx * 32 + fq * 8);
; #pragma unroll
;             for (int i = 0; i < 8; ++i) { const int mm = sx * 32 + fq * 8 + i; const float x = bf2f((bfraw)raw[i]);
;               Af[sx][i] = (short)f2bf(x * __expf(lgf * (float)(127 - mm))); Ab[sx][i] = (short)f2bf(x * __expf(lgb * (float)mm)); } }
;           WAIT_V0(); __syncthreads();
;           f32x4 accf[8] = {}, accb[8] = {};
; #pragma unroll
;           for (int g2 = 0; g2 < 4; ++g2) { bf16x8 B[2][4];
; #pragma unroll
;             for (int q4 = 0; q4 < 2; ++q4)
; #pragma unroll
;               for (int sx = 0; sx < 4; ++sx) B[q4][sx] = RLD16(0, (g2 * 2 + q4) * 16 + fr, sx * 4 + fq);
;             SBAR();
; #pragma unroll
;             for (int q4 = 0; q4 < 2; ++q4)
; #pragma unroll
;               for (int sx = 0; sx < 4; ++sx) { accf[g2 * 2 + q4] = __builtin_amdgcn_mfma_f32_16x16x32_bf16(Af[sx], B[q4][sx], accf[g2 * 2 + q4], 0, 0, 0);
;                 accb[g2 * 2 + q4] = __builtin_amdgcn_mfma_f32_16x16x32_bf16(Ab[sx], B[q4][sx], accb[g2 * 2 + q4], 0, 0, 0); }
;             SBAR(); }
	s_waitcnt lgkmcnt(0)
	s_barrier
	s_waitcnt vmcnt(0)
	v_and_b32_e32 v65, 0xffff0000, v0
	v_lshlrev_b32_e32 v64, 16, v0
	v_or_b32_e32 v0, 0x62, v4
	v_cvt_f32_ubyte0_e32 v0, v0
	v_mul_f32_e32 v0, v10, v0
	v_mul_f32_e32 v0, 0x3fb8aa3b, v0
	v_pk_mul_f32 v[62:63], v[62:63], v[64:65]
	v_pk_mul_f32 v[6:7], v[6:7], v[64:65]
	v_exp_f32_e32 v64, v61
	v_exp_f32_e32 v66, v0
	v_or_b32_e32 v0, 0x63, v4
	v_xor_b32_e32 v61, 28, v4
	v_cvt_f32_ubyte0_e32 v61, v61
	v_cvt_f32_ubyte0_e32 v0, v0
	v_mul_f32_e32 v61, v11, v61
	v_mul_f32_e32 v0, v10, v0
	v_mul_f32_e32 v61, 0x3fb8aa3b, v61
	v_mul_f32_e32 v0, 0x3fb8aa3b, v0
	v_exp_f32_e32 v65, v61
	v_exp_f32_e32 v67, v0
	v_or_b32_e32 v61, 0x64, v4
	v_cvt_f32_ubyte0_e32 v61, v61
	v_mul_f32_e32 v61, v10, v61
	v_and_b32_e32 v69, 0xffff0000, v1
	v_lshlrev_b32_e32 v68, 16, v1
	v_mul_f32_e32 v61, 0x3fb8aa3b, v61
	v_pk_mul_f32 v[0:1], v[66:67], v[68:69]
	v_pk_mul_f32 v[64:65], v[64:65], v[68:69]
	v_xor_b32_e32 v66, 27, v4
	v_exp_f32_e32 v68, v61
	v_or_b32_e32 v61, 0x65, v4
	v_xor_b32_e32 v67, 26, v4
	v_cvt_f32_ubyte0_e32 v66, v66
	v_cvt_f32_ubyte0_e32 v67, v67
	v_cvt_f32_ubyte0_e32 v61, v61
	v_mul_f32_e32 v66, v11, v66
	v_mul_f32_e32 v67, v11, v67
	v_mul_f32_e32 v61, v10, v61
	v_mul_f32_e32 v66, 0x3fb8aa3b, v66
	v_mul_f32_e32 v67, 0x3fb8aa3b, v67
	v_mul_f32_e32 v61, 0x3fb8aa3b, v61
	v_exp_f32_e32 v66, v66
	v_exp_f32_e32 v67, v67
	v_exp_f32_e32 v69, v61
	v_and_b32_e32 v71, 0xffff0000, v2
	v_lshlrev_b32_e32 v70, 16, v2
	v_or_b32_e32 v2, 0x66, v4
	v_xor_b32_e32 v61, 25, v4
	v_cvt_f32_ubyte0_e32 v61, v61
	v_cvt_f32_ubyte0_e32 v2, v2
	v_mul_f32_e32 v61, v11, v61
	v_mul_f32_e32 v2, v10, v2
	v_mul_f32_e32 v61, 0x3fb8aa3b, v61
	v_mul_f32_e32 v2, 0x3fb8aa3b, v2
	v_pk_mul_f32 v[68:69], v[68:69], v[70:71]
	v_pk_mul_f32 v[66:67], v[66:67], v[70:71]
	v_exp_f32_e32 v70, v61
	v_exp_f32_e32 v72, v2
	v_or_b32_e32 v2, 0x67, v4
	v_xor_b32_e32 v61, 24, v4
	v_cvt_f32_ubyte0_e32 v61, v61
	v_cvt_f32_ubyte0_e32 v2, v2
	v_mul_f32_e32 v11, v11, v61
	v_mul_f32_e32 v2, v10, v2
	v_mul_f32_e32 v11, 0x3fb8aa3b, v11
	v_mul_f32_e32 v2, 0x3fb8aa3b, v2
	v_exp_f32_e32 v71, v11
	v_exp_f32_e32 v73, v2
	v_and_b32_e32 v11, 0xffff0000, v3
	v_lshlrev_b32_e32 v10, 16, v3
	v_pk_mul_f32 v[2:3], v[72:73], v[10:11]
	v_pk_mul_f32 v[10:11], v[70:71], v[10:11]
	v_cvt_pk_bf16_f32 v98, v10, v10
	v_cvt_pk_bf16_f32 v97, v67, v67
	v_cvt_pk_bf16_f32 v106, v3, v3
	v_bitop3_b32 v10, v5, v12, 4 bitop3:0x36
	v_cvt_pk_bf16_f32 v101, v0, v0
	v_bitop3_b32 v0, v9, v12, 3 bitop3:0x6c
	v_lshl_or_b32 v107, v10, 4, v176
	v_bitop3_b32 v10, v5, v12, 8 bitop3:0x36
	v_bitop3_b32 v5, v5, v12, 12 bitop3:0x36
	v_cvt_pk_bf16_f32 v94, v64, v64
	v_cvt_pk_bf16_f32 v95, v65, v65
	v_cvt_pk_bf16_f32 v96, v66, v66
	v_cvt_pk_bf16_f32 v61, v11, v11
	v_lshl_or_b32 v9, v0, 4, v176
	v_lshl_or_b32 v108, v10, 4, v176
	v_lshl_or_b32 v5, v5, 4, v176
	v_cvt_pk_bf16_f32 v6, v6, v6
	v_cvt_pk_bf16_f32 v7, v7, v7
	v_cvt_pk_bf16_f32 v99, v62, v62
	v_cvt_pk_bf16_f32 v100, v63, v63
	v_cvt_pk_bf16_f32 v102, v1, v1
	v_cvt_pk_bf16_f32 v103, v68, v68
	v_cvt_pk_bf16_f32 v104, v69, v69
	v_cvt_pk_bf16_f32 v105, v2, v2
	ds_read_b128 v[0:3], v9
	ds_read_b128 v[62:65], v107
	ds_read_b128 v[66:69], v108
	ds_read_b128 v[70:73], v5
	ds_read_b128 v[74:77], v9 offset:4096
	ds_read_b128 v[78:81], v107 offset:4096
	ds_read_b128 v[82:85], v108 offset:4096
	ds_read_b128 v[86:89], v5 offset:4096
	v_perm_b32 v93, v23, v21, s58
	v_perm_b32 v92, v19, v17, s58
	v_perm_b32 v91, v16, v15, s58
	v_perm_b32 v90, v14, v13, s58
	v_perm_b32 v13, v28, v27, s58
	v_perm_b32 v12, v26, v25, s58
	v_perm_b32 v11, v24, v22, s58
	v_perm_b32 v10, v20, v18, s58
	v_perm_b32 v21, v38, v37, s58
	v_perm_b32 v20, v34, v33, s58
	v_perm_b32 v19, v32, v31, s58
	v_perm_b32 v18, v30, v29, s58
	v_perm_b32 v25, v44, v43, s58
	v_perm_b32 v24, v42, v41, s58
	v_perm_b32 v23, v40, v39, s58
	v_perm_b32 v22, v36, v35, s58
	s_waitcnt lgkmcnt(7)
	v_mfma_f32_16x16x32_bf16 v[14:17], v[90:93], v[0:3], 0
	v_perm_b32 v28, v50, v49, s58
	v_perm_b32 v27, v48, v47, s58
	v_perm_b32 v26, v46, v45, s58
	v_mfma_f32_16x16x32_bf16 v[0:3], v[10:13], v[0:3], 0
	v_perm_b32 v29, v54, v53, s58
	v_perm_b32 v33, v60, v59, s58
	v_perm_b32 v32, v58, v57, s58
	s_waitcnt lgkmcnt(3)
	v_mfma_f32_16x16x32_bf16 v[42:45], v[90:93], v[74:77], 0
	v_perm_b32 v31, v56, v55, s58
	v_perm_b32 v30, v52, v51, s58
	v_perm_b32 v37, v61, v98, s58
	v_mfma_f32_16x16x32_bf16 v[46:49], v[10:13], v[74:77], 0
	v_perm_b32 v36, v97, v96, s58
	v_perm_b32 v35, v95, v94, s58
	v_perm_b32 v34, v7, v6, s58
	v_mfma_f32_16x16x32_bf16 v[14:17], v[18:21], v[62:65], v[14:17]
	v_perm_b32 v41, v106, v105, s58
	v_perm_b32 v40, v104, v103, s58
	v_perm_b32 v39, v102, v101, s58
	v_mfma_f32_16x16x32_bf16 v[0:3], v[22:25], v[62:65], v[0:3]
	v_perm_b32 v38, v100, v99, s58
	s_waitcnt lgkmcnt(2)
	v_mfma_f32_16x16x32_bf16 v[42:45], v[18:21], v[78:81], v[42:45]
	v_mfma_f32_16x16x32_bf16 v[46:49], v[22:25], v[78:81], v[46:49]
	v_mfma_f32_16x16x32_bf16 v[14:17], v[26:29], v[66:69], v[14:17]
	v_mfma_f32_16x16x32_bf16 v[0:3], v[30:33], v[66:69], v[0:3]
	s_waitcnt lgkmcnt(1)
	v_mfma_f32_16x16x32_bf16 v[42:45], v[26:29], v[82:85], v[42:45]
	v_mfma_f32_16x16x32_bf16 v[46:49], v[30:33], v[82:85], v[46:49]
	v_mfma_f32_16x16x32_bf16 v[14:17], v[34:37], v[70:73], v[14:17]
	v_mfma_f32_16x16x32_bf16 v[0:3], v[38:41], v[70:73], v[0:3]
	s_waitcnt lgkmcnt(0)
	v_mfma_f32_16x16x32_bf16 v[42:45], v[34:37], v[86:89], v[42:45]
	v_mfma_f32_16x16x32_bf16 v[46:49], v[38:41], v[86:89], v[46:49]
	ds_read_b128 v[50:53], v9 offset:8192
	ds_read_b128 v[54:57], v9 offset:12288
	ds_read_b128 v[58:61], v107 offset:8192
	ds_read_b128 v[62:65], v107 offset:12288
	ds_read_b128 v[66:69], v108 offset:8192
	ds_read_b128 v[70:73], v108 offset:12288
	ds_read_b128 v[74:77], v5 offset:8192
	ds_read_b128 v[78:81], v5 offset:12288
	s_waitcnt lgkmcnt(7)
; #define SBAR() __builtin_amdgcn_sched_barrier(0)
; __global__ void __launch_bounds__(512) mega(Params p) {
;     ...
;           for (int g2 = 0; g2 < 4; ++g2) { bf16x8 B[2][4];
; #pragma unroll
;             for (int q4 = 0; q4 < 2; ++q4)
; #pragma unroll
;               for (int sx = 0; sx < 4; ++sx) B[q4][sx] = RLD16(0, (g2 * 2 + q4) * 16 + fr, sx * 4 + fq);
;             SBAR();
; #pragma unroll
;             for (int q4 = 0; q4 < 2; ++q4)
; #pragma unroll
;               for (int sx = 0; sx < 4; ++sx) { accf[g2 * 2 + q4] = __builtin_amdgcn_mfma_f32_16x16x32_bf16(Af[sx], B[q4][sx], accf[g2 * 2 + q4], 0, 0, 0);
;                 accb[g2 * 2 + q4] = __builtin_amdgcn_mfma_f32_16x16x32_bf16(Ab[sx], B[q4][sx], accb[g2 * 2 + q4], 0, 0, 0); }
;             SBAR(); }
	v_mfma_f32_16x16x32_bf16 v[82:85], v[90:93], v[50:53], 0
	v_mfma_f32_16x16x32_bf16 v[50:53], v[10:13], v[50:53], 0
	s_waitcnt lgkmcnt(5)
	v_mfma_f32_16x16x32_bf16 v[82:85], v[18:21], v[58:61], v[82:85]
	v_mfma_f32_16x16x32_bf16 v[50:53], v[22:25], v[58:61], v[50:53]
	s_waitcnt lgkmcnt(3)
	v_mfma_f32_16x16x32_bf16 v[58:61], v[26:29], v[66:69], v[82:85]
	v_mfma_f32_16x16x32_bf16 v[50:53], v[30:33], v[66:69], v[50:53]
	v_mfma_f32_16x16x32_bf16 v[66:69], v[90:93], v[54:57], 0
	v_mfma_f32_16x16x32_bf16 v[54:57], v[10:13], v[54:57], 0
	v_mfma_f32_16x16x32_bf16 v[66:69], v[18:21], v[62:65], v[66:69]
	v_mfma_f32_16x16x32_bf16 v[54:57], v[22:25], v[62:65], v[54:57]
	s_waitcnt lgkmcnt(2)
	v_mfma_f32_16x16x32_bf16 v[62:65], v[26:29], v[70:73], v[66:69]
	v_mfma_f32_16x16x32_bf16 v[54:57], v[30:33], v[70:73], v[54:57]
	s_waitcnt lgkmcnt(1)
	v_mfma_f32_16x16x32_bf16 v[58:61], v[34:37], v[74:77], v[58:61]
	v_mfma_f32_16x16x32_bf16 v[50:53], v[38:41], v[74:77], v[50:53]
	s_waitcnt lgkmcnt(0)
	v_mfma_f32_16x16x32_bf16 v[62:65], v[34:37], v[78:81], v[62:65]
	v_mfma_f32_16x16x32_bf16 v[54:57], v[38:41], v[78:81], v[54:57]
	ds_read_b128 v[66:69], v9 offset:16384
	ds_read_b128 v[70:73], v9 offset:20480
	ds_read_b128 v[74:77], v107 offset:16384
	ds_read_b128 v[78:81], v107 offset:20480
	ds_read_b128 v[82:85], v108 offset:16384
	ds_read_b128 v[86:89], v108 offset:20480
	ds_read_b128 v[94:97], v5 offset:16384
	ds_read_b128 v[98:101], v5 offset:20480
	s_waitcnt lgkmcnt(7)
	v_mfma_f32_16x16x32_bf16 v[102:105], v[90:93], v[66:69], 0
	v_mfma_f32_16x16x32_bf16 v[66:69], v[10:13], v[66:69], 0
	s_waitcnt lgkmcnt(5)
	v_mfma_f32_16x16x32_bf16 v[102:105], v[18:21], v[74:77], v[102:105]
	v_mfma_f32_16x16x32_bf16 v[66:69], v[22:25], v[74:77], v[66:69]
	s_waitcnt lgkmcnt(3)
	v_mfma_f32_16x16x32_bf16 v[74:77], v[26:29], v[82:85], v[102:105]
	v_mfma_f32_16x16x32_bf16 v[66:69], v[30:33], v[82:85], v[66:69]
	v_mfma_f32_16x16x32_bf16 v[82:85], v[90:93], v[70:73], 0
	v_mfma_f32_16x16x32_bf16 v[70:73], v[10:13], v[70:73], 0
	v_mfma_f32_16x16x32_bf16 v[82:85], v[18:21], v[78:81], v[82:85]
	v_mfma_f32_16x16x32_bf16 v[70:73], v[22:25], v[78:81], v[70:73]
	s_waitcnt lgkmcnt(2)
	v_mfma_f32_16x16x32_bf16 v[78:81], v[26:29], v[86:89], v[82:85]
	v_mfma_f32_16x16x32_bf16 v[70:73], v[30:33], v[86:89], v[70:73]
	s_waitcnt lgkmcnt(1)
	v_mfma_f32_16x16x32_bf16 v[74:77], v[34:37], v[94:97], v[74:77]
	v_mfma_f32_16x16x32_bf16 v[66:69], v[38:41], v[94:97], v[66:69]
	s_waitcnt lgkmcnt(0)
	v_mfma_f32_16x16x32_bf16 v[78:81], v[34:37], v[98:101], v[78:81]
	v_mfma_f32_16x16x32_bf16 v[70:73], v[38:41], v[98:101], v[70:73]
	ds_read_b128 v[82:85], v9 offset:24576
	ds_read_b128 v[86:89], v9 offset:28672
	ds_read_b128 v[94:97], v107 offset:24576
	ds_read_b128 v[98:101], v107 offset:28672
	ds_read_b128 v[102:105], v108 offset:24576
	ds_read_b128 v[106:109], v108 offset:28672
	ds_read_b128 v[110:113], v5 offset:24576
	ds_read_b128 v[114:117], v5 offset:28672
	s_waitcnt lgkmcnt(7)
	v_mfma_f32_16x16x32_bf16 v[118:121], v[90:93], v[82:85], 0
	v_mfma_f32_16x16x32_bf16 v[82:85], v[10:13], v[82:85], 0
	s_waitcnt lgkmcnt(6)
	v_mfma_f32_16x16x32_bf16 v[90:93], v[90:93], v[86:89], 0
	v_mfma_f32_16x16x32_bf16 v[10:13], v[10:13], v[86:89], 0
	s_waitcnt lgkmcnt(5)
	v_mfma_f32_16x16x32_bf16 v[118:121], v[18:21], v[94:97], v[118:121]
	v_mfma_f32_16x16x32_bf16 v[82:85], v[22:25], v[94:97], v[82:85]
	s_waitcnt lgkmcnt(4)
	v_mfma_f32_16x16x32_bf16 v[18:21], v[18:21], v[98:101], v[90:93]
	v_mfma_f32_16x16x32_bf16 v[10:13], v[22:25], v[98:101], v[10:13]
	s_waitcnt lgkmcnt(3)
	v_mfma_f32_16x16x32_bf16 v[94:97], v[26:29], v[102:105], v[118:121]
	v_mfma_f32_16x16x32_bf16 v[82:85], v[30:33], v[102:105], v[82:85]
	s_waitcnt lgkmcnt(2)
; #define SBAR() __builtin_amdgcn_sched_barrier(0)
; __global__ void __launch_bounds__(512) mega(Params p) {
;     ...
;           for (int g2 = 0; g2 < 4; ++g2) { bf16x8 B[2][4];
; #pragma unroll
;             for (int q4 = 0; q4 < 2; ++q4)
; #pragma unroll
;               for (int sx = 0; sx < 4; ++sx) B[q4][sx] = RLD16(0, (g2 * 2 + q4) * 16 + fr, sx * 4 + fq);
;             SBAR();
; #pragma unroll
;             for (int q4 = 0; q4 < 2; ++q4)
; #pragma unroll
;               for (int sx = 0; sx < 4; ++sx) { accf[g2 * 2 + q4] = __builtin_amdgcn_mfma_f32_16x16x32_bf16(Af[sx], B[q4][sx], accf[g2 * 2 + q4], 0, 0, 0);
;                 accb[g2 * 2 + q4] = __builtin_amdgcn_mfma_f32_16x16x32_bf16(Ab[sx], B[q4][sx], accb[g2 * 2 + q4], 0, 0, 0); }
;             SBAR(); }
;           bfraw* of = kv_ + ((long)((chunk * 8 + head) * 2 + 0)) * 16384 + fr * 128 + ew * 16 + fq * 4; bfraw* ob = of + 16384;
; #pragma unroll
;           for (int n = 0; n < 8; ++n) { u32x2 pf_ = {cvtpk(accf[n][0], accf[n][1]), cvtpk(accf[n][2], accf[n][3])}; u32x2 pb_ = {cvtpk(accb[n][0], accb[n][1]), cvtpk(accb[n][2], accb[n][3])};
;             *(u32x2*)(of + n * 2048) = pf_; *(u32x2*)(ob + n * 2048) = pb_; }
;         }
	v_mfma_f32_16x16x32_bf16 v[18:21], v[26:29], v[106:109], v[18:21]
	v_mfma_f32_16x16x32_bf16 v[10:13], v[30:33], v[106:109], v[10:13]
	s_waitcnt lgkmcnt(1)
	v_mfma_f32_16x16x32_bf16 v[94:97], v[34:37], v[110:113], v[94:97]
	v_mfma_f32_16x16x32_bf16 v[82:85], v[38:41], v[110:113], v[82:85]
	s_waitcnt lgkmcnt(0)
	v_mfma_f32_16x16x32_bf16 v[18:21], v[34:37], v[114:117], v[18:21]
	v_mfma_f32_16x16x32_bf16 v[10:13], v[38:41], v[114:117], v[10:13]
	s_ashr_i32 s17, s16, 31
	s_lshl_b64 s[20:21], s[16:17], 15
	s_add_u32 s20, s2, s20
	s_addc_u32 s21, s3, s21
	s_lshl_b32 s18, s18, 4
	v_lshl_add_u64 v[6:7], s[20:21], 0, v[176:177]
	s_ashr_i32 s19, s18, 31
	v_lshl_add_u64 v[6:7], s[18:19], 1, v[6:7]
	v_mov_b32_e32 v5, v177
	v_lshl_add_u64 v[4:5], v[6:7], 0, v[4:5]
	s_mov_b32 s17, 0x9000
	v_cvt_pk_bf16_f32 v6, v14, v15
	v_cvt_pk_bf16_f32 v7, v16, v17
	v_cvt_pk_bf16_f32 v0, v0, v1
	v_cvt_pk_bf16_f32 v1, v2, v3
	v_add_co_u32_e32 v2, vcc, s17, v4
	global_store_dwordx2 v[4:5], v[6:7], off
	s_nop 0
	v_addc_co_u32_e32 v3, vcc, 0, v5, vcc
	v_add_co_u32_e32 v14, vcc, s53, v4
	global_store_dwordx2 v[2:3], v[0:1], off offset:-4096
	v_cvt_pk_bf16_f32 v0, v42, v43
	v_cvt_pk_bf16_f32 v1, v44, v45
	s_nop 0
	v_addc_co_u32_e32 v15, vcc, 0, v5, vcc
	v_cvt_pk_bf16_f32 v6, v46, v47
	v_cvt_pk_bf16_f32 v7, v48, v49
	global_store_dwordx2 v[14:15], v[0:1], off offset:-4096
	global_store_dwordx2 v[2:3], v[6:7], off
	v_cvt_pk_bf16_f32 v0, v58, v59
	s_mov_b32 s17, 0xb000
	v_cvt_pk_bf16_f32 v1, v60, v61
	v_cvt_pk_bf16_f32 v2, v50, v51
	v_cvt_pk_bf16_f32 v3, v52, v53
	global_store_dwordx2 v[14:15], v[0:1], off
	v_add_co_u32_e32 v0, vcc, s17, v4
	s_mov_b32 s17, 0xd000
	s_nop 0
	v_addc_co_u32_e32 v1, vcc, 0, v5, vcc
	v_add_co_u32_e32 v14, vcc, s83, v4
	global_store_dwordx2 v[0:1], v[2:3], off offset:-4096
	v_cvt_pk_bf16_f32 v2, v62, v63
	v_cvt_pk_bf16_f32 v3, v64, v65
	s_nop 0
	v_addc_co_u32_e32 v15, vcc, 0, v5, vcc
	v_cvt_pk_bf16_f32 v6, v54, v55
	v_cvt_pk_bf16_f32 v7, v56, v57
	global_store_dwordx2 v[14:15], v[2:3], off offset:-4096
	global_store_dwordx2 v[0:1], v[6:7], off
	v_cvt_pk_bf16_f32 v0, v74, v75
	v_cvt_pk_bf16_f32 v1, v76, v77
	v_cvt_pk_bf16_f32 v2, v66, v67
	v_cvt_pk_bf16_f32 v3, v68, v69
	global_store_dwordx2 v[14:15], v[0:1], off
	v_add_co_u32_e32 v0, vcc, s17, v4
	s_movk_i32 s17, 0x6000
	s_nop 0
	v_addc_co_u32_e32 v1, vcc, 0, v5, vcc
	v_add_co_u32_e32 v14, vcc, s17, v4
	global_store_dwordx2 v[0:1], v[2:3], off offset:-4096
	v_cvt_pk_bf16_f32 v2, v78, v79
	v_cvt_pk_bf16_f32 v3, v80, v81
	s_nop 0
	v_addc_co_u32_e32 v15, vcc, 0, v5, vcc
	s_add_i32 s15, s15, s28
	v_cvt_pk_bf16_f32 v6, v70, v71
	v_cvt_pk_bf16_f32 v7, v72, v73
	global_store_dwordx2 v[14:15], v[2:3], off offset:-4096
	global_store_dwordx2 v[0:1], v[6:7], off
	v_cvt_pk_bf16_f32 v0, v94, v95
	s_mov_b32 s17, 0xf000
	s_add_u32 s12, s12, s72
	v_cvt_pk_bf16_f32 v1, v96, v97
	v_cvt_pk_bf16_f32 v2, v82, v83
	v_cvt_pk_bf16_f32 v3, v84, v85
	global_store_dwordx2 v[14:15], v[0:1], off
	v_add_co_u32_e32 v0, vcc, s17, v4
	s_addc_u32 s14, s14, s73
	s_nop 0
	v_addc_co_u32_e32 v1, vcc, 0, v5, vcc
	s_movk_i32 s17, 0x7000
	s_add_u32 s8, s8, s72
	v_add_co_u32_e32 v4, vcc, s17, v4
	s_addc_u32 s9, s9, s73
	s_add_i32 s16, s16, s59
	v_addc_co_u32_e32 v5, vcc, 0, v5, vcc
	s_cmpk_gt_i32 s15, 0x3ff
	global_store_dwordx2 v[0:1], v[2:3], off offset:-4096
	v_cvt_pk_bf16_f32 v2, v18, v19
	v_cvt_pk_bf16_f32 v3, v20, v21
	v_cvt_pk_bf16_f32 v6, v10, v11
	v_cvt_pk_bf16_f32 v7, v12, v13
	global_store_dwordx2 v[4:5], v[2:3], off
	global_store_dwordx2 v[0:1], v[6:7], off
	s_cbranch_scc0 .LBB0_2423

; DEVFI float bf2f(bfraw h) { return __uint_as_float(((unsigned)h) << 16); }
; DEVFI bfraw f2bf(float x) { unsigned u = __float_as_uint(x); u += 0x7fffu + ((u >> 16) & 1u); return (bfraw)(u >> 16); }
; __global__ void __launch_bounds__(512) mega(Params p) {
;     ...
; #pragma unroll
;           for (int r = 0; r < 4; ++r) { const int cg8 = (wid * 4 + r) * 8;
;             float lw[8], lb[8];
; #pragma unroll
;             for (int e = 0; e < 8; ++e) { lw[e] = lnw_[g * 256 + cg8 + e]; lb[e] = lnb_[g * 256 + cg8 + e]; }
; #pragma unroll
;             for (int half = 0; half < 2; ++half) { const int tok = half * 64 + lane;
;               const bf16x8 v = *(const bf16x8*)(sv_ + (long)(chunk * 128 + tok) * 1024 + g * 256 + cg8);
;               const float mu = st_mu[tok], rs = st_rs[tok];
; #pragma unroll
;               for (int e = 0; e < 8; ++e) *(bfraw*)(tile + (cg8 + e) * PITCH + tok * 2) = f2bf((bf2f((bfraw)v[e]) - mu) * rs * lw[e] + lb[e]); } }
.LBB0_2426:
	s_or_b64 exec, exec, s[2:3]
	s_and_b32 s2, s15, 3
	v_or_b32_e32 v0, s24, v97
	s_lshl_b32 s12, s2, 9
	v_ashrrev_i32_e32 v1, 31, v0
	v_lshl_add_u64 v[4:5], v[84:85], 0, s[12:13]
	v_lshlrev_b64 v[0:1], 11, v[0:1]
	v_lshl_add_u64 v[50:51], v[4:5], 0, v[0:1]
	v_lshl_add_u32 v0, s2, 8, v72
	s_waitcnt lgkmcnt(0)
	s_barrier
	global_load_dwordx4 v[30:33], v[50:51], off
	v_ashrrev_i32_e32 v1, 31, v0
	v_lshlrev_b64 v[0:1], 2, v[0:1]
	v_lshl_add_u64 v[56:57], s[18:19], 0, v[0:1]
	v_or_b32_e32 v6, s24, v104
	v_lshl_add_u64 v[52:53], s[20:21], 0, v[0:1]
	global_load_dwordx4 v[34:37], v[56:57], off
	global_load_dwordx4 v[38:41], v[52:53], off
	global_load_dwordx4 v[26:29], v[56:57], off offset:16
	global_load_dwordx4 v[0:3], v[52:53], off offset:16
	v_ashrrev_i32_e32 v7, 31, v6
	v_lshlrev_b64 v[6:7], 11, v[6:7]
	v_lshl_add_u64 v[54:55], v[4:5], 0, v[6:7]
	global_load_dwordx4 v[60:63], v[54:55], off
	v_add_u32_e32 v58, v102, v101
	ds_read_b32 v16, v100
	ds_read2st64_b32 v[48:49], v100 offset1:2
	ds_read_b32 v17, v58 offset:256
	ds_read2st64_b32 v[46:47], v58 offset0:1 offset1:3
	global_load_dwordx4 v[18:21], v[50:51], off offset:16
	global_load_dwordx4 v[4:7], v[56:57], off offset:48
	global_load_dwordx4 v[12:15], v[56:57], off offset:32
	global_load_dwordx4 v[8:11], v[52:53], off offset:48
	global_load_dwordx4 v[22:25], v[52:53], off offset:32
	v_add_u32_e32 v59, v102, v103
	s_add_i32 s15, s15, s28
	s_waitcnt vmcnt(10)
	v_lshlrev_b32_e32 v42, 16, v30
	v_and_b32_e32 v30, 0xffff0000, v30
	v_lshlrev_b32_e32 v43, 16, v31
	v_and_b32_e32 v31, 0xffff0000, v31
	v_lshlrev_b32_e32 v44, 16, v32
	v_and_b32_e32 v32, 0xffff0000, v32
	v_lshlrev_b32_e32 v45, 16, v33
	v_and_b32_e32 v33, 0xffff0000, v33
	s_waitcnt lgkmcnt(3)
	v_sub_f32_e32 v42, v42, v16
	v_sub_f32_e32 v30, v30, v16
	v_sub_f32_e32 v43, v43, v16
	v_sub_f32_e32 v31, v31, v16
	v_sub_f32_e32 v44, v44, v16
	v_sub_f32_e32 v32, v32, v16
	v_sub_f32_e32 v45, v45, v16
	v_sub_f32_e32 v16, v33, v16
	s_waitcnt lgkmcnt(2)
	v_mul_f32_e32 v33, v49, v42
	v_mul_f32_e32 v16, v49, v16
	v_mul_f32_e32 v30, v49, v30
	v_mul_f32_e32 v42, v49, v43
	v_mul_f32_e32 v31, v49, v31
	v_mul_f32_e32 v43, v49, v44
	v_mul_f32_e32 v32, v49, v32
	v_mul_f32_e32 v44, v49, v45
	s_waitcnt vmcnt(8)
	v_fma_f32 v33, v33, v34, v38
	s_waitcnt vmcnt(6)
	v_fma_f32 v16, v16, v29, v3
	v_fma_f32 v30, v30, v35, v39
	v_fma_f32 v42, v42, v36, v40
	v_fma_f32 v31, v31, v37, v41
	v_fma_f32 v43, v43, v26, v0
	v_fma_f32 v32, v32, v27, v1
	v_fma_f32 v44, v44, v28, v2
	v_cvt_pk_bf16_f32 v33, v33, v33
	v_cvt_pk_bf16_f32 v16, v16, v16
	v_cvt_pk_bf16_f32 v30, v30, v30
	v_cvt_pk_bf16_f32 v42, v42, v42
	v_cvt_pk_bf16_f32 v31, v31, v31
	v_cvt_pk_bf16_f32 v43, v43, v43
	v_cvt_pk_bf16_f32 v32, v32, v32
	v_cvt_pk_bf16_f32 v44, v44, v44
	ds_write_b16_d16_hi v59, v33 offset:1024
	ds_write_b16_d16_hi v59, v30 offset:1296
	ds_write_b16_d16_hi v59, v42 offset:1568
	ds_write_b16_d16_hi v59, v31 offset:1840
	ds_write_b16_d16_hi v59, v43 offset:2112
	ds_write_b16_d16_hi v59, v32 offset:2384
	ds_write_b16_d16_hi v59, v44 offset:2656
	ds_write_b16_d16_hi v59, v16 offset:2928
	s_waitcnt vmcnt(5)
	v_lshlrev_b32_e32 v16, 16, v60
	s_waitcnt lgkmcnt(9)
	v_sub_f32_e32 v16, v16, v17
	s_waitcnt lgkmcnt(8)
	v_mul_f32_e32 v16, v47, v16
	v_fma_f32 v16, v16, v34, v38
	v_cvt_pk_bf16_f32 v16, v16, v16
	v_add_u32_e32 v49, v105, v103
	ds_write_b16_d16_hi v49, v16 offset:1024
	v_and_b32_e32 v16, 0xffff0000, v60
	v_sub_f32_e32 v16, v16, v17
	v_mul_f32_e32 v16, v47, v16
	v_fma_f32 v16, v16, v35, v39
	v_cvt_pk_bf16_f32 v16, v16, v16
	ds_write_b16_d16_hi v49, v16 offset:1296
	v_lshlrev_b32_e32 v16, 16, v61
	v_sub_f32_e32 v16, v16, v17
	v_mul_f32_e32 v16, v47, v16
	v_fma_f32 v16, v16, v36, v40
	global_load_dwordx4 v[42:45], v[54:55], off offset:16
	v_cvt_pk_bf16_f32 v16, v16, v16
	ds_write_b16_d16_hi v49, v16 offset:1568
	v_and_b32_e32 v16, 0xffff0000, v61
	v_sub_f32_e32 v16, v16, v17
	v_mul_f32_e32 v16, v47, v16
	v_fmac_f32_e32 v41, v16, v37
	v_cvt_pk_bf16_f32 v16, v41, v41
	ds_write_b16_d16_hi v49, v16 offset:1840
	v_lshlrev_b32_e32 v16, 16, v62
	v_sub_f32_e32 v16, v16, v17
	v_mul_f32_e32 v16, v47, v16
	v_fma_f32 v0, v16, v26, v0
	v_cvt_pk_bf16_f32 v0, v0, v0
	ds_write_b16_d16_hi v49, v0 offset:2112
	v_and_b32_e32 v0, 0xffff0000, v62
	v_sub_f32_e32 v0, v0, v17
	v_mul_f32_e32 v0, v47, v0
	v_fma_f32 v0, v0, v27, v1
	v_cvt_pk_bf16_f32 v0, v0, v0
	ds_write_b16_d16_hi v49, v0 offset:2384
	v_lshlrev_b32_e32 v0, 16, v63
	v_sub_f32_e32 v0, v0, v17
	v_mul_f32_e32 v0, v47, v0
	v_fma_f32 v0, v0, v28, v2
	v_cvt_pk_bf16_f32 v0, v0, v0
	ds_write_b16_d16_hi v49, v0 offset:2656
	v_and_b32_e32 v0, 0xffff0000, v63
	v_sub_f32_e32 v0, v0, v17
	v_mul_f32_e32 v0, v47, v0
	v_fmac_f32_e32 v3, v0, v29
	ds_read_b32 v1, v100
	ds_read_b32 v2, v100 offset:512
	v_cvt_pk_bf16_f32 v0, v3, v3
	ds_write_b16_d16_hi v49, v0 offset:2928
	s_waitcnt vmcnt(5)
	v_lshlrev_b32_e32 v0, 16, v18
	s_waitcnt lgkmcnt(2)
	v_sub_f32_e32 v0, v0, v1
	s_waitcnt lgkmcnt(1)
	v_mul_f32_e32 v0, v2, v0
	s_waitcnt vmcnt(1)
; DEVFI float bf2f(bfraw h) { return __uint_as_float(((unsigned)h) << 16); }
; DEVFI bfraw f2bf(float x) { unsigned u = __float_as_uint(x); u += 0x7fffu + ((u >> 16) & 1u); return (bfraw)(u >> 16); }
; __global__ void __launch_bounds__(512) mega(Params p) {
;     ...
;           for (int r = 0; r < 4; ++r) { const int cg8 = (wid * 4 + r) * 8;
;             float lw[8], lb[8];
; #pragma unroll
;             for (int e = 0; e < 8; ++e) { lw[e] = lnw_[g * 256 + cg8 + e]; lb[e] = lnb_[g * 256 + cg8 + e]; }
; #pragma unroll
;             for (int half = 0; half < 2; ++half) { const int tok = half * 64 + lane;
;               const bf16x8 v = *(const bf16x8*)(sv_ + (long)(chunk * 128 + tok) * 1024 + g * 256 + cg8);
;               const float mu = st_mu[tok], rs = st_rs[tok];
; #pragma unroll
;               for (int e = 0; e < 8; ++e) *(bfraw*)(tile + (cg8 + e) * PITCH + tok * 2) = f2bf((bf2f((bfraw)v[e]) - mu) * rs * lw[e] + lb[e]); } }
	v_fma_f32 v0, v0, v12, v22
	v_cvt_pk_bf16_f32 v0, v0, v0
	ds_write_b16_d16_hi v59, v0 offset:3200
	v_and_b32_e32 v0, 0xffff0000, v18
	v_sub_f32_e32 v0, v0, v1
	v_mul_f32_e32 v0, v2, v0
	v_fma_f32 v0, v0, v13, v23
	v_cvt_pk_bf16_f32 v0, v0, v0
	ds_write_b16_d16_hi v59, v0 offset:3472
	v_lshlrev_b32_e32 v0, 16, v19
	v_sub_f32_e32 v0, v0, v1
	v_mul_f32_e32 v0, v2, v0
	v_fma_f32 v0, v0, v14, v24
	v_cvt_pk_bf16_f32 v0, v0, v0
	ds_write_b16_d16_hi v59, v0 offset:3744
	v_and_b32_e32 v0, 0xffff0000, v19
	v_sub_f32_e32 v0, v0, v1
	v_mul_f32_e32 v0, v2, v0
	v_fma_f32 v0, v0, v15, v25
	v_cvt_pk_bf16_f32 v0, v0, v0
	ds_write_b16_d16_hi v59, v0 offset:4016
	v_lshlrev_b32_e32 v0, 16, v20
	v_sub_f32_e32 v0, v0, v1
	v_mul_f32_e32 v0, v2, v0
	v_fma_f32 v0, v0, v4, v8
	v_cvt_pk_bf16_f32 v0, v0, v0
	ds_write_b16_d16_hi v59, v0 offset:4288
	v_and_b32_e32 v0, 0xffff0000, v20
	v_sub_f32_e32 v0, v0, v1
	v_mul_f32_e32 v0, v2, v0
	v_fma_f32 v0, v0, v5, v9
	global_load_dwordx4 v[36:39], v[50:51], off offset:32
	v_cvt_pk_bf16_f32 v0, v0, v0
	ds_write_b16_d16_hi v59, v0 offset:4560
	v_lshlrev_b32_e32 v0, 16, v21
	v_sub_f32_e32 v0, v0, v1
	global_load_dwordx4 v[32:35], v[56:57], off offset:64
	global_load_dwordx4 v[16:19], v[52:53], off offset:64
	v_mul_f32_e32 v0, v2, v0
	v_fma_f32 v0, v0, v6, v10
	v_cvt_pk_bf16_f32 v0, v0, v0
	ds_write_b16_d16_hi v59, v0 offset:4832
	v_and_b32_e32 v0, 0xffff0000, v21
	v_sub_f32_e32 v0, v0, v1
	v_mul_f32_e32 v0, v2, v0
	v_fma_f32 v0, v0, v7, v11
	ds_read_b32 v2, v58 offset:256
	ds_read_b32 v3, v58 offset:768
	v_cvt_pk_bf16_f32 v0, v0, v0
	ds_write_b16_d16_hi v59, v0 offset:5104
	s_waitcnt vmcnt(3)
	v_lshlrev_b32_e32 v0, 16, v42
	s_waitcnt lgkmcnt(2)
	v_sub_f32_e32 v0, v0, v2
	s_waitcnt lgkmcnt(1)
	v_mul_f32_e32 v0, v3, v0
	v_fma_f32 v0, v0, v12, v22
	v_cvt_pk_bf16_f32 v0, v0, v0
	ds_write_b16_d16_hi v49, v0 offset:3200
	v_and_b32_e32 v0, 0xffff0000, v42
	v_sub_f32_e32 v0, v0, v2
	v_mul_f32_e32 v0, v3, v0
	v_fma_f32 v0, v0, v13, v23
	v_cvt_pk_bf16_f32 v0, v0, v0
	ds_write_b16_d16_hi v49, v0 offset:3472
	global_load_dwordx4 v[28:31], v[56:57], off offset:80
	global_load_dwordx4 v[20:23], v[52:53], off offset:80
	v_lshlrev_b32_e32 v0, 16, v43
	v_sub_f32_e32 v0, v0, v2
	v_mul_f32_e32 v0, v3, v0
	v_fma_f32 v0, v0, v14, v24
	v_cvt_pk_bf16_f32 v0, v0, v0
	ds_write_b16_d16_hi v49, v0 offset:3744
	v_and_b32_e32 v0, 0xffff0000, v43
	v_sub_f32_e32 v0, v0, v2
	v_mul_f32_e32 v0, v3, v0
	v_fmac_f32_e32 v25, v0, v15
	v_cvt_pk_bf16_f32 v0, v25, v25
	global_load_dwordx4 v[40:43], v[54:55], off offset:32
	ds_write_b16_d16_hi v49, v0 offset:4016
	v_lshlrev_b32_e32 v0, 16, v44
	v_sub_f32_e32 v0, v0, v2
	v_mul_f32_e32 v0, v3, v0
	v_fma_f32 v0, v0, v4, v8
	v_cvt_pk_bf16_f32 v0, v0, v0
	ds_write_b16_d16_hi v49, v0 offset:4288
	v_and_b32_e32 v0, 0xffff0000, v44
	v_sub_f32_e32 v0, v0, v2
	v_mul_f32_e32 v0, v3, v0
	v_fma_f32 v0, v0, v5, v9
	v_cvt_pk_bf16_f32 v0, v0, v0
	ds_write_b16_d16_hi v49, v0 offset:4560
	v_lshlrev_b32_e32 v0, 16, v45
	v_sub_f32_e32 v0, v0, v2
	v_mul_f32_e32 v0, v3, v0
	v_fma_f32 v0, v0, v6, v10
	v_cvt_pk_bf16_f32 v0, v0, v0
	ds_write_b16_d16_hi v49, v0 offset:4832
	v_and_b32_e32 v0, 0xffff0000, v45
	v_sub_f32_e32 v0, v0, v2
	v_mul_f32_e32 v0, v3, v0
	v_fmac_f32_e32 v11, v0, v7
	v_cvt_pk_bf16_f32 v0, v11, v11
	ds_write_b16_d16_hi v49, v0 offset:5104
	global_load_dwordx4 v[0:3], v[56:57], off offset:112
	global_load_dwordx4 v[4:7], v[56:57], off offset:96
	ds_read_b32 v44, v100
	ds_read_b32 v45, v100 offset:512
	global_load_dwordx4 v[8:11], v[52:53], off offset:112
	global_load_dwordx4 v[12:15], v[52:53], off offset:96
	s_waitcnt vmcnt(9)
	v_lshlrev_b32_e32 v24, 16, v36
	s_waitcnt lgkmcnt(1)
	v_sub_f32_e32 v24, v24, v44
	s_waitcnt lgkmcnt(0)
	v_mul_f32_e32 v24, v45, v24
	s_waitcnt vmcnt(7)
	v_fma_f32 v24, v24, v32, v16
	v_cvt_pk_bf16_f32 v24, v24, v24
	ds_write_b16_d16_hi v59, v24 offset:5376
	v_and_b32_e32 v24, 0xffff0000, v36
	v_sub_f32_e32 v24, v24, v44
	v_mul_f32_e32 v24, v45, v24
	v_fma_f32 v24, v24, v33, v17
	v_cvt_pk_bf16_f32 v24, v24, v24
	ds_write_b16_d16_hi v59, v24 offset:5648
	v_lshlrev_b32_e32 v24, 16, v37
	v_sub_f32_e32 v24, v24, v44
	v_mul_f32_e32 v24, v45, v24
	v_fma_f32 v24, v24, v34, v18
	v_cvt_pk_bf16_f32 v24, v24, v24
	ds_write_b16_d16_hi v59, v24 offset:5920
	v_and_b32_e32 v24, 0xffff0000, v37
	v_sub_f32_e32 v24, v24, v44
	v_mul_f32_e32 v24, v45, v24
	v_fma_f32 v24, v24, v35, v19
	v_cvt_pk_bf16_f32 v24, v24, v24
	ds_write_b16_d16_hi v59, v24 offset:6192
	v_lshlrev_b32_e32 v24, 16, v38
	v_sub_f32_e32 v24, v24, v44
	v_mul_f32_e32 v24, v45, v24
	s_waitcnt vmcnt(5)
	v_fma_f32 v24, v24, v28, v20
	v_cvt_pk_bf16_f32 v24, v24, v24
	ds_write_b16_d16_hi v59, v24 offset:6464
	v_and_b32_e32 v24, 0xffff0000, v38
	v_sub_f32_e32 v36, v24, v44
	global_load_dwordx4 v[24:27], v[50:51], off offset:48
	v_mul_f32_e32 v36, v45, v36
	v_fma_f32 v36, v36, v29, v21
	v_cvt_pk_bf16_f32 v36, v36, v36
	ds_write_b16_d16_hi v59, v36 offset:6736
	v_lshlrev_b32_e32 v36, 16, v39
	v_sub_f32_e32 v36, v36, v44
	v_mul_f32_e32 v36, v45, v36
	v_fma_f32 v36, v36, v30, v22
	v_cvt_pk_bf16_f32 v36, v36, v36
	ds_write_b16_d16_hi v59, v36 offset:7008
	v_and_b32_e32 v36, 0xffff0000, v39
	v_sub_f32_e32 v36, v36, v44
	v_mul_f32_e32 v36, v45, v36
	v_fma_f32 v36, v36, v31, v23
	ds_read_b32 v38, v58 offset:256
	ds_read_b32 v39, v58 offset:768
	v_cvt_pk_bf16_f32 v36, v36, v36
	ds_write_b16_d16_hi v59, v36 offset:7280
	s_waitcnt vmcnt(5)
	v_lshlrev_b32_e32 v36, 16, v40
	s_waitcnt lgkmcnt(2)
	v_sub_f32_e32 v36, v36, v38
	s_waitcnt lgkmcnt(1)
; DEVFI float bf2f(bfraw h) { return __uint_as_float(((unsigned)h) << 16); }
; DEVFI bfraw f2bf(float x) { unsigned u = __float_as_uint(x); u += 0x7fffu + ((u >> 16) & 1u); return (bfraw)(u >> 16); }
; __global__ void __launch_bounds__(512) mega(Params p) {
;     ...
;           for (int r = 0; r < 4; ++r) { const int cg8 = (wid * 4 + r) * 8;
;             float lw[8], lb[8];
; #pragma unroll
;             for (int e = 0; e < 8; ++e) { lw[e] = lnw_[g * 256 + cg8 + e]; lb[e] = lnb_[g * 256 + cg8 + e]; }
; #pragma unroll
;             for (int half = 0; half < 2; ++half) { const int tok = half * 64 + lane;
;               const bf16x8 v = *(const bf16x8*)(sv_ + (long)(chunk * 128 + tok) * 1024 + g * 256 + cg8);
;               const float mu = st_mu[tok], rs = st_rs[tok];
; #pragma unroll
;               for (int e = 0; e < 8; ++e) *(bfraw*)(tile + (cg8 + e) * PITCH + tok * 2) = f2bf((bf2f((bfraw)v[e]) - mu) * rs * lw[e] + lb[e]); } }
;           __syncthreads();
	v_mul_f32_e32 v36, v39, v36
	v_fma_f32 v16, v36, v32, v16
	v_cvt_pk_bf16_f32 v16, v16, v16
	ds_write_b16_d16_hi v49, v16 offset:5376
	v_and_b32_e32 v16, 0xffff0000, v40
	v_sub_f32_e32 v16, v16, v38
	v_mul_f32_e32 v16, v39, v16
	v_fma_f32 v16, v16, v33, v17
	v_cvt_pk_bf16_f32 v16, v16, v16
	ds_write_b16_d16_hi v49, v16 offset:5648
	v_lshlrev_b32_e32 v16, 16, v41
	v_sub_f32_e32 v16, v16, v38
	v_mul_f32_e32 v16, v39, v16
	v_fma_f32 v16, v16, v34, v18
	v_cvt_pk_bf16_f32 v16, v16, v16
	ds_write_b16_d16_hi v49, v16 offset:5920
	v_and_b32_e32 v16, 0xffff0000, v41
	v_sub_f32_e32 v16, v16, v38
	v_mul_f32_e32 v16, v39, v16
	v_fmac_f32_e32 v19, v16, v35
	v_cvt_pk_bf16_f32 v16, v19, v19
	ds_write_b16_d16_hi v49, v16 offset:6192
	v_lshlrev_b32_e32 v16, 16, v42
	v_sub_f32_e32 v16, v16, v38
	v_mul_f32_e32 v16, v39, v16
	v_fma_f32 v16, v16, v28, v20
	v_cvt_pk_bf16_f32 v16, v16, v16
	ds_write_b16_d16_hi v49, v16 offset:6464
	global_load_dwordx4 v[16:19], v[54:55], off offset:48
	v_and_b32_e32 v20, 0xffff0000, v42
	v_sub_f32_e32 v20, v20, v38
	v_mul_f32_e32 v20, v39, v20
	v_fma_f32 v20, v20, v29, v21
	v_cvt_pk_bf16_f32 v20, v20, v20
	ds_write_b16_d16_hi v49, v20 offset:6736
	v_lshlrev_b32_e32 v20, 16, v43
	v_sub_f32_e32 v20, v20, v38
	v_mul_f32_e32 v20, v39, v20
	v_fma_f32 v20, v20, v30, v22
	v_cvt_pk_bf16_f32 v20, v20, v20
	ds_write_b16_d16_hi v49, v20 offset:7008
	v_and_b32_e32 v20, 0xffff0000, v43
	v_sub_f32_e32 v20, v20, v38
	v_mul_f32_e32 v20, v39, v20
	v_fmac_f32_e32 v23, v20, v31
	ds_read_b32 v21, v100 offset:512
	v_cvt_pk_bf16_f32 v20, v23, v23
	ds_write_b16_d16_hi v49, v20 offset:7280
	s_waitcnt vmcnt(1)
	v_lshlrev_b32_e32 v20, 16, v24
	v_sub_f32_e32 v20, v20, v48
	s_waitcnt lgkmcnt(1)
	v_mul_f32_e32 v20, v21, v20
	v_fma_f32 v20, v20, v4, v12
	v_cvt_pk_bf16_f32 v20, v20, v20
	ds_write_b16_d16_hi v59, v20 offset:7552
	v_and_b32_e32 v20, 0xffff0000, v24
	v_sub_f32_e32 v20, v20, v48
	v_mul_f32_e32 v20, v21, v20
	v_fma_f32 v20, v20, v5, v13
	v_cvt_pk_bf16_f32 v20, v20, v20
	ds_write_b16_d16_hi v59, v20 offset:7824
	v_lshlrev_b32_e32 v20, 16, v25
	v_sub_f32_e32 v20, v20, v48
	v_mul_f32_e32 v20, v21, v20
	v_fma_f32 v20, v20, v6, v14
	v_cvt_pk_bf16_f32 v20, v20, v20
	ds_write_b16_d16_hi v59, v20 offset:8096
	v_and_b32_e32 v20, 0xffff0000, v25
	v_sub_f32_e32 v20, v20, v48
	v_mul_f32_e32 v20, v21, v20
	v_fma_f32 v20, v20, v7, v15
	v_cvt_pk_bf16_f32 v20, v20, v20
	ds_write_b16_d16_hi v59, v20 offset:8368
	v_lshlrev_b32_e32 v20, 16, v26
	v_sub_f32_e32 v20, v20, v48
	v_mul_f32_e32 v20, v21, v20
	v_fma_f32 v20, v20, v0, v8
	v_cvt_pk_bf16_f32 v20, v20, v20
	ds_write_b16_d16_hi v59, v20 offset:8640
	v_and_b32_e32 v20, 0xffff0000, v26
	v_sub_f32_e32 v20, v20, v48
	v_mul_f32_e32 v20, v21, v20
	v_fma_f32 v20, v20, v1, v9
	v_cvt_pk_bf16_f32 v20, v20, v20
	ds_write_b16_d16_hi v59, v20 offset:8912
	v_lshlrev_b32_e32 v20, 16, v27
	v_sub_f32_e32 v20, v20, v48
	v_mul_f32_e32 v20, v21, v20
	v_fma_f32 v20, v20, v2, v10
	v_cvt_pk_bf16_f32 v20, v20, v20
	ds_write_b16_d16_hi v59, v20 offset:9184
	v_and_b32_e32 v20, 0xffff0000, v27
	v_sub_f32_e32 v20, v20, v48
	v_mul_f32_e32 v20, v21, v20
	v_fma_f32 v20, v20, v3, v11
	v_cvt_pk_bf16_f32 v21, v20, v20
	ds_read_b32 v20, v58 offset:768
	v_add_u32_e32 v22, v102, v106
	ds_write_b16_d16_hi v22, v21 offset:1024
	s_waitcnt vmcnt(0)
	v_lshlrev_b32_e32 v21, 16, v16
	v_sub_f32_e32 v21, v21, v46
	s_waitcnt lgkmcnt(1)
	v_mul_f32_e32 v21, v20, v21
	v_fma_f32 v4, v21, v4, v12
	v_cvt_pk_bf16_f32 v4, v4, v4
	ds_write_b16_d16_hi v49, v4 offset:7552
	v_and_b32_e32 v4, 0xffff0000, v16
	v_sub_f32_e32 v4, v4, v46
	v_mul_f32_e32 v4, v20, v4
	v_fma_f32 v4, v4, v5, v13
	v_cvt_pk_bf16_f32 v4, v4, v4
	ds_write_b16_d16_hi v49, v4 offset:7824
	v_lshlrev_b32_e32 v4, 16, v17
	v_sub_f32_e32 v4, v4, v46
	v_mul_f32_e32 v4, v20, v4
	v_fma_f32 v4, v4, v6, v14
	v_cvt_pk_bf16_f32 v4, v4, v4
	ds_write_b16_d16_hi v49, v4 offset:8096
	v_and_b32_e32 v4, 0xffff0000, v17
	v_sub_f32_e32 v4, v4, v46
	v_mul_f32_e32 v4, v20, v4
	v_fmac_f32_e32 v15, v4, v7
	v_cvt_pk_bf16_f32 v4, v15, v15
	ds_write_b16_d16_hi v49, v4 offset:8368
	v_lshlrev_b32_e32 v4, 16, v18
	v_sub_f32_e32 v4, v4, v46
	v_mul_f32_e32 v4, v20, v4
	v_fma_f32 v0, v4, v0, v8
	v_cvt_pk_bf16_f32 v0, v0, v0
	ds_write_b16_d16_hi v49, v0 offset:8640
	v_and_b32_e32 v0, 0xffff0000, v18
	v_sub_f32_e32 v0, v0, v46
	v_mul_f32_e32 v0, v20, v0
	v_fma_f32 v0, v0, v1, v9
	v_cvt_pk_bf16_f32 v0, v0, v0
	ds_write_b16_d16_hi v49, v0 offset:8912
	v_lshlrev_b32_e32 v0, 16, v19
	v_sub_f32_e32 v0, v0, v46
	v_mul_f32_e32 v0, v20, v0
	v_fma_f32 v0, v0, v2, v10
	v_cvt_pk_bf16_f32 v0, v0, v0
	ds_write_b16_d16_hi v49, v0 offset:9184
	v_and_b32_e32 v0, 0xffff0000, v19
	v_sub_f32_e32 v0, v0, v46
	v_lshl_add_u32 v14, s2, 14, v107
	v_mul_f32_e32 v0, v20, v0
	v_or_b32_e32 v16, 0x800, v14
	v_fmac_f32_e32 v11, v0, v3
	v_ashrrev_i32_e32 v17, 31, v16
	v_lshlrev_b64 v[18:19], 1, v[16:17]
	v_cvt_pk_bf16_f32 v0, v11, v11
	v_add_u32_e32 v1, v105, v106
	v_lshl_add_u64 v[16:17], v[74:75], 0, v[18:19]
	ds_write_b16_d16_hi v1, v0 offset:1024
	s_waitcnt lgkmcnt(0)
	s_barrier
; __global__ void __launch_bounds__(512) mega(Params p) {
;     ...
;           const int wm = wid >> 2, wn = wid & 3;
;           f32x4 acc[4][4] = {};
; #pragma unroll
;           for (int sx = 0; sx < 4; ++sx) { bf16x8 A[4], B[4];
; #pragma unroll
;             for (int mi = 0; mi < 4; ++mi) A[mi] = *(const bf16x8*)(wsg_ + (g * 128 + wm * 64 + mi * 16 + fr) * 128 + sx * 32 + fq * 8);
; #pragma unroll
;             for (int ni = 0; ni < 4; ++ni) B[ni] = *(const bf16x8*)(tile + (wn * 64 + ni * 16 + fr) * PITCH + (sx * 32 + fq * 8) * 2);
; #pragma unroll
;             for (int mi = 0; mi < 4; ++mi)
; #pragma unroll
;               for (int ni = 0; ni < 4; ++ni) acc[mi][ni] = __builtin_amdgcn_mfma_f32_16x16x32_bf16(A[mi], B[ni], acc[mi][ni], 0, 0, 0); }
	global_load_dwordx4 v[42:45], v[16:17], off
	v_or_b32_e32 v16, 0x1000, v14
	v_ashrrev_i32_e32 v15, 31, v14
	v_ashrrev_i32_e32 v17, 31, v16
	v_lshl_add_u64 v[12:13], v[14:15], 1, v[74:75]
	v_lshlrev_b64 v[16:17], 1, v[16:17]
	v_or_b32_e32 v14, 0x1800, v14
	v_lshl_add_u64 v[20:21], v[74:75], 0, v[16:17]
	v_ashrrev_i32_e32 v15, 31, v14
	global_load_dwordx4 v[58:61], v[20:21], off
	v_lshlrev_b64 v[20:21], 1, v[14:15]
	v_lshl_add_u64 v[14:15], v[74:75], 0, v[20:21]
	global_load_dwordx4 v[0:3], v[12:13], off
	global_load_dwordx4 v[124:127], v[12:13], off offset:64
	global_load_dwordx4 v[90:93], v[14:15], off
	ds_read_b128 v[4:7], v73 offset:1024
	ds_read_b128 v[22:25], v73 offset:5376
	ds_read_b128 v[30:33], v73 offset:9728
	ds_read_b128 v[132:135], v73 offset:9792
	ds_read_b128 v[34:37], v73 offset:14080
	ds_read_b128 v[136:139], v73 offset:14144
	s_waitcnt vmcnt(2) lgkmcnt(5)
	v_mfma_f32_16x16x32_bf16 v[8:11], v[0:3], v[4:7], 0
	ds_read_b128 v[128:131], v73 offset:5440
	v_lshl_add_u64 v[14:15], v[78:79], 0, v[18:19]
	s_waitcnt lgkmcnt(5)
	v_mfma_f32_16x16x32_bf16 v[26:29], v[0:3], v[22:25], 0
	s_waitcnt lgkmcnt(4)
	v_mfma_f32_16x16x32_bf16 v[38:41], v[0:3], v[30:33], 0
	s_waitcnt lgkmcnt(2)
	v_mfma_f32_16x16x32_bf16 v[0:3], v[0:3], v[34:37], 0
	v_mfma_f32_16x16x32_bf16 v[46:49], v[42:45], v[4:7], 0
	v_mfma_f32_16x16x32_bf16 v[50:53], v[42:45], v[22:25], 0
	v_mfma_f32_16x16x32_bf16 v[54:57], v[42:45], v[30:33], 0
	v_mfma_f32_16x16x32_bf16 v[42:45], v[42:45], v[34:37], 0
	v_mfma_f32_16x16x32_bf16 v[62:65], v[58:61], v[4:7], 0
	v_mfma_f32_16x16x32_bf16 v[66:69], v[58:61], v[22:25], 0
	v_mfma_f32_16x16x32_bf16 v[86:89], v[58:61], v[30:33], 0
	v_mfma_f32_16x16x32_bf16 v[58:61], v[58:61], v[34:37], 0
	s_waitcnt vmcnt(0)
	v_mfma_f32_16x16x32_bf16 v[4:7], v[90:93], v[4:7], 0
	v_mfma_f32_16x16x32_bf16 v[22:25], v[90:93], v[22:25], 0
	v_mfma_f32_16x16x32_bf16 v[30:33], v[90:93], v[30:33], 0
	v_mfma_f32_16x16x32_bf16 v[34:37], v[90:93], v[34:37], 0
	ds_read_b128 v[90:93], v73 offset:1088
	s_waitcnt lgkmcnt(0)
	v_mfma_f32_16x16x32_bf16 v[8:11], v[124:127], v[90:93], v[8:11]
	v_mfma_f32_16x16x32_bf16 v[26:29], v[124:127], v[128:131], v[26:29]
	v_mfma_f32_16x16x32_bf16 v[38:41], v[124:127], v[132:135], v[38:41]
	v_mfma_f32_16x16x32_bf16 v[0:3], v[124:127], v[136:139], v[0:3]
	global_load_dwordx4 v[124:127], v[14:15], off
	v_lshl_add_u64 v[14:15], v[78:79], 0, v[16:17]
	s_waitcnt vmcnt(0)
	v_mfma_f32_16x16x32_bf16 v[46:49], v[124:127], v[90:93], v[46:49]
	v_mfma_f32_16x16x32_bf16 v[50:53], v[124:127], v[128:131], v[50:53]
	v_mfma_f32_16x16x32_bf16 v[54:57], v[124:127], v[132:135], v[54:57]
	v_mfma_f32_16x16x32_bf16 v[42:45], v[124:127], v[136:139], v[42:45]
	global_load_dwordx4 v[124:127], v[14:15], off
	v_lshl_add_u64 v[14:15], v[78:79], 0, v[20:21]
	s_waitcnt vmcnt(0)
	v_mfma_f32_16x16x32_bf16 v[62:65], v[124:127], v[90:93], v[62:65]
	v_mfma_f32_16x16x32_bf16 v[66:69], v[124:127], v[128:131], v[66:69]
	v_mfma_f32_16x16x32_bf16 v[86:89], v[124:127], v[132:135], v[86:89]
	v_mfma_f32_16x16x32_bf16 v[58:61], v[124:127], v[136:139], v[58:61]
	global_load_dwordx4 v[124:127], v[14:15], off
	v_lshl_add_u64 v[14:15], v[80:81], 0, v[18:19]
	v_lshl_add_u64 v[18:19], v[82:83], 0, v[18:19]
	s_waitcnt vmcnt(0)
	v_mfma_f32_16x16x32_bf16 v[4:7], v[124:127], v[90:93], v[4:7]
	global_load_dwordx4 v[90:93], v[12:13], off offset:128
	v_mfma_f32_16x16x32_bf16 v[22:25], v[124:127], v[128:131], v[22:25]
	v_mfma_f32_16x16x32_bf16 v[30:33], v[124:127], v[132:135], v[30:33]
	ds_read_b128 v[132:135], v73 offset:9856
	v_mfma_f32_16x16x32_bf16 v[34:37], v[124:127], v[136:139], v[34:37]
	ds_read_b128 v[124:127], v73 offset:1152
	ds_read_b128 v[136:139], v73 offset:14208
	s_waitcnt vmcnt(0) lgkmcnt(1)
	v_mfma_f32_16x16x32_bf16 v[128:131], v[90:93], v[124:127], v[8:11]
	s_nop 2
	ds_read_b128 v[8:11], v73 offset:5504
	s_waitcnt lgkmcnt(0)
	v_mfma_f32_16x16x32_bf16 v[26:29], v[90:93], v[8:11], v[26:29]
	v_mfma_f32_16x16x32_bf16 v[38:41], v[90:93], v[132:135], v[38:41]
	v_mfma_f32_16x16x32_bf16 v[90:93], v[90:93], v[136:139], v[0:3]
	s_nop 2
	global_load_dwordx4 v[0:3], v[14:15], off
	v_lshl_add_u64 v[14:15], v[80:81], 0, v[16:17]
	s_waitcnt vmcnt(0)
	v_mfma_f32_16x16x32_bf16 v[140:143], v[0:3], v[124:127], v[46:49]
	v_lshl_add_u64 v[16:17], v[82:83], 0, v[16:17]
	v_mfma_f32_16x16x32_bf16 v[144:147], v[0:3], v[8:11], v[50:53]
	v_mfma_f32_16x16x32_bf16 v[52:55], v[0:3], v[132:135], v[54:57]
	v_mfma_f32_16x16x32_bf16 v[148:151], v[0:3], v[136:139], v[42:45]
	global_load_dwordx4 v[0:3], v[14:15], off
	v_lshl_add_u64 v[14:15], v[80:81], 0, v[20:21]
	s_nop 0
	global_load_dwordx4 v[42:45], v[14:15], off
	s_waitcnt vmcnt(1)
	v_mfma_f32_16x16x32_bf16 v[152:155], v[0:3], v[124:127], v[62:65]
	v_mfma_f32_16x16x32_bf16 v[156:159], v[0:3], v[8:11], v[66:69]
	v_mfma_f32_16x16x32_bf16 v[160:163], v[0:3], v[132:135], v[86:89]
	v_mfma_f32_16x16x32_bf16 v[164:167], v[0:3], v[136:139], v[58:61]
	s_nop 1
	v_lshl_add_u64 v[86:87], v[76:77], 0, s[12:13]
	s_waitcnt vmcnt(0)
	v_mfma_f32_16x16x32_bf16 v[0:3], v[42:45], v[124:127], v[4:7]
	ds_read_b128 v[124:127], v73 offset:1216
	v_mfma_f32_16x16x32_bf16 v[4:7], v[42:45], v[8:11], v[22:25]
	s_nop 2
	global_load_dwordx4 v[22:25], v[12:13], off offset:192
	v_mfma_f32_16x16x32_bf16 v[8:11], v[42:45], v[132:135], v[30:33]
	ds_read_b128 v[132:135], v73 offset:9920
	v_mfma_f32_16x16x32_bf16 v[12:15], v[42:45], v[136:139], v[34:37]
	ds_read_b128 v[136:139], v73 offset:14272
	s_waitcnt vmcnt(0) lgkmcnt(2)
	v_mfma_f32_16x16x32_bf16 v[60:63], v[22:25], v[124:127], v[128:131]
	s_nop 2
	ds_read_b128 v[128:131], v73 offset:5568
	s_waitcnt lgkmcnt(0)
; DEVFI float bf2f(bfraw h) { return __uint_as_float(((unsigned)h) << 16); }
; DEVFI bfraw f2bf(float x) { unsigned u = __float_as_uint(x); u += 0x7fffu + ((u >> 16) & 1u); return (bfraw)(u >> 16); }
; __global__ void __launch_bounds__(512) mega(Params p) {
;     ...
;           for (int sx = 0; sx < 4; ++sx) { bf16x8 A[4], B[4];
; #pragma unroll
;             for (int mi = 0; mi < 4; ++mi) A[mi] = *(const bf16x8*)(wsg_ + (g * 128 + wm * 64 + mi * 16 + fr) * 128 + sx * 32 + fq * 8);
; #pragma unroll
;             for (int ni = 0; ni < 4; ++ni) B[ni] = *(const bf16x8*)(tile + (wn * 64 + ni * 16 + fr) * PITCH + (sx * 32 + fq * 8) * 2);
; #pragma unroll
;             for (int mi = 0; mi < 4; ++mi)
; #pragma unroll
;               for (int ni = 0; ni < 4; ++ni) acc[mi][ni] = __builtin_amdgcn_mfma_f32_16x16x32_bf16(A[mi], B[ni], acc[mi][ni], 0, 0, 0); }
; #pragma unroll
;           for (int mi = 0; mi < 4; ++mi)
; #pragma unroll
;             for (int j = 0; j < 4; ++j) { const int c = wm * 64 + mi * 16 + fq * 4 + j; const float bb = sgb_[g * 128 + c];
;               bfraw* up = su_ + (long)(chunk * 128 + c) * 1024 + g * 256 + wn * 64 + fr;
; #pragma unroll
;               for (int ni = 0; ni < 4; ++ni) up[ni * 16] = f2bf((acc[mi][ni][j] + bb) * bf2f(up[ni * 16])); }
	v_mfma_f32_16x16x32_bf16 v[64:67], v[22:25], v[128:131], v[26:29]
	v_mfma_f32_16x16x32_bf16 v[48:51], v[22:25], v[132:135], v[38:41]
	v_mfma_f32_16x16x32_bf16 v[56:59], v[22:25], v[136:139], v[90:93]
	global_load_dwordx4 v[22:25], v[18:19], off
	s_nop 1
	global_load_dwordx4 v[90:93], v[16:17], off
	v_lshl_add_u64 v[16:17], v[82:83], 0, v[20:21]
	s_waitcnt vmcnt(1)
	v_mfma_f32_16x16x32_bf16 v[36:39], v[22:25], v[132:135], v[52:55]
	s_nop 2
	global_load_dwordx4 v[52:55], v[16:17], off
	v_lshl_add_u32 v16, s2, 7, v99
	v_ashrrev_i32_e32 v17, 31, v16
	v_lshl_add_u64 v[88:89], v[16:17], 2, s[22:23]
	v_add_u32_e32 v16, s24, v99
	v_ashrrev_i32_e32 v17, 31, v16
	v_lshlrev_b64 v[16:17], 11, v[16:17]
	v_mfma_f32_16x16x32_bf16 v[44:47], v[22:25], v[124:127], v[140:143]
	global_load_dwordx4 v[68:71], v[88:89], off
	v_add_u32_e32 v20, s24, v108
	v_ashrrev_i32_e32 v21, 31, v20
	v_lshl_add_u64 v[140:141], v[86:87], 0, v[16:17]
	global_load_ushort v123, v[140:141], off
	global_load_ushort v142, v[140:141], off offset:32
	v_mfma_f32_16x16x32_bf16 v[40:43], v[22:25], v[128:131], v[144:147]
	global_load_ushort v143, v[140:141], off offset:64
	s_nop 1
	global_load_ushort v144, v[140:141], off offset:96
	v_lshlrev_b64 v[20:21], 11, v[20:21]
	v_lshl_add_u64 v[94:95], v[86:87], 0, v[20:21]
	global_load_ushort v145, v[94:95], off
	global_load_ushort v146, v[94:95], off offset:32
	s_waitcnt vmcnt(8)
	v_mfma_f32_16x16x32_bf16 v[28:31], v[90:93], v[124:127], v[152:155]
	v_readlane_b32 s2, v254, 5
	s_add_i32 s14, s14, s2
	s_cmpk_gt_i32 s15, 0x1ff
	s_waitcnt vmcnt(7)
	v_mfma_f32_16x16x32_bf16 v[0:3], v[52:55], v[124:127], v[0:3]
	global_load_ushort v124, v[94:95], off offset:64
	global_load_ushort v125, v[94:95], off offset:96
	v_readlane_b32 s3, v254, 6
	s_waitcnt vmcnt(8)
	v_add_f32_e32 v48, v68, v48
	v_mfma_f32_16x16x32_bf16 v[32:35], v[22:25], v[136:139], v[148:151]
	v_mfma_f32_16x16x32_bf16 v[16:19], v[90:93], v[128:131], v[156:159]
	v_mfma_f32_16x16x32_bf16 v[24:27], v[90:93], v[132:135], v[160:163]
	v_mfma_f32_16x16x32_bf16 v[20:23], v[90:93], v[136:139], v[164:167]
	v_add_u32_e32 v90, s24, v109
	v_ashrrev_i32_e32 v91, 31, v90
	v_lshlrev_b64 v[90:91], 11, v[90:91]
	v_lshl_add_u64 v[92:93], v[86:87], 0, v[90:91]
	global_load_ushort v126, v[92:93], off
	global_load_ushort v127, v[92:93], off offset:32
	v_mfma_f32_16x16x32_bf16 v[4:7], v[52:55], v[128:131], v[4:7]
	global_load_ushort v128, v[92:93], off offset:96
	v_mfma_f32_16x16x32_bf16 v[8:11], v[52:55], v[132:135], v[8:11]
	v_mfma_f32_16x16x32_bf16 v[12:15], v[52:55], v[136:139], v[12:15]
	v_add_f32_e32 v52, v68, v60
	s_waitcnt vmcnt(10)
	v_lshlrev_b32_e32 v53, 16, v123
	v_mul_f32_e32 v52, v52, v53
	v_cvt_pk_bf16_f32 v52, v52, v52
	global_load_ushort v123, v[92:93], off offset:64
	s_waitcnt vmcnt(10)
	v_lshlrev_b32_e32 v53, 16, v142
	global_store_short_d16_hi v[140:141], v52, off
	v_add_f32_e32 v52, v68, v64
	v_mul_f32_e32 v52, v52, v53
	v_cvt_pk_bf16_f32 v52, v52, v52
	global_store_short_d16_hi v[140:141], v52, off offset:32
	v_add_u32_e32 v52, s24, v110
	v_ashrrev_i32_e32 v53, 31, v52
	v_lshlrev_b64 v[52:53], 11, v[52:53]
	v_lshl_add_u64 v[90:91], v[86:87], 0, v[52:53]
	global_load_ushort v129, v[90:91], off
	global_load_ushort v130, v[90:91], off offset:32
	s_waitcnt vmcnt(13)
	v_lshlrev_b32_e32 v52, 16, v143
	v_mul_f32_e32 v48, v48, v52
	v_cvt_pk_bf16_f32 v48, v48, v48
	global_store_short_d16_hi v[140:141], v48, off offset:64
	v_add_f32_e32 v48, v68, v56
	s_waitcnt vmcnt(13)
	v_lshlrev_b32_e32 v52, 16, v144
	v_mul_f32_e32 v48, v48, v52
	global_load_ushort v68, v[90:91], off offset:64
	v_cvt_pk_bf16_f32 v48, v48, v48
	global_store_short_d16_hi v[140:141], v48, off offset:96
	v_add_f32_e32 v48, v69, v61
	s_waitcnt vmcnt(14)
	v_lshlrev_b32_e32 v52, 16, v145
	v_mul_f32_e32 v48, v48, v52
	v_cvt_pk_bf16_f32 v48, v48, v48
	global_store_short_d16_hi v[94:95], v48, off
	v_add_f32_e32 v48, v69, v65
	s_waitcnt vmcnt(14)
	v_lshlrev_b32_e32 v52, 16, v146
	v_mul_f32_e32 v48, v48, v52
	v_add_u32_e32 v60, s24, v111
	v_cvt_pk_bf16_f32 v48, v48, v48
	global_load_ushort v131, v[90:91], off offset:96
	global_load_dwordx4 v[52:55], v[88:89], off offset:64
	v_ashrrev_i32_e32 v61, 31, v60
	v_lshlrev_b64 v[60:61], 11, v[60:61]
	v_lshl_add_u64 v[64:65], v[86:87], 0, v[60:61]
	global_load_ushort v132, v[64:65], off
	s_waitcnt vmcnt(1)
; DEVFI float bf2f(bfraw h) { return __uint_as_float(((unsigned)h) << 16); }
; DEVFI bfraw f2bf(float x) { unsigned u = __float_as_uint(x); u += 0x7fffu + ((u >> 16) & 1u); return (bfraw)(u >> 16); }
; __global__ void __launch_bounds__(512) mega(Params p) {
;     ...
;           for (int mi = 0; mi < 4; ++mi)
; #pragma unroll
;             for (int j = 0; j < 4; ++j) { const int c = wm * 64 + mi * 16 + fq * 4 + j; const float bb = sgb_[g * 128 + c];
;               bfraw* up = su_ + (long)(chunk * 128 + c) * 1024 + g * 256 + wn * 64 + fr;
; #pragma unroll
;               for (int ni = 0; ni < 4; ++ni) up[ni * 16] = f2bf((acc[mi][ni][j] + bb) * bf2f(up[ni * 16])); }
	v_add_f32_e32 v44, v52, v44
	global_store_short_d16_hi v[94:95], v48, off offset:32
	v_add_f32_e32 v48, v69, v49
	v_lshlrev_b32_e32 v49, 16, v124
	v_mul_f32_e32 v48, v48, v49
	v_cvt_pk_bf16_f32 v48, v48, v48
	global_store_short_d16_hi v[94:95], v48, off offset:64
	v_add_f32_e32 v48, v69, v57
	v_lshlrev_b32_e32 v49, 16, v125
	global_load_ushort v124, v[64:65], off offset:32
	v_mul_f32_e32 v48, v48, v49
	v_cvt_pk_bf16_f32 v48, v48, v48
	global_store_short_d16_hi v[94:95], v48, off offset:96
	v_add_f32_e32 v48, v70, v62
	v_lshlrev_b32_e32 v49, 16, v126
	v_mul_f32_e32 v48, v48, v49
	global_load_ushort v62, v[64:65], off offset:64
	v_cvt_pk_bf16_f32 v48, v48, v48
	global_store_short_d16_hi v[92:93], v48, off
	v_add_f32_e32 v48, v70, v66
	v_lshlrev_b32_e32 v49, 16, v127
	v_mul_f32_e32 v48, v48, v49
	global_load_ushort v66, v[64:65], off offset:96
	v_cvt_pk_bf16_f32 v56, v48, v48
	v_add_u32_e32 v48, s24, v112
	v_ashrrev_i32_e32 v49, 31, v48
	v_lshlrev_b64 v[48:49], 11, v[48:49]
	v_lshl_add_u64 v[60:61], v[86:87], 0, v[48:49]
	global_load_ushort v69, v[60:61], off
	v_add_f32_e32 v48, v70, v50
	v_lshlrev_b32_e32 v49, 16, v123
	v_mul_f32_e32 v48, v48, v49
	global_load_ushort v50, v[60:61], off offset:32
	v_cvt_pk_bf16_f32 v48, v48, v48
	global_store_short_d16_hi v[92:93], v48, off offset:64
	v_add_f32_e32 v48, v70, v58
	v_lshlrev_b32_e32 v49, 16, v128
	v_mul_f32_e32 v48, v48, v49
	v_cvt_pk_bf16_f32 v48, v48, v48
	global_store_short_d16_hi v[92:93], v48, off offset:96
	v_add_f32_e32 v48, v71, v63
	v_lshlrev_b32_e32 v49, 16, v129
	v_mul_f32_e32 v48, v48, v49
	global_load_ushort v70, v[60:61], off offset:64
	v_cvt_pk_bf16_f32 v48, v48, v48
	global_store_short_d16_hi v[90:91], v48, off
	v_add_f32_e32 v48, v71, v67
	v_lshlrev_b32_e32 v49, 16, v130
	v_mul_f32_e32 v48, v48, v49
	v_cvt_pk_bf16_f32 v48, v48, v48
	global_load_ushort v67, v[60:61], off offset:96
	v_add_f32_e32 v40, v52, v40
	global_store_short_d16_hi v[90:91], v48, off offset:32
	v_add_u32_e32 v48, s24, v113
	v_ashrrev_i32_e32 v49, 31, v48
	v_lshlrev_b64 v[48:49], 11, v[48:49]
	global_store_short_d16_hi v[92:93], v56, off offset:32
	v_lshl_add_u64 v[56:57], v[86:87], 0, v[48:49]
	global_load_ushort v92, v[56:57], off
	v_lshlrev_b32_e32 v49, 16, v68
	global_load_ushort v68, v[56:57], off offset:32
	v_add_f32_e32 v48, v71, v51
	v_mul_f32_e32 v48, v48, v49
	v_cvt_pk_bf16_f32 v48, v48, v48
	global_store_short_d16_hi v[90:91], v48, off offset:64
	v_add_f32_e32 v48, v71, v59
	v_lshlrev_b32_e32 v49, 16, v131
	v_mul_f32_e32 v48, v48, v49
	v_cvt_pk_bf16_f32 v48, v48, v48
	global_load_ushort v71, v[56:57], off offset:64
	v_add_f32_e32 v36, v52, v36
	global_store_short_d16_hi v[90:91], v48, off offset:96
	s_waitcnt vmcnt(21)
	v_lshlrev_b32_e32 v48, 16, v132
	v_mul_f32_e32 v44, v44, v48
	v_cvt_pk_bf16_f32 v44, v44, v44
	global_load_ushort v90, v[56:57], off offset:96
	v_add_u32_e32 v48, s24, v114
	v_ashrrev_i32_e32 v49, 31, v48
	v_lshlrev_b64 v[48:49], 11, v[48:49]
	v_lshl_add_u64 v[58:59], v[86:87], 0, v[48:49]
	global_load_ushort v91, v[58:59], off
	v_add_f32_e32 v32, v52, v32
	global_store_short_d16_hi v[64:65], v44, off
	s_waitcnt vmcnt(21)
	v_lshlrev_b32_e32 v44, 16, v124
	v_mul_f32_e32 v40, v40, v44
	v_cvt_pk_bf16_f32 v40, v40, v40
	global_store_short_d16_hi v[64:65], v40, off offset:32
	s_waitcnt vmcnt(20)
	v_lshlrev_b32_e32 v40, 16, v62
	v_mul_f32_e32 v36, v36, v40
	v_cvt_pk_bf16_f32 v36, v36, v36
	global_store_short_d16_hi v[64:65], v36, off offset:64
	global_load_ushort v36, v[58:59], off offset:32
	s_waitcnt vmcnt(20)
	v_lshlrev_b32_e32 v40, 16, v66
	v_mul_f32_e32 v32, v32, v40
	v_cvt_pk_bf16_f32 v32, v32, v32
	global_store_short_d16_hi v[64:65], v32, off offset:96
	v_add_f32_e32 v32, v53, v45
	global_load_ushort v52, v[58:59], off offset:64
	s_waitcnt vmcnt(21)
	v_lshlrev_b32_e32 v40, 16, v69
	v_mul_f32_e32 v32, v32, v40
	v_cvt_pk_bf16_f32 v32, v32, v32
	global_store_short_d16_hi v[60:61], v32, off
	v_add_f32_e32 v32, v53, v41
	s_waitcnt vmcnt(21)
	v_lshlrev_b32_e32 v40, 16, v50
	v_mul_f32_e32 v32, v32, v40
	v_cvt_pk_bf16_f32 v32, v32, v32
	v_add_u32_e32 v40, s24, v115
	global_load_ushort v64, v[58:59], off offset:96
	global_load_dwordx4 v[48:51], v[88:89], off offset:128
	v_ashrrev_i32_e32 v41, 31, v40
	v_lshlrev_b64 v[40:41], 11, v[40:41]
	v_lshl_add_u64 v[62:63], v[86:87], 0, v[40:41]
	global_load_ushort v65, v[62:63], off
	s_waitcnt vmcnt(1)
; DEVFI float bf2f(bfraw h) { return __uint_as_float(((unsigned)h) << 16); }
; DEVFI bfraw f2bf(float x) { unsigned u = __float_as_uint(x); u += 0x7fffu + ((u >> 16) & 1u); return (bfraw)(u >> 16); }
; __global__ void __launch_bounds__(512) mega(Params p) {
;     ...
;           for (int mi = 0; mi < 4; ++mi)
; #pragma unroll
;             for (int j = 0; j < 4; ++j) { const int c = wm * 64 + mi * 16 + fq * 4 + j; const float bb = sgb_[g * 128 + c];
;               bfraw* up = su_ + (long)(chunk * 128 + c) * 1024 + g * 256 + wn * 64 + fr;
; #pragma unroll
;               for (int ni = 0; ni < 4; ++ni) up[ni * 16] = f2bf((acc[mi][ni][j] + bb) * bf2f(up[ni * 16])); }
	v_add_f32_e32 v28, v48, v28
	global_store_short_d16_hi v[60:61], v32, off offset:32
	v_add_f32_e32 v32, v53, v37
	v_lshlrev_b32_e32 v37, 16, v70
	v_mul_f32_e32 v32, v32, v37
	v_cvt_pk_bf16_f32 v32, v32, v32
	global_load_ushort v37, v[62:63], off offset:32
	v_add_f32_e32 v16, v48, v16
	global_store_short_d16_hi v[60:61], v32, off offset:64
	v_add_f32_e32 v32, v53, v33
	v_lshlrev_b32_e32 v33, 16, v67
	v_mul_f32_e32 v32, v32, v33
	v_cvt_pk_bf16_f32 v32, v32, v32
	global_store_short_d16_hi v[60:61], v32, off offset:96
	v_add_f32_e32 v32, v54, v46
	v_lshlrev_b32_e32 v33, 16, v92
	v_mul_f32_e32 v32, v32, v33
	global_load_ushort v46, v[62:63], off offset:64
	v_cvt_pk_bf16_f32 v32, v32, v32
	global_store_short_d16_hi v[56:57], v32, off
	v_add_f32_e32 v32, v54, v42
	v_lshlrev_b32_e32 v33, 16, v68
	v_mul_f32_e32 v32, v32, v33
	global_load_ushort v42, v[62:63], off offset:96
	v_cvt_pk_bf16_f32 v40, v32, v32
	v_add_u32_e32 v32, s24, v116
	v_ashrrev_i32_e32 v33, 31, v32
	v_lshlrev_b64 v[32:33], 11, v[32:33]
	v_lshl_add_u64 v[44:45], v[86:87], 0, v[32:33]
	global_load_ushort v53, v[44:45], off
	v_add_f32_e32 v32, v54, v38
	v_lshlrev_b32_e32 v33, 16, v71
	global_load_ushort v38, v[44:45], off offset:32
	v_mul_f32_e32 v32, v32, v33
	v_cvt_pk_bf16_f32 v32, v32, v32
	global_store_short_d16_hi v[56:57], v32, off offset:64
	v_add_f32_e32 v32, v54, v34
	v_lshlrev_b32_e32 v33, 16, v90
	global_load_ushort v34, v[44:45], off offset:64
	v_mul_f32_e32 v32, v32, v33
	v_cvt_pk_bf16_f32 v32, v32, v32
	global_store_short_d16_hi v[56:57], v32, off offset:96
	v_add_f32_e32 v32, v55, v47
	v_lshlrev_b32_e32 v33, 16, v91
	v_mul_f32_e32 v32, v32, v33
	v_cvt_pk_bf16_f32 v32, v32, v32
	global_store_short_d16_hi v[58:59], v32, off
	v_add_f32_e32 v32, v55, v43
	global_load_ushort v43, v[44:45], off offset:96
	v_lshlrev_b32_e32 v33, 16, v36
	v_mul_f32_e32 v32, v32, v33
	v_cvt_pk_bf16_f32 v32, v32, v32
	global_store_short_d16_hi v[58:59], v32, off offset:32
	v_add_u32_e32 v32, s24, v117
	v_ashrrev_i32_e32 v33, 31, v32
	v_lshlrev_b64 v[32:33], 11, v[32:33]
	global_store_short_d16_hi v[56:57], v40, off offset:32
	v_lshl_add_u64 v[40:41], v[86:87], 0, v[32:33]
	global_load_ushort v47, v[40:41], off
	v_add_f32_e32 v32, v55, v39
	v_lshlrev_b32_e32 v33, 16, v52
	v_mul_f32_e32 v32, v32, v33
	v_cvt_pk_bf16_f32 v32, v32, v32
	global_load_ushort v39, v[40:41], off offset:32
	global_load_ushort v52, v[40:41], off offset:64
	v_lshlrev_b32_e32 v33, 16, v64
	global_store_short_d16_hi v[58:59], v32, off offset:64
	v_add_f32_e32 v32, v55, v35
	v_mul_f32_e32 v32, v32, v33
	v_cvt_pk_bf16_f32 v32, v32, v32
	global_store_short_d16_hi v[58:59], v32, off offset:96
	s_waitcnt vmcnt(21)
	v_lshlrev_b32_e32 v32, 16, v65
	v_mul_f32_e32 v28, v28, v32
	v_cvt_pk_bf16_f32 v28, v28, v28
	global_store_short_d16_hi v[62:63], v28, off
	v_add_u32_e32 v32, s24, v118
	s_waitcnt vmcnt(20)
	v_lshlrev_b32_e32 v28, 16, v37
	v_mul_f32_e32 v16, v16, v28
	v_cvt_pk_bf16_f32 v16, v16, v16
	global_load_ushort v28, v[40:41], off offset:96
	v_ashrrev_i32_e32 v33, 31, v32
	v_lshlrev_b64 v[32:33], 11, v[32:33]
	v_lshl_add_u64 v[36:37], v[86:87], 0, v[32:33]
	global_load_ushort v54, v[36:37], off
	v_add_f32_e32 v18, v50, v18
	global_store_short_d16_hi v[62:63], v16, off offset:32
	v_add_f32_e32 v16, v48, v24
	s_waitcnt vmcnt(20)
	v_lshlrev_b32_e32 v24, 16, v46
	v_mul_f32_e32 v16, v16, v24
	v_cvt_pk_bf16_f32 v16, v16, v16
	global_store_short_d16_hi v[62:63], v16, off offset:64
	v_add_f32_e32 v16, v48, v20
	global_load_ushort v46, v[36:37], off offset:64
	global_load_ushort v24, v[36:37], off offset:96
	s_waitcnt vmcnt(21)
	v_lshlrev_b32_e32 v20, 16, v42
	v_mul_f32_e32 v16, v16, v20
	v_cvt_pk_bf16_f32 v16, v16, v16
	global_load_ushort v42, v[36:37], off offset:32
	s_waitcnt vmcnt(21)
	v_lshlrev_b32_e32 v20, 16, v53
	global_store_short_d16_hi v[62:63], v16, off offset:96
	v_add_f32_e32 v16, v49, v29
	v_mul_f32_e32 v16, v16, v20
	v_cvt_pk_bf16_f32 v16, v16, v16
	global_store_short_d16_hi v[44:45], v16, off
	v_add_f32_e32 v16, v49, v17
	s_waitcnt vmcnt(22)
	v_lshlrev_b32_e32 v17, 16, v38
	v_mul_f32_e32 v16, v16, v17
	v_cvt_pk_bf16_f32 v16, v16, v16
	global_store_short_d16_hi v[44:45], v16, off offset:32
	v_add_f32_e32 v16, v49, v25
	s_waitcnt vmcnt(21)
	v_lshlrev_b32_e32 v17, 16, v34
	v_mul_f32_e32 v16, v16, v17
	v_cvt_pk_bf16_f32 v16, v16, v16
	global_store_short_d16_hi v[44:45], v16, off offset:64
	v_add_u32_e32 v16, s24, v119
	v_ashrrev_i32_e32 v17, 31, v16
	v_lshlrev_b64 v[16:17], 11, v[16:17]
	v_lshl_add_u64 v[16:17], v[86:87], 0, v[16:17]
	global_load_dwordx4 v[32:35], v[88:89], off offset:192
	global_load_ushort v25, v[16:17], off
	global_load_ushort v38, v[16:17], off offset:64
	v_add_f32_e32 v20, v49, v21
	s_waitcnt vmcnt(22)
	v_lshlrev_b32_e32 v21, 16, v43
	v_mul_f32_e32 v20, v20, v21
	v_cvt_pk_bf16_f32 v20, v20, v20
	global_store_short_d16_hi v[44:45], v20, off offset:96
	v_add_f32_e32 v20, v50, v30
	global_load_ushort v30, v[16:17], off offset:32
	s_waitcnt vmcnt(21)
	v_lshlrev_b32_e32 v21, 16, v47
	v_mul_f32_e32 v20, v20, v21
	v_cvt_pk_bf16_f32 v20, v20, v20
	global_store_short_d16_hi v[40:41], v20, off
	s_waitcnt vmcnt(21)
; DEVFI float bf2f(bfraw h) { return __uint_as_float(((unsigned)h) << 16); }
; DEVFI bfraw f2bf(float x) { unsigned u = __float_as_uint(x); u += 0x7fffu + ((u >> 16) & 1u); return (bfraw)(u >> 16); }
; __global__ void __launch_bounds__(512) mega(Params p) {
;     ...
;           for (int mi = 0; mi < 4; ++mi)
; #pragma unroll
;             for (int j = 0; j < 4; ++j) { const int c = wm * 64 + mi * 16 + fq * 4 + j; const float bb = sgb_[g * 128 + c];
;               bfraw* up = su_ + (long)(chunk * 128 + c) * 1024 + g * 256 + wn * 64 + fr;
; #pragma unroll
;               for (int ni = 0; ni < 4; ++ni) up[ni * 16] = f2bf((acc[mi][ni][j] + bb) * bf2f(up[ni * 16])); }
	v_lshlrev_b32_e32 v20, 16, v39
	v_mul_f32_e32 v18, v18, v20
	v_cvt_pk_bf16_f32 v18, v18, v18
	global_load_ushort v39, v[16:17], off offset:96
	v_add_u32_e32 v20, s24, v120
	v_ashrrev_i32_e32 v21, 31, v20
	v_lshlrev_b64 v[20:21], 11, v[20:21]
	v_lshl_add_u64 v[20:21], v[86:87], 0, v[20:21]
	global_store_short_d16_hi v[40:41], v18, off offset:32
	v_add_f32_e32 v18, v50, v26
	global_load_ushort v26, v[20:21], off
	s_waitcnt vmcnt(23)
	v_lshlrev_b32_e32 v29, 16, v52
	v_mul_f32_e32 v18, v18, v29
	v_cvt_pk_bf16_f32 v18, v18, v18
	global_load_ushort v43, v[20:21], off offset:32
	s_waitcnt vmcnt(9)
	v_add_f32_e32 v0, v32, v0
	global_store_short_d16_hi v[40:41], v18, off offset:64
	v_add_f32_e32 v18, v50, v22
	v_lshlrev_b32_e32 v22, 16, v28
	v_mul_f32_e32 v18, v18, v22
	v_cvt_pk_bf16_f32 v18, v18, v18
	global_load_ushort v22, v[20:21], off offset:64
	v_lshlrev_b32_e32 v28, 16, v54
	global_store_short_d16_hi v[40:41], v18, off offset:96
	v_add_f32_e32 v18, v51, v31
	v_mul_f32_e32 v18, v18, v28
	global_load_ushort v31, v[20:21], off offset:96
	v_cvt_pk_bf16_f32 v18, v18, v18
	v_add_u32_e32 v28, s24, v121
	v_ashrrev_i32_e32 v29, 31, v28
	v_lshlrev_b64 v[28:29], 11, v[28:29]
	v_lshl_add_u64 v[28:29], v[86:87], 0, v[28:29]
	global_load_ushort v40, v[28:29], off
	global_load_ushort v41, v[28:29], off offset:32
	v_add_f32_e32 v8, v32, v8
	global_store_short_d16_hi v[36:37], v18, off
	v_add_f32_e32 v18, v51, v19
	v_lshlrev_b32_e32 v19, 16, v42
	v_mul_f32_e32 v18, v18, v19
	v_cvt_pk_bf16_f32 v18, v18, v18
	global_store_short_d16_hi v[36:37], v18, off offset:32
	v_add_f32_e32 v18, v51, v27
	v_lshlrev_b32_e32 v19, 16, v46
	v_mul_f32_e32 v18, v18, v19
	global_load_ushort v27, v[28:29], off offset:64
	v_cvt_pk_bf16_f32 v18, v18, v18
	global_store_short_d16_hi v[36:37], v18, off offset:64
	v_add_f32_e32 v18, v51, v23
	v_lshlrev_b32_e32 v19, 16, v24
	global_load_ushort v23, v[28:29], off offset:96
	v_mul_f32_e32 v24, v18, v19
	v_add_u32_e32 v18, s24, v122
	v_ashrrev_i32_e32 v19, 31, v18
	v_lshlrev_b64 v[18:19], 11, v[18:19]
	v_lshl_add_u64 v[18:19], v[86:87], 0, v[18:19]
	global_load_ushort v42, v[18:19], off
	v_bfe_u32 v44, v24, 16, 1
	v_add3_u32 v24, v24, v44, s82
	global_store_short_d16_hi v[36:37], v24, off offset:96
	s_waitcnt vmcnt(21)
	v_lshlrev_b32_e32 v24, 16, v25
	global_load_ushort v25, v[18:19], off offset:32
	v_mul_f32_e32 v0, v0, v24
	v_cvt_pk_bf16_f32 v0, v0, v0
	global_store_short_d16_hi v[16:17], v0, off
	v_add_f32_e32 v0, v32, v4
	global_load_ushort v4, v[18:19], off offset:64
	s_waitcnt vmcnt(21)
	v_lshlrev_b32_e32 v24, 16, v30
	v_mul_f32_e32 v0, v0, v24
	v_cvt_pk_bf16_f32 v0, v0, v0
	global_store_short_d16_hi v[16:17], v0, off offset:32
	global_load_ushort v0, v[18:19], off offset:96
	v_lshlrev_b32_e32 v24, 16, v38
	v_mul_f32_e32 v8, v8, v24
	v_bfe_u32 v24, v8, 16, 1
	v_add3_u32 v8, v8, v24, s82
	global_store_short_d16_hi v[16:17], v8, off offset:64
	v_add_f32_e32 v8, v32, v12
	s_waitcnt vmcnt(22)
	v_lshlrev_b32_e32 v12, 16, v39
	v_mul_f32_e32 v8, v8, v12
	v_bfe_u32 v12, v8, 16, 1
	v_add3_u32 v8, v8, v12, s82
	global_store_short_d16_hi v[16:17], v8, off offset:96
	v_add_f32_e32 v1, v33, v1
	s_waitcnt vmcnt(21)
	v_lshlrev_b32_e32 v8, 16, v26
	v_mul_f32_e32 v1, v1, v8
	v_bfe_u32 v8, v1, 16, 1
	v_add3_u32 v1, v1, v8, s82
	global_store_short_d16_hi v[20:21], v1, off
	v_add_f32_e32 v1, v33, v5
	s_waitcnt vmcnt(21)
	v_lshlrev_b32_e32 v5, 16, v43
	v_mul_f32_e32 v1, v1, v5
	v_cvt_pk_bf16_f32 v1, v1, v1
	global_store_short_d16_hi v[20:21], v1, off offset:32
	v_add_f32_e32 v1, v33, v9
	s_waitcnt vmcnt(20)
	v_lshlrev_b32_e32 v5, 16, v22
	v_mul_f32_e32 v1, v1, v5
	v_cvt_pk_bf16_f32 v1, v1, v1
	global_store_short_d16_hi v[20:21], v1, off offset:64
	v_add_f32_e32 v1, v33, v13
	s_waitcnt vmcnt(19)
	v_lshlrev_b32_e32 v5, 16, v31
	v_mul_f32_e32 v1, v1, v5
	v_bfe_u32 v5, v1, 16, 1
	v_add3_u32 v1, v1, v5, s82
	global_store_short_d16_hi v[20:21], v1, off offset:96
	v_add_f32_e32 v1, v34, v2
	s_waitcnt vmcnt(19)
	v_lshlrev_b32_e32 v2, 16, v40
	v_mul_f32_e32 v1, v1, v2
	v_cvt_pk_bf16_f32 v1, v1, v1
	global_store_short_d16_hi v[28:29], v1, off
	v_add_f32_e32 v1, v34, v6
	s_waitcnt vmcnt(19)
	v_lshlrev_b32_e32 v2, 16, v41
	v_mul_f32_e32 v1, v1, v2
	v_cvt_pk_bf16_f32 v1, v1, v1
	global_store_short_d16_hi v[28:29], v1, off offset:32
	v_add_f32_e32 v1, v34, v10
	s_waitcnt vmcnt(17)
	v_lshlrev_b32_e32 v2, 16, v27
	v_mul_f32_e32 v1, v1, v2
	v_cvt_pk_bf16_f32 v1, v1, v1
	global_store_short_d16_hi v[28:29], v1, off offset:64
	v_add_f32_e32 v1, v34, v14
	s_waitcnt vmcnt(16)
	v_lshlrev_b32_e32 v2, 16, v23
	v_mul_f32_e32 v1, v1, v2
	v_cvt_pk_bf16_f32 v1, v1, v1
	global_store_short_d16_hi v[28:29], v1, off offset:96
	v_add_f32_e32 v1, v35, v3
	s_waitcnt vmcnt(16)
	v_lshlrev_b32_e32 v2, 16, v42
	v_mul_f32_e32 v1, v1, v2
	v_cvt_pk_bf16_f32 v1, v1, v1
	global_store_short_d16_hi v[18:19], v1, off
	v_add_f32_e32 v1, v35, v7
	s_waitcnt vmcnt(15)
	v_lshlrev_b32_e32 v2, 16, v25
	v_mul_f32_e32 v1, v1, v2
	v_cvt_pk_bf16_f32 v1, v1, v1
	global_store_short_d16_hi v[18:19], v1, off offset:32
	v_add_f32_e32 v1, v35, v11
	s_waitcnt vmcnt(14)
	v_lshlrev_b32_e32 v2, 16, v4
	v_mul_f32_e32 v1, v1, v2
	v_bfe_u32 v2, v1, 16, 1
	v_add3_u32 v1, v1, v2, s82
	global_store_short_d16_hi v[18:19], v1, off offset:64
	v_add_f32_e32 v1, v35, v15
	s_waitcnt vmcnt(13)
	v_lshlrev_b32_e32 v0, 16, v0
	v_mul_f32_e32 v0, v1, v0
	v_bfe_u32 v1, v0, 16, 1
	v_add3_u32 v0, v0, v1, s82
	global_store_short_d16_hi v[18:19], v0, off offset:96
	s_cbranch_scc1 .LBB0_2429

; DEVFI bfraw f2bf(float x) { unsigned u = __float_as_uint(x); u += 0x7fffu + ((u >> 16) & 1u); return (bfraw)(u >> 16); }
; DEVFI int crow(int r, int hi) { return (r & 3) + 8 * (r >> 2) + 4 * hi; }
; template <int LDQ, int LDK, int LDO>
; DEVFI void attn_dense_body(const bfraw* __restrict__ Qb, const bfraw* __restrict__ Kh, const bfraw* __restrict__ Vh,
;                            bfraw* __restrict__ Ob, int seq, char* lds, const int wv) {
;     ...
;   if (hi == 0) li_l[r32] = l_reg; asm volatile("s_waitcnt lgkmcnt(0)" ::: "memory");
;   float rli[16];
; #pragma unroll
;   for (int r = 0; r < 16; ++r) rli[r] = __builtin_amdgcn_rcpf(li_l[crow(r, hi)]);
;   bfraw* Ow = Ob + (long)(wid * AQBLK) * LDO;
; #pragma unroll
;   for (int r = 0; r < 16; ++r) { int orow = crow(r, hi);
; #pragma unroll
;     for (int d0 = 0; d0 < 4; ++d0) Ow[(long)orow * LDO + d0 * 32 + r32] = f2bf(o[d0][r] * rli[r]); }
.LBB0_2454:
	s_or_b64 exec, exec, s[2:3]
	s_waitcnt lgkmcnt(0)
	v_add_u32_e32 v72, v185, v176
	ds_read_b128 v[64:67], v72
	ds_read_b128 v[68:71], v72 offset:32
	s_lshl_b64 s[2:3], s[74:75], 1
	s_add_u32 s2, s44, s2
	s_addc_u32 s3, s45, s3
	s_waitcnt lgkmcnt(1)
	v_rcp_f32_e32 v73, v64
	v_rcp_f32_e32 v74, v65
	v_rcp_f32_e32 v75, v66
	v_rcp_f32_e32 v76, v67
	ds_read_b128 v[64:67], v72 offset:64
	s_add_u32 s2, s2, s76
	s_waitcnt lgkmcnt(1)
	v_rcp_f32_e32 v77, v68
	v_rcp_f32_e32 v78, v69
	v_rcp_f32_e32 v79, v70
	v_rcp_f32_e32 v80, v71
	ds_read_b128 v[68:71], v72 offset:96
	v_ashrrev_i32_e32 v185, 31, v184
	s_addc_u32 s3, s3, s77
	s_waitcnt lgkmcnt(1)
	v_rcp_f32_e32 v72, v64
	v_rcp_f32_e32 v81, v65
	v_lshlrev_b64 v[64:65], 11, v[184:185]
	v_lshl_add_u64 v[64:65], s[2:3], 0, v[64:65]
	v_lshlrev_b32_e32 v176, 1, v195
	v_rcp_f32_e32 v82, v66
	v_rcp_f32_e32 v83, v67
	v_lshlrev_b32_e32 v66, 13, v194
	v_lshl_add_u64 v[64:65], v[64:65], 0, v[176:177]
	v_mov_b32_e32 v67, v177
	v_lshl_add_u64 v[64:65], v[64:65], 0, v[66:67]
	s_mov_b64 s[2:3], 0x36720000
	v_mul_f32_e32 v0, v0, v73
	s_waitcnt lgkmcnt(0)
	v_rcp_f32_e32 v84, v68
	v_lshl_add_u64 v[66:67], v[64:65], 0, s[2:3]
	s_mov_b32 s2, 0x36721000
	v_cvt_pk_bf16_f32 v0, v0, v0
	v_add_co_u32_e32 v68, vcc, s2, v64
	v_rcp_f32_e32 v85, v69
	s_nop 0
	v_addc_co_u32_e32 v69, vcc, 0, v65, vcc
	global_store_short_d16_hi v[68:69], v0, off offset:-4096
	v_mul_f32_e32 v0, v48, v73
	v_bfe_u32 v48, v0, 16, 1
	v_add3_u32 v0, v0, v48, s82
	global_store_short_d16_hi v[66:67], v0, off offset:64
	v_mul_f32_e32 v0, v32, v73
	v_bfe_u32 v32, v0, 16, 1
	v_add3_u32 v0, v0, v32, s82
	global_store_short_d16_hi v[66:67], v0, off offset:128
	v_mul_f32_e32 v0, v16, v73
	v_cvt_pk_bf16_f32 v0, v0, v0
	global_store_short_d16_hi v[66:67], v0, off offset:192
	v_mul_f32_e32 v0, v1, v74
	v_cvt_pk_bf16_f32 v0, v0, v0
	global_store_short_d16_hi v[66:67], v0, off offset:2048
	v_mul_f32_e32 v0, v49, v74
	v_cvt_pk_bf16_f32 v0, v0, v0
	global_store_short_d16_hi v[66:67], v0, off offset:2112
	v_mul_f32_e32 v0, v33, v74
	v_cvt_pk_bf16_f32 v0, v0, v0
	global_store_short_d16_hi v[66:67], v0, off offset:2176
	v_mul_f32_e32 v0, v17, v74
	v_cvt_pk_bf16_f32 v0, v0, v0
	global_store_short_d16_hi v[66:67], v0, off offset:2240
	v_mul_f32_e32 v0, v2, v75
	v_cvt_pk_bf16_f32 v0, v0, v0
	global_store_short_d16_hi v[68:69], v0, off
	v_mul_f32_e32 v0, v50, v75
	v_cvt_pk_bf16_f32 v0, v0, v0
	global_store_short_d16_hi v[68:69], v0, off offset:64
	v_mul_f32_e32 v0, v34, v75
	v_cvt_pk_bf16_f32 v0, v0, v0
	global_store_short_d16_hi v[68:69], v0, off offset:128
	v_mul_f32_e32 v0, v18, v75
	v_cvt_pk_bf16_f32 v0, v0, v0
	global_store_short_d16_hi v[68:69], v0, off offset:192
	v_mul_f32_e32 v0, v3, v76
	v_cvt_pk_bf16_f32 v0, v0, v0
	global_store_short_d16_hi v[68:69], v0, off offset:2048
	v_mul_f32_e32 v0, v51, v76
	v_cvt_pk_bf16_f32 v0, v0, v0
	global_store_short_d16_hi v[68:69], v0, off offset:2112
	v_mul_f32_e32 v0, v35, v76
	v_cvt_pk_bf16_f32 v0, v0, v0
	global_store_short_d16_hi v[68:69], v0, off offset:2176
	v_mul_f32_e32 v0, v19, v76
	v_cvt_pk_bf16_f32 v0, v0, v0
	global_store_short_d16_hi v[68:69], v0, off offset:2240
	v_mul_f32_e32 v0, v4, v77
	s_mov_b32 s2, 0x36724000
	v_cvt_pk_bf16_f32 v4, v0, v0
	v_add_co_u32_e32 v0, vcc, s2, v64
	s_mov_b32 s2, 0x36725000
	s_nop 0
	v_addc_co_u32_e32 v1, vcc, 0, v65, vcc
	v_add_co_u32_e32 v2, vcc, s2, v64
	s_mov_b32 s2, 0x36728000
	s_nop 0
	v_addc_co_u32_e32 v3, vcc, 0, v65, vcc
	global_store_short_d16_hi v[2:3], v4, off offset:-4096
	v_mul_f32_e32 v4, v52, v77
	v_cvt_pk_bf16_f32 v4, v4, v4
	global_store_short_d16_hi v[0:1], v4, off offset:64
	v_mul_f32_e32 v4, v36, v77
	v_cvt_pk_bf16_f32 v4, v4, v4
	global_store_short_d16_hi v[0:1], v4, off offset:128
	v_mul_f32_e32 v4, v20, v77
	v_bfe_u32 v16, v4, 16, 1
	v_add3_u32 v4, v4, v16, s82
	global_store_short_d16_hi v[0:1], v4, off offset:192
	v_mul_f32_e32 v4, v5, v78
	v_cvt_pk_bf16_f32 v4, v4, v4
	global_store_short_d16_hi v[0:1], v4, off offset:2048
	v_mul_f32_e32 v4, v53, v78
	v_cvt_pk_bf16_f32 v4, v4, v4
	global_store_short_d16_hi v[0:1], v4, off offset:2112
	v_mul_f32_e32 v4, v37, v78
	v_cvt_pk_bf16_f32 v4, v4, v4
	global_store_short_d16_hi v[0:1], v4, off offset:2176
	v_mul_f32_e32 v4, v21, v78
	v_cvt_pk_bf16_f32 v4, v4, v4
	global_store_short_d16_hi v[0:1], v4, off offset:2240
	v_mul_f32_e32 v0, v6, v79
	v_cvt_pk_bf16_f32 v0, v0, v0
	global_store_short_d16_hi v[2:3], v0, off
	v_mul_f32_e32 v0, v54, v79
	v_cvt_pk_bf16_f32 v0, v0, v0
	global_store_short_d16_hi v[2:3], v0, off offset:64
	v_mul_f32_e32 v0, v38, v79
	v_cvt_pk_bf16_f32 v0, v0, v0
	global_store_short_d16_hi v[2:3], v0, off offset:128
	v_mul_f32_e32 v0, v22, v79
; DEVFI bfraw f2bf(float x) { unsigned u = __float_as_uint(x); u += 0x7fffu + ((u >> 16) & 1u); return (bfraw)(u >> 16); }
; DEVFI int crow(int r, int hi) { return (r & 3) + 8 * (r >> 2) + 4 * hi; }
; template <int LDQ, int LDK, int LDO>
; DEVFI void attn_dense_body(const bfraw* __restrict__ Qb, const bfraw* __restrict__ Kh, const bfraw* __restrict__ Vh,
;                            bfraw* __restrict__ Ob, int seq, char* lds, const int wv) {
;     ...
;   for (int r = 0; r < 16; ++r) { int orow = crow(r, hi);
; #pragma unroll
;     for (int d0 = 0; d0 < 4; ++d0) Ow[(long)orow * LDO + d0 * 32 + r32] = f2bf(o[d0][r] * rli[r]); }
	v_cvt_pk_bf16_f32 v0, v0, v0
	global_store_short_d16_hi v[2:3], v0, off offset:192
	v_mul_f32_e32 v0, v7, v80
	v_cvt_pk_bf16_f32 v0, v0, v0
	global_store_short_d16_hi v[2:3], v0, off offset:2048
	v_mul_f32_e32 v0, v55, v80
	v_cvt_pk_bf16_f32 v0, v0, v0
	global_store_short_d16_hi v[2:3], v0, off offset:2112
	v_mul_f32_e32 v0, v39, v80
	v_cvt_pk_bf16_f32 v0, v0, v0
	global_store_short_d16_hi v[2:3], v0, off offset:2176
	v_mul_f32_e32 v0, v23, v80
	v_cvt_pk_bf16_f32 v0, v0, v0
	global_store_short_d16_hi v[2:3], v0, off offset:2240
	v_mul_f32_e32 v0, v8, v72
	v_cvt_pk_bf16_f32 v4, v0, v0
	v_add_co_u32_e32 v0, vcc, s2, v64
	s_mov_b32 s2, 0x36729000
	s_nop 0
	v_addc_co_u32_e32 v1, vcc, 0, v65, vcc
	v_add_co_u32_e32 v2, vcc, s2, v64
	s_mov_b32 s2, 0x3672c000
	s_nop 0
	v_addc_co_u32_e32 v3, vcc, 0, v65, vcc
	global_store_short_d16_hi v[2:3], v4, off offset:-4096
	v_mul_f32_e32 v4, v56, v72
	v_cvt_pk_bf16_f32 v4, v4, v4
	global_store_short_d16_hi v[0:1], v4, off offset:64
	v_mul_f32_e32 v4, v40, v72
	v_cvt_pk_bf16_f32 v4, v4, v4
	global_store_short_d16_hi v[0:1], v4, off offset:128
	v_mul_f32_e32 v4, v24, v72
	v_cvt_pk_bf16_f32 v4, v4, v4
	global_store_short_d16_hi v[0:1], v4, off offset:192
	v_mul_f32_e32 v4, v9, v81
	v_cvt_pk_bf16_f32 v4, v4, v4
	global_store_short_d16_hi v[0:1], v4, off offset:2048
	v_mul_f32_e32 v4, v57, v81
	v_cvt_pk_bf16_f32 v4, v4, v4
	global_store_short_d16_hi v[0:1], v4, off offset:2112
	v_mul_f32_e32 v4, v41, v81
	v_cvt_pk_bf16_f32 v4, v4, v4
	global_store_short_d16_hi v[0:1], v4, off offset:2176
	v_mul_f32_e32 v4, v25, v81
	v_cvt_pk_bf16_f32 v4, v4, v4
	global_store_short_d16_hi v[0:1], v4, off offset:2240
	v_mul_f32_e32 v0, v10, v82
	v_cvt_pk_bf16_f32 v0, v0, v0
	global_store_short_d16_hi v[2:3], v0, off
	v_mul_f32_e32 v0, v58, v82
	v_cvt_pk_bf16_f32 v0, v0, v0
	global_store_short_d16_hi v[2:3], v0, off offset:64
	v_mul_f32_e32 v0, v42, v82
	v_cvt_pk_bf16_f32 v0, v0, v0
	global_store_short_d16_hi v[2:3], v0, off offset:128
	v_mul_f32_e32 v0, v26, v82
	v_cvt_pk_bf16_f32 v0, v0, v0
	global_store_short_d16_hi v[2:3], v0, off offset:192
	v_mul_f32_e32 v0, v11, v83
	v_cvt_pk_bf16_f32 v0, v0, v0
	global_store_short_d16_hi v[2:3], v0, off offset:2048
	v_mul_f32_e32 v0, v59, v83
	v_cvt_pk_bf16_f32 v0, v0, v0
	global_store_short_d16_hi v[2:3], v0, off offset:2112
	v_mul_f32_e32 v0, v43, v83
	v_cvt_pk_bf16_f32 v0, v0, v0
	global_store_short_d16_hi v[2:3], v0, off offset:2176
	v_mul_f32_e32 v0, v27, v83
	v_cvt_pk_bf16_f32 v0, v0, v0
	global_store_short_d16_hi v[2:3], v0, off offset:2240
	v_mul_f32_e32 v0, v12, v84
	v_cvt_pk_bf16_f32 v4, v0, v0
	v_add_co_u32_e32 v0, vcc, s2, v64
	s_mov_b32 s2, 0x3672d000
	s_nop 0
	v_addc_co_u32_e32 v1, vcc, 0, v65, vcc
	v_add_co_u32_e32 v2, vcc, s2, v64
	v_rcp_f32_e32 v70, v70
	s_nop 0
	v_addc_co_u32_e32 v3, vcc, 0, v65, vcc
	global_store_short_d16_hi v[2:3], v4, off offset:-4096
	v_mul_f32_e32 v4, v60, v84
	v_cvt_pk_bf16_f32 v4, v4, v4
	global_store_short_d16_hi v[0:1], v4, off offset:64
	v_mul_f32_e32 v4, v44, v84
	v_cvt_pk_bf16_f32 v4, v4, v4
	global_store_short_d16_hi v[0:1], v4, off offset:128
	v_mul_f32_e32 v4, v28, v84
	v_cvt_pk_bf16_f32 v4, v4, v4
	global_store_short_d16_hi v[0:1], v4, off offset:192
	v_mul_f32_e32 v4, v13, v85
	v_cvt_pk_bf16_f32 v4, v4, v4
	global_store_short_d16_hi v[0:1], v4, off offset:2048
	v_mul_f32_e32 v4, v61, v85
	v_cvt_pk_bf16_f32 v4, v4, v4
	global_store_short_d16_hi v[0:1], v4, off offset:2112
	v_mul_f32_e32 v4, v45, v85
	v_cvt_pk_bf16_f32 v4, v4, v4
	global_store_short_d16_hi v[0:1], v4, off offset:2176
	v_mul_f32_e32 v4, v29, v85
	v_bfe_u32 v5, v4, 16, 1
	v_add3_u32 v4, v4, v5, s82
	global_store_short_d16_hi v[0:1], v4, off offset:2240
	v_mul_f32_e32 v0, v14, v70
	v_cvt_pk_bf16_f32 v0, v0, v0
	global_store_short_d16_hi v[2:3], v0, off
	v_mul_f32_e32 v0, v62, v70
	v_cvt_pk_bf16_f32 v0, v0, v0
	global_store_short_d16_hi v[2:3], v0, off offset:64
	v_mul_f32_e32 v0, v46, v70
	v_rcp_f32_e32 v71, v71
	v_cvt_pk_bf16_f32 v0, v0, v0
	global_store_short_d16_hi v[2:3], v0, off offset:128
	v_mul_f32_e32 v0, v30, v70
	v_cvt_pk_bf16_f32 v0, v0, v0
	global_store_short_d16_hi v[2:3], v0, off offset:192
	v_mul_f32_e32 v0, v15, v71
	v_cvt_pk_bf16_f32 v0, v0, v0
	global_store_short_d16_hi v[2:3], v0, off offset:2048
	v_mul_f32_e32 v0, v63, v71
	v_cvt_pk_bf16_f32 v0, v0, v0
	global_store_short_d16_hi v[2:3], v0, off offset:2112
	v_mul_f32_e32 v0, v47, v71
	v_cvt_pk_bf16_f32 v0, v0, v0
	global_store_short_d16_hi v[2:3], v0, off offset:2176
	v_mul_f32_e32 v0, v31, v71
	v_bfe_u32 v1, v0, 16, 1
	s_add_i32 s79, s79, s28
	v_add3_u32 v0, v0, v1, s82
	s_cmpk_gt_i32 s79, 0x1ff
	global_store_short_d16_hi v[2:3], v0, off offset:2240
	s_cbranch_scc1 .LBB0_2479

; #define RQ ((bfraw*)(kargs()->ws + O_RQ))
; #define RK ((bfraw*)(kargs()->ws + O_RK))
; #define RVT ((bfraw*)(kargs()->ws + O_RVT))
; #define ST ((bfraw*)(kargs()->ws + O_ST))
; #define LGT ((float*)(kargs()->ws + O_LGT))
; __global__ void __launch_bounds__(512) mega(Params p) {
;     ...
;         for (int bi = bid; bi < 128 * 8; bi += nb) {
;           int tz = tid; asm volatile("" : "+v"(tz));
;           const int w = __builtin_amdgcn_readfirstlane(tz >> 6), lz = tz & 63, fr = tz & 15, fq = (tz >> 4) & 3;
;           const int head = bi & 7, chunk = bi >> 3;
;           const float lgf = LGT[l * 16 + head], lgb = LGT[l * 16 + 8 + head];
;           const long tok0 = (long)chunk * 128;
;           __syncthreads();
;           { const bfraw* kb = RK + tok0 * 1024 + head * 128; const bfraw* vb = RVT + ((long)(chunk * 8 + head) * 128) * 128;
;             const bfraw* sfb = ST + ((long)((chunk * 8 + head) * 2)) * 16384;
;             const int wz = w;
; #pragma unroll
;             for (int g = 0; g < 16; ++g) { const int blk = g * 8 + wz, row = (blk & 31) * 4 + (lz >> 4), c = (lz ^ row) & 15;
;               const bfraw* sp = (g < 4) ? kb + (long)row * 1024 + c * 8 : (g < 8) ? vb + row * 128 + c * 8 : sfb + (g < 12 ? 0 : 16384) + row * 128 + c * 8;
;               __builtin_amdgcn_global_load_lds((const unsigned*)sp, (unsigned*)(shm + blk * 1024), 16, 0, 0); } }
;           bf16x8 qf[4];
;           { const bfraw* qp = RQ + (tok0 + w * 16 + fr) * 1024 + head * 128 + fq * 8;
; #pragma unroll
;             for (int sx = 0; sx < 4; ++sx) qf[sx] = *(const bf16x8*)(qp + sx * 32); }
.LBB0_2481:
	v_mov_b32_e32 v116, v114
	s_and_b32 s17, s16, 7
	v_readfirstlane_b32 s2, v116
	s_ashr_i32 s18, s2, 6
	s_mov_b64 s[2:3], s[0:1]
	s_load_dwordx2 s[4:5], s[2:3], 0xe8
	s_or_b32 s12, s17, s10
	s_ashr_i32 s2, s16, 3
	s_lshl_b64 s[14:15], s[12:13], 2
	v_bfe_u32 v68, v116, 4, 2
	s_waitcnt lgkmcnt(0)
	s_add_u32 s4, s4, s14
	s_addc_u32 s5, s5, s15
	global_load_dword v117, v252, s[4:5]
	s_mov_b64 s[4:5], s[0:1]
	s_load_dwordx2 s[4:5], s[4:5], 0xe8
	v_and_b32_e32 v115, 15, v116
	v_lshrrev_b32_e32 v119, 4, v116
	v_lshlrev_b32_e32 v120, 8, v115
	v_bitop3_b32 v8, v68, v115, 4 bitop3:0x36
	s_waitcnt lgkmcnt(0)
	s_add_u32 s4, s4, s14
	s_addc_u32 s5, s5, s15
	global_load_dword v118, v252, s[4:5] offset:32
	s_mov_b64 s[4:5], s[0:1]
	s_waitcnt vmcnt(63) expcnt(7) lgkmcnt(15)
	s_barrier
	s_load_dwordx2 s[4:5], s[4:5], 0xe8
	s_ashr_i32 s3, s2, 31
	s_lshl_b64 s[14:15], s[2:3], 18
	v_bitop3_b32 v16, v68, v115, 8 bitop3:0x36
	v_bitop3_b32 v26, v68, v115, 12 bitop3:0x36
	s_waitcnt lgkmcnt(0)
	s_add_u32 s4, s4, s14
	s_addc_u32 s5, s5, s15
	s_lshl_b32 s12, s17, 8
	s_add_u32 s7, s4, s12
	s_addc_u32 s19, s5, 0
	s_mov_b64 s[4:5], s[0:1]
	s_load_dwordx2 s[14:15], s[4:5], 0xe8
	s_mov_b64 s[4:5], s[0:1]
	s_load_dwordx2 s[4:5], s[4:5], 0xe8
	s_add_u32 s20, s7, 0x13720000
	s_addc_u32 s21, s19, 0
	s_ashr_i32 s7, s6, 31
	s_lshl_b64 s[22:23], s[6:7], 15
	s_waitcnt lgkmcnt(0)
	s_add_u32 s7, s4, s22
	s_addc_u32 s19, s5, s23
	s_add_u32 s4, s7, 0x30720000
	s_addc_u32 s5, s19, 0
	s_lshl_b32 s22, s18, 2
	s_and_b32 s22, s22, 0x7c
	v_or_b32_e32 v0, s22, v68
	v_bitop3_b32 v2, s22, v116, v68 bitop3:0x36
	v_lshlrev_b32_e32 v176, 11, v0
	v_lshlrev_b32_e32 v2, 4, v2
	s_add_i32 s22, s18, 8
	v_lshl_add_u64 v[0:1], s[20:21], 0, v[176:177]
	v_and_b32_e32 v176, 0xf0, v2
	s_lshl_b32 s23, s22, 2
	v_lshl_add_u64 v[0:1], v[0:1], 0, v[176:177]
	s_lshl_b32 m0, s18, 10
	s_and_b32 s23, s23, 0x7c
	global_load_lds_dwordx4 v[0:1], off
	v_or_b32_e32 v0, s23, v68
	v_bitop3_b32 v2, s23, v116, v68 bitop3:0x36
	v_lshlrev_b32_e32 v176, 11, v0
	v_lshlrev_b32_e32 v2, 4, v2
	s_lshl_b32 m0, s22, 10
	s_add_i32 s22, s18, 16
	v_lshl_add_u64 v[0:1], s[20:21], 0, v[176:177]
	v_and_b32_e32 v176, 0xf0, v2
	s_lshl_b32 s23, s22, 2
	v_lshl_add_u64 v[0:1], v[0:1], 0, v[176:177]
	s_and_b32 s23, s23, 0x7c
	global_load_lds_dwordx4 v[0:1], off
	v_or_b32_e32 v0, s23, v68
	v_bitop3_b32 v2, s23, v116, v68 bitop3:0x36
	v_lshlrev_b32_e32 v176, 11, v0
	v_lshlrev_b32_e32 v2, 4, v2
	s_lshl_b32 m0, s22, 10
	s_add_i32 s22, s18, 24
	v_lshl_add_u64 v[0:1], s[20:21], 0, v[176:177]
	v_and_b32_e32 v176, 0xf0, v2
	s_lshl_b32 s23, s22, 2
	v_lshl_add_u64 v[0:1], v[0:1], 0, v[176:177]
	s_and_b32 s23, s23, 0x7c
	global_load_lds_dwordx4 v[0:1], off
	v_or_b32_e32 v0, s23, v68
	v_bitop3_b32 v2, s23, v116, v68 bitop3:0x36
	v_lshlrev_b32_e32 v176, 11, v0
	v_lshlrev_b32_e32 v2, 4, v2
	v_lshl_add_u64 v[0:1], s[20:21], 0, v[176:177]
	v_and_b32_e32 v176, 0xf0, v2
	v_lshl_add_u64 v[0:1], v[0:1], 0, v[176:177]
	s_lshl_b32 m0, s22, 10
	s_add_i32 s20, s18, 32
	global_load_lds_dwordx4 v[0:1], off
	v_lshl_or_b32 v0, s20, 2, v68
	s_and_b32 s21, s20, 31
	v_lshlrev_b32_e32 v2, 8, v68
	v_bitop3_b32 v0, v0, 15, v116 bitop3:0x48
	v_lshl_or_b32 v1, s21, 10, v2
	v_lshl_or_b32 v176, v0, 4, v1
	v_lshl_add_u64 v[0:1], s[14:15], 0, v[176:177]
	v_lshl_add_u64 v[0:1], v[0:1], 0, s[8:9]
	s_lshl_b32 m0, s20, 10
	s_add_i32 s20, s18, 40
	global_load_lds_dwordx4 v[0:1], off
	v_lshl_or_b32 v0, s20, 2, v68
	s_and_b32 s21, s20, 31
	v_bitop3_b32 v0, v0, 15, v116 bitop3:0x48
	v_lshl_or_b32 v1, s21, 10, v2
	v_lshl_or_b32 v176, v0, 4, v1
	v_lshl_add_u64 v[0:1], s[14:15], 0, v[176:177]
	v_lshl_add_u64 v[0:1], v[0:1], 0, s[8:9]
	s_lshl_b32 m0, s20, 10
	s_add_i32 s20, s18, 48
	global_load_lds_dwordx4 v[0:1], off
	v_lshl_or_b32 v0, s20, 2, v68
	s_and_b32 s21, s20, 31
	v_bitop3_b32 v0, v0, 15, v116 bitop3:0x48
	v_lshl_or_b32 v1, s21, 10, v2
	v_lshl_or_b32 v176, v0, 4, v1
	v_lshl_add_u64 v[0:1], s[14:15], 0, v[176:177]
	v_lshl_add_u64 v[0:1], v[0:1], 0, s[8:9]
	s_lshl_b32 m0, s20, 10
	s_add_i32 s20, s18, 56
	global_load_lds_dwordx4 v[0:1], off
	v_lshl_or_b32 v0, s20, 2, v68
	s_and_b32 s21, s20, 31
	v_bitop3_b32 v0, v0, 15, v116 bitop3:0x48
	v_lshl_or_b32 v1, s21, 10, v2
	v_lshl_or_b32 v176, v0, 4, v1
	v_lshl_add_u64 v[0:1], s[14:15], 0, v[176:177]
	s_add_i32 s14, s18, 64
	s_lshl_b32 s15, s14, 2
	v_lshl_add_u64 v[0:1], v[0:1], 0, s[8:9]
	s_lshl_b32 m0, s20, 10
	s_and_b32 s15, s15, 0x7c
	global_load_lds_dwordx4 v[0:1], off
	v_or_b32_e32 v0, s15, v68
	v_bitop3_b32 v2, s15, v116, v68 bitop3:0x36
	v_lshlrev_b32_e32 v176, 8, v0
	v_lshlrev_b32_e32 v2, 4, v2
	s_lshl_b32 m0, s14, 10
	s_add_i32 s14, s18, 0x48
	v_lshl_add_u64 v[0:1], s[4:5], 0, v[176:177]
	v_and_b32_e32 v176, 0xf0, v2
	s_lshl_b32 s15, s14, 2
	v_lshl_add_u64 v[0:1], v[0:1], 0, v[176:177]
	s_and_b32 s15, s15, 0x7c
	global_load_lds_dwordx4 v[0:1], off
	v_or_b32_e32 v0, s15, v68
	v_bitop3_b32 v2, s15, v116, v68 bitop3:0x36
	v_lshlrev_b32_e32 v176, 8, v0
	v_lshlrev_b32_e32 v2, 4, v2
	s_lshl_b32 m0, s14, 10
	s_add_i32 s14, s18, 0x50
	v_lshl_add_u64 v[0:1], s[4:5], 0, v[176:177]
	v_and_b32_e32 v176, 0xf0, v2
	s_lshl_b32 s15, s14, 2
	v_lshl_add_u64 v[0:1], v[0:1], 0, v[176:177]
	s_and_b32 s15, s15, 0x7c
	global_load_lds_dwordx4 v[0:1], off
	v_or_b32_e32 v0, s15, v68
	v_bitop3_b32 v2, s15, v116, v68 bitop3:0x36
	v_lshlrev_b32_e32 v176, 8, v0
	v_lshlrev_b32_e32 v2, 4, v2
	s_lshl_b32 m0, s14, 10
	s_add_i32 s14, s18, 0x58
	v_lshl_add_u64 v[0:1], s[4:5], 0, v[176:177]
	v_and_b32_e32 v176, 0xf0, v2
	s_lshl_b32 s15, s14, 2
	v_lshl_add_u64 v[0:1], v[0:1], 0, v[176:177]
	s_and_b32 s15, s15, 0x7c
	global_load_lds_dwordx4 v[0:1], off
; #define SBAR() __builtin_amdgcn_sched_barrier(0)
; #define WAIT_V0() asm volatile("s_waitcnt vmcnt(0)" ::: "memory")
; #define RQ ((bfraw*)(kargs()->ws + O_RQ))
; #define RK ((bfraw*)(kargs()->ws + O_RK))
; #define RVT ((bfraw*)(kargs()->ws + O_RVT))
; #define ST ((bfraw*)(kargs()->ws + O_ST))
; __global__ void __launch_bounds__(512) mega(Params p) {
;     ...
;           { const bfraw* kb = RK + tok0 * 1024 + head * 128; const bfraw* vb = RVT + ((long)(chunk * 8 + head) * 128) * 128;
;             const bfraw* sfb = ST + ((long)((chunk * 8 + head) * 2)) * 16384;
;             const int wz = w;
; #pragma unroll
;             for (int g = 0; g < 16; ++g) { const int blk = g * 8 + wz, row = (blk & 31) * 4 + (lz >> 4), c = (lz ^ row) & 15;
;               const bfraw* sp = (g < 4) ? kb + (long)row * 1024 + c * 8 : (g < 8) ? vb + row * 128 + c * 8 : sfb + (g < 12 ? 0 : 16384) + row * 128 + c * 8;
;               __builtin_amdgcn_global_load_lds((const unsigned*)sp, (unsigned*)(shm + blk * 1024), 16, 0, 0); } }
;           bf16x8 qf[4];
;           { const bfraw* qp = RQ + (tok0 + w * 16 + fr) * 1024 + head * 128 + fq * 8;
; #pragma unroll
;             for (int sx = 0; sx < 4; ++sx) qf[sx] = *(const bf16x8*)(qp + sx * 32); }
;           WAIT_V0(); __syncthreads();
;           f32x4 o[8];
;           { f32x4 af[8] = {}, ab[8] = {};
; #pragma unroll
;             for (int ne = 0; ne < 8; ++ne) { bf16x8 Bf[4], Bb[4];
; #pragma unroll
;               for (int sx = 0; sx < 4; ++sx) { Bf[sx] = RLD16(2, ne * 16 + fr, sx * 4 + fq); Bb[sx] = RLD16(3, ne * 16 + fr, sx * 4 + fq); }
;               SBAR();
; #pragma unroll
;               for (int sx = 0; sx < 4; ++sx) { af[ne] = __builtin_amdgcn_mfma_f32_16x16x32_bf16(qf[sx], Bf[sx], af[ne], 0, 0, 0);
;                 ab[ne] = __builtin_amdgcn_mfma_f32_16x16x32_bf16(qf[sx], Bb[sx], ab[ne], 0, 0, 0); }
;               SBAR(); }
	v_or_b32_e32 v0, s15, v68
	v_bitop3_b32 v2, s15, v116, v68 bitop3:0x36
	v_lshlrev_b32_e32 v176, 8, v0
	v_lshlrev_b32_e32 v2, 4, v2
	s_lshl_b32 m0, s14, 10
	s_add_i32 s14, s18, 0x60
	v_lshl_add_u64 v[0:1], s[4:5], 0, v[176:177]
	v_and_b32_e32 v176, 0xf0, v2
	s_lshl_b32 s4, s14, 2
	v_lshl_add_u64 v[0:1], v[0:1], 0, v[176:177]
	s_and_b32 s4, s4, 0x7c
	global_load_lds_dwordx4 v[0:1], off
	v_or_b32_e32 v0, s4, v68
	v_bitop3_b32 v2, s4, v116, v68 bitop3:0x36
	s_add_u32 s4, s7, 0x30728000
	s_addc_u32 s5, s19, 0
	v_lshlrev_b32_e32 v176, 8, v0
	v_lshlrev_b32_e32 v2, 4, v2
	s_add_i32 s7, s18, 0x68
	v_lshl_add_u64 v[0:1], s[4:5], 0, v[176:177]
	v_and_b32_e32 v176, 0xf0, v2
	s_lshl_b32 m0, s14, 10
	s_lshl_b32 s14, s7, 2
	v_lshl_add_u64 v[0:1], v[0:1], 0, v[176:177]
	s_and_b32 s14, s14, 0x7c
	global_load_lds_dwordx4 v[0:1], off
	v_or_b32_e32 v0, s14, v68
	v_bitop3_b32 v2, s14, v116, v68 bitop3:0x36
	v_lshlrev_b32_e32 v176, 8, v0
	v_lshlrev_b32_e32 v2, 4, v2
	s_lshl_b32 m0, s7, 10
	s_add_i32 s7, s18, 0x70
	v_lshl_add_u64 v[0:1], s[4:5], 0, v[176:177]
	v_and_b32_e32 v176, 0xf0, v2
	s_lshl_b32 s14, s7, 2
	v_lshl_add_u64 v[0:1], v[0:1], 0, v[176:177]
	s_and_b32 s14, s14, 0x7c
	global_load_lds_dwordx4 v[0:1], off
	v_or_b32_e32 v0, s14, v68
	v_bitop3_b32 v2, s14, v116, v68 bitop3:0x36
	v_lshlrev_b32_e32 v176, 8, v0
	v_lshlrev_b32_e32 v2, 4, v2
	s_lshl_b32 m0, s7, 10
	s_add_i32 s7, s18, 0x78
	v_lshl_add_u64 v[0:1], s[4:5], 0, v[176:177]
	v_and_b32_e32 v176, 0xf0, v2
	s_lshl_b32 s14, s7, 2
	v_lshl_add_u64 v[0:1], v[0:1], 0, v[176:177]
	s_and_b32 s14, s14, 0x7c
	global_load_lds_dwordx4 v[0:1], off
	v_or_b32_e32 v0, s14, v68
	v_bitop3_b32 v2, s14, v116, v68 bitop3:0x36
	v_lshlrev_b32_e32 v176, 8, v0
	v_lshlrev_b32_e32 v2, 4, v2
	v_lshl_add_u64 v[0:1], s[4:5], 0, v[176:177]
	v_and_b32_e32 v176, 0xf0, v2
	v_lshl_add_u64 v[0:1], v[0:1], 0, v[176:177]
	s_lshl_b32 m0, s7, 10
	s_lshl_b64 s[4:5], s[2:3], 7
	s_mov_b64 s[2:3], s[0:1]
	global_load_lds_dwordx4 v[0:1], off
	s_load_dwordx2 s[14:15], s[2:3], 0xe8
	s_lshl_b32 s2, s18, 4
	s_ashr_i32 s3, s2, 31
	s_add_u32 s7, s4, s2
	s_addc_u32 s3, s5, s3
	v_or_b32_e32 v104, s7, v115
	v_mov_b32_e32 v105, s3
	v_lshlrev_b64 v[0:1], 11, v[104:105]
	s_waitcnt lgkmcnt(0)
	v_lshl_add_u64 v[0:1], s[14:15], 0, v[0:1]
	v_lshl_add_u64 v[0:1], v[0:1], 0, s[12:13]
	v_lshlrev_b32_e32 v176, 4, v68
	v_lshl_add_u64 v[0:1], v[0:1], 0, v[176:177]
	v_lshl_add_u64 v[2:3], v[0:1], 0, s[24:25]
	v_add_co_u32_e32 v0, vcc, s84, v0
	v_or_b32_e32 v24, 0x10000, v120
	s_nop 0
	v_addc_co_u32_e32 v1, vcc, 0, v1, vcc
	global_load_dwordx4 v[64:67], v[2:3], off offset:64
	global_load_dwordx4 v[84:87], v[2:3], off offset:128
	global_load_dwordx4 v[92:95], v[0:1], off
	global_load_dwordx4 v[88:91], v[2:3], off offset:192
	v_bitop3_b32 v0, v119, v115, 3 bitop3:0x6c
	v_or_b32_e32 v25, 0x18000, v120
	v_lshlrev_b32_e32 v69, 4, v0
	v_lshlrev_b32_e32 v82, 4, v8
	v_lshlrev_b32_e32 v83, 4, v16
	v_lshlrev_b32_e32 v121, 4, v26
	v_or_b32_e32 v0, v24, v69
	v_or_b32_e32 v4, v25, v69
	v_or_b32_e32 v8, v24, v82
	v_or_b32_e32 v12, v25, v82
	v_or_b32_e32 v16, v24, v83
	v_or_b32_e32 v20, v25, v83
	v_or_b32_e32 v24, v24, v121
	s_waitcnt vmcnt(0)
	s_waitcnt vmcnt(0)
	s_barrier
	ds_read_b128 v[0:3], v0
	ds_read_b128 v[4:7], v4
	ds_read_b128 v[8:11], v8
	ds_read_b128 v[12:15], v12
	ds_read_b128 v[16:19], v16
	ds_read_b128 v[20:23], v20
	v_or_b32_e32 v28, v25, v121
	ds_read_b128 v[24:27], v24
	ds_read_b128 v[32:35], v28
	s_waitcnt lgkmcnt(7)
	v_mfma_f32_16x16x32_bf16 v[0:3], v[92:95], v[0:3], 0
	s_waitcnt lgkmcnt(6)
	v_mfma_f32_16x16x32_bf16 v[4:7], v[92:95], v[4:7], 0
	s_waitcnt lgkmcnt(5)
	v_mfma_f32_16x16x32_bf16 v[0:3], v[64:67], v[8:11], v[0:3]
	s_waitcnt lgkmcnt(4)
	v_mfma_f32_16x16x32_bf16 v[4:7], v[64:67], v[12:15], v[4:7]
	s_waitcnt lgkmcnt(3)
	v_mfma_f32_16x16x32_bf16 v[0:3], v[84:87], v[16:19], v[0:3]
	s_waitcnt lgkmcnt(2)
	v_mfma_f32_16x16x32_bf16 v[4:7], v[84:87], v[20:23], v[4:7]
	s_waitcnt lgkmcnt(1)
	v_mfma_f32_16x16x32_bf16 v[28:31], v[88:91], v[24:27], v[0:3]
	s_waitcnt lgkmcnt(0)
	v_mfma_f32_16x16x32_bf16 v[60:63], v[88:91], v[32:35], v[4:7]
	v_or_b32_e32 v24, 0x1000, v120
	v_or_b32_e32 v100, 0x10000, v69
	v_or_b32_e32 v101, 0x18000, v69
	v_or_b32_e32 v102, 0x10000, v82
	v_or_b32_e32 v103, 0x18000, v82
	v_or_b32_e32 v104, 0x10000, v83
	v_or_b32_e32 v106, 0x18000, v83
	v_or_b32_e32 v107, 0x10000, v121
	v_or_b32_e32 v108, 0x18000, v121
	v_or_b32_e32 v0, v100, v24
	v_or_b32_e32 v4, v101, v24
	v_or_b32_e32 v8, v102, v24
	v_or_b32_e32 v12, v103, v24
	v_or_b32_e32 v16, v104, v24
	v_or_b32_e32 v20, v106, v24
	v_or_b32_e32 v25, v107, v24
	v_or_b32_e32 v32, v108, v24
	ds_read_b128 v[0:3], v0
	ds_read_b128 v[4:7], v4
	ds_read_b128 v[8:11], v8
	ds_read_b128 v[12:15], v12
	ds_read_b128 v[16:19], v16
	ds_read_b128 v[20:23], v20
	ds_read_b128 v[24:27], v25
	ds_read_b128 v[32:35], v32
	s_waitcnt lgkmcnt(7)
	v_mfma_f32_16x16x32_bf16 v[0:3], v[92:95], v[0:3], 0
	s_waitcnt lgkmcnt(6)
	v_mfma_f32_16x16x32_bf16 v[4:7], v[92:95], v[4:7], 0
	s_waitcnt lgkmcnt(5)
	v_mfma_f32_16x16x32_bf16 v[0:3], v[64:67], v[8:11], v[0:3]
	s_waitcnt lgkmcnt(4)
	v_mfma_f32_16x16x32_bf16 v[4:7], v[64:67], v[12:15], v[4:7]
	s_waitcnt lgkmcnt(3)
	v_mfma_f32_16x16x32_bf16 v[0:3], v[84:87], v[16:19], v[0:3]
	s_waitcnt lgkmcnt(2)
	v_mfma_f32_16x16x32_bf16 v[4:7], v[84:87], v[20:23], v[4:7]
	s_waitcnt lgkmcnt(1)
	v_mfma_f32_16x16x32_bf16 v[0:3], v[88:91], v[24:27], v[0:3]
	s_waitcnt lgkmcnt(0)
; #define SBAR() __builtin_amdgcn_sched_barrier(0)
; __global__ void __launch_bounds__(512) mega(Params p) {
;     ...
;           { f32x4 af[8] = {}, ab[8] = {};
; #pragma unroll
;             for (int ne = 0; ne < 8; ++ne) { bf16x8 Bf[4], Bb[4];
; #pragma unroll
;               for (int sx = 0; sx < 4; ++sx) { Bf[sx] = RLD16(2, ne * 16 + fr, sx * 4 + fq); Bb[sx] = RLD16(3, ne * 16 + fr, sx * 4 + fq); }
;               SBAR();
; #pragma unroll
;               for (int sx = 0; sx < 4; ++sx) { af[ne] = __builtin_amdgcn_mfma_f32_16x16x32_bf16(qf[sx], Bf[sx], af[ne], 0, 0, 0);
;                 ab[ne] = __builtin_amdgcn_mfma_f32_16x16x32_bf16(qf[sx], Bb[sx], ab[ne], 0, 0, 0); }
;               SBAR(); }
	v_mfma_f32_16x16x32_bf16 v[56:59], v[88:91], v[32:35], v[4:7]
	v_or_b32_e32 v32, 0x2000, v120
	s_nop 2
	v_or_b32_e32 v4, v100, v32
	v_or_b32_e32 v8, v101, v32
	v_or_b32_e32 v12, v102, v32
	v_or_b32_e32 v16, v103, v32
	v_or_b32_e32 v20, v104, v32
	v_or_b32_e32 v24, v106, v32
	v_or_b32_e32 v33, v107, v32
	v_or_b32_e32 v36, v108, v32
	ds_read_b128 v[4:7], v4
	ds_read_b128 v[8:11], v8
	ds_read_b128 v[12:15], v12
	ds_read_b128 v[16:19], v16
	ds_read_b128 v[20:23], v20
	ds_read_b128 v[24:27], v24
	ds_read_b128 v[32:35], v33
	ds_read_b128 v[36:39], v36
	s_waitcnt lgkmcnt(7)
	v_mfma_f32_16x16x32_bf16 v[4:7], v[92:95], v[4:7], 0
	s_waitcnt lgkmcnt(6)
	v_mfma_f32_16x16x32_bf16 v[8:11], v[92:95], v[8:11], 0
	s_waitcnt lgkmcnt(5)
	v_mfma_f32_16x16x32_bf16 v[4:7], v[64:67], v[12:15], v[4:7]
	s_waitcnt lgkmcnt(4)
	v_mfma_f32_16x16x32_bf16 v[8:11], v[64:67], v[16:19], v[8:11]
	s_waitcnt lgkmcnt(3)
	v_mfma_f32_16x16x32_bf16 v[4:7], v[84:87], v[20:23], v[4:7]
	s_waitcnt lgkmcnt(2)
	v_mfma_f32_16x16x32_bf16 v[8:11], v[84:87], v[24:27], v[8:11]
	s_waitcnt lgkmcnt(1)
	v_mfma_f32_16x16x32_bf16 v[4:7], v[88:91], v[32:35], v[4:7]
	s_waitcnt lgkmcnt(0)
	v_mfma_f32_16x16x32_bf16 v[52:55], v[88:91], v[36:39], v[8:11]
	v_or_b32_e32 v36, 0x3000, v120
	s_nop 2
	v_or_b32_e32 v8, v100, v36
	v_or_b32_e32 v12, v101, v36
	v_or_b32_e32 v16, v102, v36
	v_or_b32_e32 v20, v103, v36
	v_or_b32_e32 v24, v104, v36
	v_or_b32_e32 v32, v106, v36
	v_or_b32_e32 v37, v107, v36
	v_or_b32_e32 v40, v108, v36
	ds_read_b128 v[8:11], v8
	ds_read_b128 v[12:15], v12
	ds_read_b128 v[16:19], v16
	ds_read_b128 v[20:23], v20
	ds_read_b128 v[24:27], v24
	ds_read_b128 v[32:35], v32
	ds_read_b128 v[36:39], v37
	ds_read_b128 v[40:43], v40
	s_waitcnt lgkmcnt(7)
	v_mfma_f32_16x16x32_bf16 v[8:11], v[92:95], v[8:11], 0
	s_waitcnt lgkmcnt(6)
	v_mfma_f32_16x16x32_bf16 v[12:15], v[92:95], v[12:15], 0
	s_waitcnt lgkmcnt(5)
	v_mfma_f32_16x16x32_bf16 v[8:11], v[64:67], v[16:19], v[8:11]
	s_waitcnt lgkmcnt(4)
	v_mfma_f32_16x16x32_bf16 v[12:15], v[64:67], v[20:23], v[12:15]
	s_waitcnt lgkmcnt(3)
	v_mfma_f32_16x16x32_bf16 v[8:11], v[84:87], v[24:27], v[8:11]
	s_waitcnt lgkmcnt(2)
	v_mfma_f32_16x16x32_bf16 v[12:15], v[84:87], v[32:35], v[12:15]
	s_waitcnt lgkmcnt(1)
	v_mfma_f32_16x16x32_bf16 v[8:11], v[88:91], v[36:39], v[8:11]
	s_waitcnt lgkmcnt(0)
	v_mfma_f32_16x16x32_bf16 v[48:51], v[88:91], v[40:43], v[12:15]
	v_or_b32_e32 v40, 0x4000, v120
	s_nop 2
	v_or_b32_e32 v12, v100, v40
	v_or_b32_e32 v16, v101, v40
	v_or_b32_e32 v20, v102, v40
	v_or_b32_e32 v24, v103, v40
	v_or_b32_e32 v32, v104, v40
	v_or_b32_e32 v36, v106, v40
	v_or_b32_e32 v41, v107, v40
	v_or_b32_e32 v44, v108, v40
	ds_read_b128 v[12:15], v12
	ds_read_b128 v[16:19], v16
	ds_read_b128 v[20:23], v20
	ds_read_b128 v[24:27], v24
	ds_read_b128 v[32:35], v32
	ds_read_b128 v[36:39], v36
	ds_read_b128 v[40:43], v41
	ds_read_b128 v[44:47], v44
	s_waitcnt lgkmcnt(7)
	v_mfma_f32_16x16x32_bf16 v[12:15], v[92:95], v[12:15], 0
	s_waitcnt lgkmcnt(6)
	v_mfma_f32_16x16x32_bf16 v[16:19], v[92:95], v[16:19], 0
	s_waitcnt lgkmcnt(5)
	v_mfma_f32_16x16x32_bf16 v[12:15], v[64:67], v[20:23], v[12:15]
	s_waitcnt lgkmcnt(4)
	v_mfma_f32_16x16x32_bf16 v[16:19], v[64:67], v[24:27], v[16:19]
	s_waitcnt lgkmcnt(3)
	v_mfma_f32_16x16x32_bf16 v[12:15], v[84:87], v[32:35], v[12:15]
	s_waitcnt lgkmcnt(2)
	v_mfma_f32_16x16x32_bf16 v[16:19], v[84:87], v[36:39], v[16:19]
	s_waitcnt lgkmcnt(1)
	v_mfma_f32_16x16x32_bf16 v[12:15], v[88:91], v[40:43], v[12:15]
	s_waitcnt lgkmcnt(0)
	v_mfma_f32_16x16x32_bf16 v[44:47], v[88:91], v[44:47], v[16:19]
	v_or_b32_e32 v70, 0x5000, v120
	s_nop 2
	v_or_b32_e32 v16, v100, v70
	v_or_b32_e32 v20, v101, v70
	v_or_b32_e32 v24, v102, v70
	v_or_b32_e32 v32, v103, v70
	v_or_b32_e32 v36, v104, v70
	v_or_b32_e32 v40, v106, v70
	v_or_b32_e32 v71, v107, v70
	v_or_b32_e32 v74, v108, v70
	ds_read_b128 v[16:19], v16
	ds_read_b128 v[20:23], v20
	ds_read_b128 v[24:27], v24
	ds_read_b128 v[32:35], v32
	ds_read_b128 v[36:39], v36
	ds_read_b128 v[40:43], v40
	ds_read_b128 v[70:73], v71
	ds_read_b128 v[74:77], v74
	s_waitcnt lgkmcnt(7)
	v_mfma_f32_16x16x32_bf16 v[16:19], v[92:95], v[16:19], 0
	s_waitcnt lgkmcnt(6)
	v_mfma_f32_16x16x32_bf16 v[20:23], v[92:95], v[20:23], 0
	s_waitcnt lgkmcnt(5)
	v_mfma_f32_16x16x32_bf16 v[16:19], v[64:67], v[24:27], v[16:19]
	s_waitcnt lgkmcnt(4)
	v_mfma_f32_16x16x32_bf16 v[20:23], v[64:67], v[32:35], v[20:23]
	s_waitcnt lgkmcnt(3)
	v_mfma_f32_16x16x32_bf16 v[16:19], v[84:87], v[36:39], v[16:19]
	s_waitcnt lgkmcnt(2)
	v_mfma_f32_16x16x32_bf16 v[20:23], v[84:87], v[40:43], v[20:23]
	s_waitcnt lgkmcnt(1)
	v_mfma_f32_16x16x32_bf16 v[16:19], v[88:91], v[70:73], v[16:19]
	s_waitcnt lgkmcnt(0)
	v_mfma_f32_16x16x32_bf16 v[40:43], v[88:91], v[74:77], v[20:23]
	v_or_b32_e32 v78, 0x6000, v120
	s_nop 2
	v_or_b32_e32 v20, v100, v78
	v_or_b32_e32 v24, v101, v78
	v_or_b32_e32 v32, v102, v78
	v_or_b32_e32 v36, v103, v78
	v_or_b32_e32 v70, v104, v78
	v_or_b32_e32 v74, v106, v78
	v_or_b32_e32 v79, v107, v78
	v_or_b32_e32 v96, v108, v78
	ds_read_b128 v[20:23], v20
	ds_read_b128 v[24:27], v24
	ds_read_b128 v[32:35], v32
	ds_read_b128 v[36:39], v36
	ds_read_b128 v[70:73], v70
	ds_read_b128 v[74:77], v74
	ds_read_b128 v[78:81], v79
	ds_read_b128 v[96:99], v96
	s_waitcnt lgkmcnt(7)
	v_mfma_f32_16x16x32_bf16 v[20:23], v[92:95], v[20:23], 0
	s_waitcnt lgkmcnt(6)
	v_mfma_f32_16x16x32_bf16 v[24:27], v[92:95], v[24:27], 0
	s_waitcnt lgkmcnt(5)
	v_mfma_f32_16x16x32_bf16 v[20:23], v[64:67], v[32:35], v[20:23]
	s_waitcnt lgkmcnt(4)
	v_mfma_f32_16x16x32_bf16 v[24:27], v[64:67], v[36:39], v[24:27]
	s_waitcnt lgkmcnt(3)
	v_mfma_f32_16x16x32_bf16 v[20:23], v[84:87], v[70:73], v[20:23]
	s_waitcnt lgkmcnt(2)
; #define SBAR() __builtin_amdgcn_sched_barrier(0)
; __global__ void __launch_bounds__(512) mega(Params p) {
;     ...
;           { f32x4 af[8] = {}, ab[8] = {};
; #pragma unroll
;             for (int ne = 0; ne < 8; ++ne) { bf16x8 Bf[4], Bb[4];
; #pragma unroll
;               for (int sx = 0; sx < 4; ++sx) { Bf[sx] = RLD16(2, ne * 16 + fr, sx * 4 + fq); Bb[sx] = RLD16(3, ne * 16 + fr, sx * 4 + fq); }
;               SBAR();
; #pragma unroll
;               for (int sx = 0; sx < 4; ++sx) { af[ne] = __builtin_amdgcn_mfma_f32_16x16x32_bf16(qf[sx], Bf[sx], af[ne], 0, 0, 0);
;                 ab[ne] = __builtin_amdgcn_mfma_f32_16x16x32_bf16(qf[sx], Bb[sx], ab[ne], 0, 0, 0); }
;               SBAR(); }
; #pragma unroll
;             for (int j = 0; j < 4; ++j) { const int c = w * 16 + fq * 4 + j; const float xf = __expf(lgf * (float)(c + 1)), xb = __expf(lgb * (float)(128 - c));
; #pragma unroll
;               for (int ne = 0; ne < 8; ++ne) o[ne][j] = xf * af[ne][j] + xb * ab[ne][j]; } }
;           bf16x8 pf[4];
;           { f32x4 sc[8] = {};
; #pragma unroll
;             for (int n2 = 0; n2 < 4; ++n2) { bf16x8 A[2][4];
; #pragma unroll
;               for (int q2 = 0; q2 < 2; ++q2)
; #pragma unroll
;                 for (int sx = 0; sx < 4; ++sx) A[q2][sx] = RLD16(0, (n2 * 2 + q2) * 16 + fr, sx * 4 + fq);
;               SBAR();
; #pragma unroll
;               for (int q2 = 0; q2 < 2; ++q2)
; #pragma unroll
;                 for (int sx = 0; sx < 4; ++sx) sc[n2 * 2 + q2] = __builtin_amdgcn_mfma_f32_16x16x32_bf16(A[q2][sx], qf[sx], sc[n2 * 2 + q2], 0, 0, 0);
;               SBAR(); }
	v_mfma_f32_16x16x32_bf16 v[24:27], v[84:87], v[74:77], v[24:27]
	s_waitcnt lgkmcnt(1)
	v_mfma_f32_16x16x32_bf16 v[20:23], v[88:91], v[78:81], v[20:23]
	s_waitcnt lgkmcnt(0)
	v_mfma_f32_16x16x32_bf16 v[36:39], v[88:91], v[96:99], v[24:27]
	v_or_b32_e32 v109, 0x7000, v120
	s_nop 2
	v_or_b32_e32 v24, v100, v109
	v_or_b32_e32 v32, v101, v109
	v_or_b32_e32 v70, v102, v109
	v_or_b32_e32 v74, v103, v109
	v_or_b32_e32 v78, v104, v109
	v_or_b32_e32 v96, v106, v109
	v_or_b32_e32 v100, v107, v109
	ds_read_b128 v[24:27], v24
	ds_read_b128 v[32:35], v32
	ds_read_b128 v[70:73], v70
	ds_read_b128 v[74:77], v74
	ds_read_b128 v[78:81], v78
	ds_read_b128 v[96:99], v96
	v_or_b32_e32 v104, v108, v109
	ds_read_b128 v[100:103], v100
	ds_read_b128 v[106:109], v104
	s_waitcnt lgkmcnt(7)
	v_mfma_f32_16x16x32_bf16 v[24:27], v[92:95], v[24:27], 0
	s_waitcnt lgkmcnt(6)
	v_mfma_f32_16x16x32_bf16 v[32:35], v[92:95], v[32:35], 0
	s_waitcnt lgkmcnt(5)
	v_mfma_f32_16x16x32_bf16 v[24:27], v[64:67], v[70:73], v[24:27]
	s_waitcnt lgkmcnt(4)
	v_mfma_f32_16x16x32_bf16 v[32:35], v[64:67], v[74:77], v[32:35]
	s_waitcnt lgkmcnt(3)
	v_mfma_f32_16x16x32_bf16 v[24:27], v[84:87], v[78:81], v[24:27]
	s_waitcnt lgkmcnt(2)
	v_mfma_f32_16x16x32_bf16 v[32:35], v[84:87], v[96:99], v[32:35]
	s_waitcnt lgkmcnt(1)
	v_mfma_f32_16x16x32_bf16 v[24:27], v[88:91], v[100:103], v[24:27]
	s_waitcnt lgkmcnt(0)
	v_mfma_f32_16x16x32_bf16 v[32:35], v[88:91], v[106:109], v[32:35]
	v_lshlrev_b32_e32 v104, 2, v68
	v_or_b32_e32 v68, s2, v104
	v_or_b32_e32 v70, 1, v68
	v_cvt_f32_i32_e32 v71, v70
	v_sub_u32_e32 v70, 0x80, v70
	v_cvt_f32_i32_e32 v70, v70
	v_or_b32_e32 v146, v120, v69
	v_mul_f32_e32 v71, v117, v71
	v_mul_f32_e32 v71, 0x3fb8aa3b, v71
	v_exp_f32_e32 v106, v71
	v_sub_u32_e32 v71, 0x80, v68
	v_cvt_f32_i32_e32 v71, v71
	v_mul_f32_e32 v70, v118, v70
	v_mul_f32_e32 v70, 0x3fb8aa3b, v70
	v_exp_f32_e32 v109, v70
	v_mul_f32_e32 v71, v118, v71
	v_mul_f32_e32 v71, 0x3fb8aa3b, v71
	v_exp_f32_e32 v108, v71
	v_or_b32_e32 v71, 2, v68
	v_or_b32_e32 v70, 3, v68
	v_add_u32_e32 v68, 4, v68
	v_cvt_f32_i32_e32 v68, v68
	v_cvt_f32_i32_e32 v72, v71
	v_sub_u32_e32 v71, 0x80, v71
	v_cvt_f32_i32_e32 v71, v71
	v_mul_f32_e32 v68, v117, v68
	v_mul_f32_e32 v72, v117, v72
	v_mul_f32_e32 v68, 0x3fb8aa3b, v68
	v_mul_f32_e32 v72, 0x3fb8aa3b, v72
	v_exp_f32_e32 v111, v68
	v_sub_u32_e32 v68, 0x80, v70
	v_exp_f32_e32 v107, v72
	v_cvt_f32_i32_e32 v72, v70
	v_cvt_f32_i32_e32 v68, v68
	v_mul_f32_e32 v71, v118, v71
	v_mul_f32_e32 v71, 0x3fb8aa3b, v71
	v_mul_f32_e32 v72, v117, v72
	v_mul_f32_e32 v68, v118, v68
	v_mul_f32_e32 v72, 0x3fb8aa3b, v72
	v_mul_f32_e32 v68, 0x3fb8aa3b, v68
	v_or_b32_e32 v147, v120, v82
	v_or_b32_e32 v148, v120, v83
	v_or_b32_e32 v121, v120, v121
	v_exp_f32_e32 v110, v72
	v_exp_f32_e32 v112, v71
	v_exp_f32_e32 v113, v68
	ds_read_b128 v[68:71], v146
	ds_read_b128 v[72:75], v147
	ds_read_b128 v[76:79], v148
	ds_read_b128 v[80:83], v121
	ds_read_b128 v[96:99], v146 offset:4096
	ds_read_b128 v[100:103], v147 offset:4096
	ds_read_b128 v[122:125], v148 offset:4096
	ds_read_b128 v[126:129], v121 offset:4096
	s_waitcnt lgkmcnt(7)
	v_mfma_f32_16x16x32_bf16 v[68:71], v[68:71], v[92:95], 0
	s_waitcnt lgkmcnt(6)
	v_mfma_f32_16x16x32_bf16 v[68:71], v[72:75], v[64:67], v[68:71]
	s_waitcnt lgkmcnt(5)
	v_mfma_f32_16x16x32_bf16 v[68:71], v[76:79], v[84:87], v[68:71]
	s_waitcnt lgkmcnt(4)
	v_mfma_f32_16x16x32_bf16 v[130:133], v[80:83], v[88:91], v[68:71]
	s_waitcnt lgkmcnt(3)
	v_mfma_f32_16x16x32_bf16 v[68:71], v[96:99], v[92:95], 0
	s_waitcnt lgkmcnt(2)
	v_mfma_f32_16x16x32_bf16 v[68:71], v[100:103], v[64:67], v[68:71]
	s_waitcnt lgkmcnt(1)
	v_mfma_f32_16x16x32_bf16 v[68:71], v[122:125], v[84:87], v[68:71]
	s_waitcnt lgkmcnt(0)
	v_mfma_f32_16x16x32_bf16 v[100:103], v[126:129], v[88:91], v[68:71]
	s_nop 5
	ds_read_b128 v[68:71], v146 offset:8192
	ds_read_b128 v[72:75], v146 offset:12288
	ds_read_b128 v[76:79], v147 offset:8192
	ds_read_b128 v[80:83], v147 offset:12288
	ds_read_b128 v[96:99], v148 offset:8192
	ds_read_b128 v[122:125], v148 offset:12288
	ds_read_b128 v[126:129], v121 offset:8192
	ds_read_b128 v[134:137], v121 offset:12288
	s_waitcnt lgkmcnt(7)
	v_mfma_f32_16x16x32_bf16 v[68:71], v[68:71], v[92:95], 0
	s_waitcnt lgkmcnt(5)
	v_mfma_f32_16x16x32_bf16 v[68:71], v[76:79], v[64:67], v[68:71]
	s_waitcnt lgkmcnt(3)
	v_mfma_f32_16x16x32_bf16 v[68:71], v[96:99], v[84:87], v[68:71]
	s_waitcnt lgkmcnt(1)
	v_mfma_f32_16x16x32_bf16 v[96:99], v[126:129], v[88:91], v[68:71]
	v_mfma_f32_16x16x32_bf16 v[68:71], v[72:75], v[92:95], 0
	v_mfma_f32_16x16x32_bf16 v[68:71], v[80:83], v[64:67], v[68:71]
	v_mfma_f32_16x16x32_bf16 v[68:71], v[122:125], v[84:87], v[68:71]
	s_waitcnt lgkmcnt(0)
	v_mfma_f32_16x16x32_bf16 v[80:83], v[134:137], v[88:91], v[68:71]
	s_nop 5
	ds_read_b128 v[68:71], v146 offset:16384
	ds_read_b128 v[72:75], v146 offset:20480
	ds_read_b128 v[76:79], v147 offset:16384
	ds_read_b128 v[122:125], v147 offset:20480
	ds_read_b128 v[126:129], v148 offset:16384
	ds_read_b128 v[134:137], v148 offset:20480
	ds_read_b128 v[138:141], v121 offset:16384
	ds_read_b128 v[142:145], v121 offset:20480
	s_waitcnt lgkmcnt(7)
	v_mfma_f32_16x16x32_bf16 v[68:71], v[68:71], v[92:95], 0
	s_waitcnt lgkmcnt(5)
	v_mfma_f32_16x16x32_bf16 v[68:71], v[76:79], v[64:67], v[68:71]
	s_waitcnt lgkmcnt(3)
	v_mfma_f32_16x16x32_bf16 v[68:71], v[126:129], v[84:87], v[68:71]
	s_waitcnt lgkmcnt(1)
	v_mfma_f32_16x16x32_bf16 v[76:79], v[138:141], v[88:91], v[68:71]
	v_mfma_f32_16x16x32_bf16 v[68:71], v[72:75], v[92:95], 0
	v_mfma_f32_16x16x32_bf16 v[68:71], v[122:125], v[64:67], v[68:71]
	v_mfma_f32_16x16x32_bf16 v[68:71], v[134:137], v[84:87], v[68:71]
	s_waitcnt lgkmcnt(0)
; DEVFI bfraw f2bf(float x) { unsigned u = __float_as_uint(x); u += 0x7fffu + ((u >> 16) & 1u); return (bfraw)(u >> 16); }
; #define SBAR() __builtin_amdgcn_sched_barrier(0)
; __global__ void __launch_bounds__(512) mega(Params p) {
;     ...
; #pragma unroll
;                 for (int sx = 0; sx < 4; ++sx) sc[n2 * 2 + q2] = __builtin_amdgcn_mfma_f32_16x16x32_bf16(A[q2][sx], qf[sx], sc[n2 * 2 + q2], 0, 0, 0);
;               SBAR(); }
;             const int cc = w * 16 + fr;
; #pragma unroll
;             for (int sx = 0; sx < 4; ++sx)
; #pragma unroll
;               for (int hf = 0; hf < 2; ++hf)
; #pragma unroll
;                 for (int j = 0; j < 4; ++j) { const int n = 2 * sx + hf, mm = n * 16 + fq * 4 + j, diff = cc - mm;
;                   const float Dm = (diff >= 0) ? __expf(lgf * (float)diff) : __expf(lgb * (float)(-diff));
;                   pf[sx][hf * 4 + j] = (short)f2bf(sc[n][j] * Dm); } }
	v_mfma_f32_16x16x32_bf16 v[72:75], v[142:145], v[88:91], v[68:71]
	s_nop 5
	ds_read_b128 v[68:71], v146 offset:24576
	ds_read_b128 v[122:125], v146 offset:28672
	ds_read_b128 v[126:129], v147 offset:24576
	ds_read_b128 v[134:137], v147 offset:28672
	ds_read_b128 v[138:141], v148 offset:24576
	ds_read_b128 v[142:145], v148 offset:28672
	ds_read_b128 v[146:149], v121 offset:24576
	ds_read_b128 v[150:153], v121 offset:28672
	s_waitcnt lgkmcnt(7)
	v_mfma_f32_16x16x32_bf16 v[68:71], v[68:71], v[92:95], 0
	s_waitcnt lgkmcnt(6)
	v_mfma_f32_16x16x32_bf16 v[92:95], v[122:125], v[92:95], 0
	s_waitcnt lgkmcnt(5)
	v_mfma_f32_16x16x32_bf16 v[68:71], v[126:129], v[64:67], v[68:71]
	s_waitcnt lgkmcnt(4)
	v_mfma_f32_16x16x32_bf16 v[64:67], v[134:137], v[64:67], v[92:95]
	s_waitcnt lgkmcnt(3)
	v_mfma_f32_16x16x32_bf16 v[68:71], v[138:141], v[84:87], v[68:71]
	s_waitcnt lgkmcnt(2)
	v_mfma_f32_16x16x32_bf16 v[64:67], v[142:145], v[84:87], v[64:67]
	s_waitcnt lgkmcnt(1)
	v_mfma_f32_16x16x32_bf16 v[68:71], v[146:149], v[88:91], v[68:71]
	s_waitcnt lgkmcnt(0)
	v_mfma_f32_16x16x32_bf16 v[64:67], v[150:153], v[88:91], v[64:67]
	v_or_b32_e32 v87, s2, v115
	v_sub_u32_e32 v84, v87, v104
	v_sub_u32_e32 v85, 0, v84
	v_max_i32_e32 v85, v84, v85
	v_cvt_f32_u32_e32 v85, v85
	v_cmp_gt_i32_e32 vcc, 0, v84
	v_or_b32_e32 v86, 1, v104
	s_nop 0
	v_cndmask_b32_e32 v84, v117, v118, vcc
	v_mul_f32_e32 v84, v84, v85
	v_sub_u32_e32 v85, v87, v86
	v_sub_u32_e32 v88, 0, v85
	v_max_i32_e32 v88, v85, v88
	v_cvt_f32_u32_e32 v88, v88
	v_cmp_gt_i32_e32 vcc, 0, v85
	v_mul_f32_e32 v84, 0x3fb8aa3b, v84
	v_exp_f32_e32 v84, v84
	v_cndmask_b32_e32 v85, v117, v118, vcc
	v_mul_f32_e32 v85, v85, v88
	v_mul_f32_e32 v85, 0x3fb8aa3b, v85
	v_exp_f32_e32 v85, v85
	s_nop 0
	v_pk_mul_f32 v[94:95], v[84:85], v[130:131]
	v_or_b32_e32 v85, 2, v104
	v_sub_u32_e32 v84, v87, v85
	v_sub_u32_e32 v88, 0, v84
	v_max_i32_e32 v88, v84, v88
	v_cvt_f32_u32_e32 v88, v88
	v_cmp_gt_i32_e32 vcc, 0, v84
	s_nop 1
	v_cndmask_b32_e32 v84, v117, v118, vcc
	v_mul_f32_e32 v84, v84, v88
	v_mul_f32_e32 v84, 0x3fb8aa3b, v84
	v_exp_f32_e32 v88, v84
	v_or_b32_e32 v84, 3, v104
	v_sub_u32_e32 v89, v87, v84
	v_sub_u32_e32 v90, 0, v89
	v_max_i32_e32 v90, v89, v90
	v_cvt_f32_u32_e32 v90, v90
	v_cmp_gt_i32_e32 vcc, 0, v89
	s_nop 1
	v_cndmask_b32_e32 v89, v117, v118, vcc
	v_mul_f32_e32 v89, v89, v90
	v_or_b32_e32 v90, 16, v104
	v_sub_u32_e32 v90, v87, v90
	v_sub_u32_e32 v91, 0, v90
	v_max_i32_e32 v91, v90, v91
	v_cvt_f32_u32_e32 v91, v91
	v_cmp_gt_i32_e32 vcc, 0, v90
	v_mul_f32_e32 v89, 0x3fb8aa3b, v89
	v_exp_f32_e32 v89, v89
	v_cndmask_b32_e32 v90, v117, v118, vcc
	v_mul_f32_e32 v90, v90, v91
	v_or_b32_e32 v91, 17, v104
	v_sub_u32_e32 v91, v87, v91
	v_sub_u32_e32 v92, 0, v91
	v_max_i32_e32 v92, v91, v92
	v_cvt_f32_u32_e32 v92, v92
	v_cmp_gt_i32_e32 vcc, 0, v91
	v_mul_f32_e32 v90, 0x3fb8aa3b, v90
	v_exp_f32_e32 v90, v90
	v_cndmask_b32_e32 v91, v117, v118, vcc
	v_mul_f32_e32 v91, v91, v92
	v_mul_f32_e32 v91, 0x3fb8aa3b, v91
	v_exp_f32_e32 v91, v91
	v_pk_mul_f32 v[88:89], v[88:89], v[132:133]
	v_pk_mul_f32 v[100:101], v[90:91], v[100:101]
	v_or_b32_e32 v90, 18, v104
	v_sub_u32_e32 v90, v87, v90
	v_sub_u32_e32 v91, 0, v90
	v_max_i32_e32 v91, v90, v91
	v_cvt_f32_u32_e32 v91, v91
	v_cmp_gt_i32_e32 vcc, 0, v90
	s_nop 1
	v_cndmask_b32_e32 v90, v117, v118, vcc
	v_mul_f32_e32 v90, v90, v91
	v_or_b32_e32 v91, 19, v104
	v_sub_u32_e32 v91, v87, v91
	v_sub_u32_e32 v92, 0, v91
	v_max_i32_e32 v92, v91, v92
	v_cvt_f32_u32_e32 v92, v92
	v_cmp_gt_i32_e32 vcc, 0, v91
	v_mul_f32_e32 v90, 0x3fb8aa3b, v90
	v_exp_f32_e32 v90, v90
	v_cndmask_b32_e32 v91, v117, v118, vcc
	v_mul_f32_e32 v91, v91, v92
	v_mul_f32_e32 v91, 0x3fb8aa3b, v91
	v_exp_f32_e32 v91, v91
	s_nop 0
	v_pk_mul_f32 v[92:93], v[90:91], v[102:103]
	s_nop 0
	v_cvt_pk_bf16_f32 v93, v93, v93
	v_cvt_pk_bf16_f32 v90, v94, v94
	v_cvt_pk_bf16_f32 v94, v100, v100
	v_or_b32_e32 v100, 32, v104
	v_sub_u32_e32 v100, v87, v100
	v_cvt_pk_bf16_f32 v91, v92, v92
	v_cvt_pk_bf16_f32 v92, v95, v95
	v_cvt_pk_bf16_f32 v95, v101, v101
	v_sub_u32_e32 v101, 0, v100
	v_max_i32_e32 v101, v100, v101
	v_cvt_f32_u32_e32 v101, v101
	v_cmp_gt_i32_e32 vcc, 0, v100
	v_cvt_pk_bf16_f32 v89, v89, v89
	s_nop 0
	v_cndmask_b32_e32 v100, v117, v118, vcc
	v_mul_f32_e32 v100, v100, v101
	v_or_b32_e32 v101, 33, v104
	v_sub_u32_e32 v101, v87, v101
	v_sub_u32_e32 v102, 0, v101
	v_max_i32_e32 v102, v101, v102
	v_cvt_f32_u32_e32 v102, v102
	v_cmp_gt_i32_e32 vcc, 0, v101
	v_mul_f32_e32 v100, 0x3fb8aa3b, v100
	v_exp_f32_e32 v100, v100
	v_cndmask_b32_e32 v101, v117, v118, vcc
	v_mul_f32_e32 v101, v101, v102
	v_mul_f32_e32 v101, 0x3fb8aa3b, v101
	v_exp_f32_e32 v101, v101
	v_cvt_pk_bf16_f32 v88, v88, v88
	v_pk_mul_f32 v[100:101], v[100:101], v[96:97]
	v_or_b32_e32 v96, 34, v104
	v_sub_u32_e32 v96, v87, v96
	v_sub_u32_e32 v97, 0, v96
	v_max_i32_e32 v97, v96, v97
	v_cvt_f32_u32_e32 v97, v97
	v_cmp_gt_i32_e32 vcc, 0, v96
	s_nop 1
	v_cndmask_b32_e32 v96, v117, v118, vcc
	v_mul_f32_e32 v96, v96, v97
	v_or_b32_e32 v97, 35, v104
	v_sub_u32_e32 v97, v87, v97
	v_sub_u32_e32 v102, 0, v97
	v_max_i32_e32 v102, v97, v102
	v_cvt_f32_u32_e32 v102, v102
	v_cmp_gt_i32_e32 vcc, 0, v97
	v_mul_f32_e32 v96, 0x3fb8aa3b, v96
	v_exp_f32_e32 v96, v96
	v_cndmask_b32_e32 v97, v117, v118, vcc
	v_mul_f32_e32 v97, v97, v102
	v_mul_f32_e32 v97, 0x3fb8aa3b, v97
	v_exp_f32_e32 v97, v97
	s_nop 0
	v_pk_mul_f32 v[96:97], v[96:97], v[98:99]
	v_or_b32_e32 v98, 48, v104
	v_sub_u32_e32 v98, v87, v98
	v_sub_u32_e32 v99, 0, v98
	v_max_i32_e32 v99, v98, v99
	v_cvt_f32_u32_e32 v99, v99
	v_cmp_gt_i32_e32 vcc, 0, v98
	s_nop 1
	v_cndmask_b32_e32 v98, v117, v118, vcc
	v_mul_f32_e32 v98, v98, v99
; DEVFI bfraw f2bf(float x) { unsigned u = __float_as_uint(x); u += 0x7fffu + ((u >> 16) & 1u); return (bfraw)(u >> 16); }
; __global__ void __launch_bounds__(512) mega(Params p) {
;     ...
;             for (int sx = 0; sx < 4; ++sx)
; #pragma unroll
;               for (int hf = 0; hf < 2; ++hf)
; #pragma unroll
;                 for (int j = 0; j < 4; ++j) { const int n = 2 * sx + hf, mm = n * 16 + fq * 4 + j, diff = cc - mm;
;                   const float Dm = (diff >= 0) ? __expf(lgf * (float)diff) : __expf(lgb * (float)(-diff));
;                   pf[sx][hf * 4 + j] = (short)f2bf(sc[n][j] * Dm); } }
	v_or_b32_e32 v99, 49, v104
	v_sub_u32_e32 v99, v87, v99
	v_sub_u32_e32 v102, 0, v99
	v_max_i32_e32 v102, v99, v102
	v_cvt_f32_u32_e32 v102, v102
	v_cmp_gt_i32_e32 vcc, 0, v99
	v_mul_f32_e32 v98, 0x3fb8aa3b, v98
	v_exp_f32_e32 v98, v98
	v_cndmask_b32_e32 v99, v117, v118, vcc
	v_mul_f32_e32 v99, v99, v102
	v_mul_f32_e32 v99, 0x3fb8aa3b, v99
	v_exp_f32_e32 v99, v99
	s_nop 0
	v_pk_mul_f32 v[98:99], v[98:99], v[80:81]
	v_or_b32_e32 v80, 50, v104
	v_sub_u32_e32 v80, v87, v80
	v_sub_u32_e32 v81, 0, v80
	v_max_i32_e32 v81, v80, v81
	v_cvt_f32_u32_e32 v81, v81
	v_cmp_gt_i32_e32 vcc, 0, v80
	v_cvt_pk_bf16_f32 v98, v98, v98
	s_nop 0
	v_cndmask_b32_e32 v80, v117, v118, vcc
	v_mul_f32_e32 v80, v80, v81
	v_or_b32_e32 v81, 51, v104
	v_sub_u32_e32 v81, v87, v81
	v_sub_u32_e32 v102, 0, v81
	v_max_i32_e32 v102, v81, v102
	v_cvt_f32_u32_e32 v102, v102
	v_cmp_gt_i32_e32 vcc, 0, v81
	v_mul_f32_e32 v80, 0x3fb8aa3b, v80
	v_exp_f32_e32 v80, v80
	v_cndmask_b32_e32 v81, v117, v118, vcc
	v_mul_f32_e32 v81, v81, v102
	v_mul_f32_e32 v81, 0x3fb8aa3b, v81
	v_exp_f32_e32 v81, v81
	v_cvt_pk_bf16_f32 v99, v99, v99
	v_pk_mul_f32 v[102:103], v[80:81], v[82:83]
	s_nop 0
	v_cvt_pk_bf16_f32 v81, v97, v97
	v_cvt_pk_bf16_f32 v97, v103, v103
	v_cvt_pk_bf16_f32 v82, v100, v100
	v_or_b32_e32 v100, 64, v104
	v_sub_u32_e32 v100, v87, v100
	v_cvt_pk_bf16_f32 v80, v96, v96
	v_cvt_pk_bf16_f32 v96, v101, v101
	v_sub_u32_e32 v101, 0, v100
	v_max_i32_e32 v101, v100, v101
	v_cvt_f32_u32_e32 v101, v101
	v_cmp_gt_i32_e32 vcc, 0, v100
	v_cvt_pk_bf16_f32 v83, v102, v102
	s_nop 0
	v_cndmask_b32_e32 v100, v117, v118, vcc
	v_mul_f32_e32 v100, v100, v101
	v_or_b32_e32 v101, 0x41, v104
	v_sub_u32_e32 v101, v87, v101
	v_sub_u32_e32 v102, 0, v101
	v_max_i32_e32 v102, v101, v102
	v_cvt_f32_u32_e32 v102, v102
	v_cmp_gt_i32_e32 vcc, 0, v101
	v_mul_f32_e32 v100, 0x3fb8aa3b, v100
	v_exp_f32_e32 v100, v100
	v_cndmask_b32_e32 v101, v117, v118, vcc
	v_mul_f32_e32 v101, v101, v102
	v_mul_f32_e32 v101, 0x3fb8aa3b, v101
	v_exp_f32_e32 v101, v101
	s_nop 0
	v_pk_mul_f32 v[76:77], v[100:101], v[76:77]
	v_or_b32_e32 v100, 0x42, v104
	v_sub_u32_e32 v100, v87, v100
	v_sub_u32_e32 v101, 0, v100
	v_max_i32_e32 v101, v100, v101
	v_cvt_f32_u32_e32 v101, v101
	v_cmp_gt_i32_e32 vcc, 0, v100
	s_nop 1
	v_cndmask_b32_e32 v100, v117, v118, vcc
	v_mul_f32_e32 v100, v100, v101
	v_or_b32_e32 v101, 0x43, v104
	v_sub_u32_e32 v101, v87, v101
	v_sub_u32_e32 v102, 0, v101
	v_max_i32_e32 v102, v101, v102
	v_cvt_f32_u32_e32 v102, v102
	v_cmp_gt_i32_e32 vcc, 0, v101
	v_mul_f32_e32 v100, 0x3fb8aa3b, v100
	v_exp_f32_e32 v100, v100
	v_cndmask_b32_e32 v101, v117, v118, vcc
	v_mul_f32_e32 v101, v101, v102
	v_mul_f32_e32 v101, 0x3fb8aa3b, v101
	v_exp_f32_e32 v101, v101
	v_cvt_pk_bf16_f32 v142, v76, v76
	v_cvt_pk_bf16_f32 v143, v77, v77
	v_pk_mul_f32 v[78:79], v[100:101], v[78:79]
	v_or_b32_e32 v100, 0x50, v104
	v_sub_u32_e32 v100, v87, v100
	v_sub_u32_e32 v101, 0, v100
	v_max_i32_e32 v101, v100, v101
	v_cvt_f32_u32_e32 v101, v101
	v_cmp_gt_i32_e32 vcc, 0, v100
	v_cvt_pk_bf16_f32 v78, v78, v78
	s_nop 0
	v_cndmask_b32_e32 v100, v117, v118, vcc
	v_mul_f32_e32 v100, v100, v101
	v_or_b32_e32 v101, 0x51, v104
	v_sub_u32_e32 v101, v87, v101
	v_sub_u32_e32 v102, 0, v101
	v_max_i32_e32 v102, v101, v102
	v_cvt_f32_u32_e32 v102, v102
	v_cmp_gt_i32_e32 vcc, 0, v101
	v_mul_f32_e32 v100, 0x3fb8aa3b, v100
	v_exp_f32_e32 v100, v100
	v_cndmask_b32_e32 v101, v117, v118, vcc
	v_mul_f32_e32 v101, v101, v102
	v_mul_f32_e32 v101, 0x3fb8aa3b, v101
	v_exp_f32_e32 v101, v101
	s_nop 0
	v_pk_mul_f32 v[72:73], v[100:101], v[72:73]
	v_or_b32_e32 v100, 0x52, v104
	v_sub_u32_e32 v100, v87, v100
	v_sub_u32_e32 v101, 0, v100
	v_max_i32_e32 v101, v100, v101
	v_cvt_f32_u32_e32 v101, v101
	v_cmp_gt_i32_e32 vcc, 0, v100
	v_cvt_pk_bf16_f32 v144, v72, v72
	s_nop 0
	v_cndmask_b32_e32 v100, v117, v118, vcc
	v_mul_f32_e32 v100, v100, v101
	v_or_b32_e32 v101, 0x53, v104
	v_sub_u32_e32 v101, v87, v101
	v_sub_u32_e32 v102, 0, v101
	v_max_i32_e32 v102, v101, v102
	v_cvt_f32_u32_e32 v102, v102
	v_cmp_gt_i32_e32 vcc, 0, v101
	v_or_b32_e32 v72, 0x60, v104
	s_nop 0
	v_cndmask_b32_e32 v101, v117, v118, vcc
	v_sub_u32_e32 v72, v87, v72
	v_mul_f32_e32 v101, v101, v102
	v_cvt_pk_bf16_f32 v145, v73, v73
	v_sub_u32_e32 v73, 0, v72
	v_mul_f32_e32 v100, 0x3fb8aa3b, v100
	v_mul_f32_e32 v101, 0x3fb8aa3b, v101
	v_max_i32_e32 v73, v72, v73
	v_exp_f32_e32 v100, v100
	v_exp_f32_e32 v101, v101
	v_cvt_f32_u32_e32 v73, v73
	v_cmp_gt_i32_e32 vcc, 0, v72
	v_pk_mul_f32 v[74:75], v[100:101], v[74:75]
	s_nop 0
	v_cndmask_b32_e32 v72, v117, v118, vcc
	v_mul_f32_e32 v72, v72, v73
	v_or_b32_e32 v73, 0x61, v104
	v_sub_u32_e32 v73, v87, v73
	v_cvt_pk_bf16_f32 v140, v74, v74
	v_sub_u32_e32 v74, 0, v73
	v_max_i32_e32 v74, v73, v74
	v_cvt_f32_u32_e32 v74, v74
	v_cmp_gt_i32_e32 vcc, 0, v73
	v_mul_f32_e32 v72, 0x3fb8aa3b, v72
	v_exp_f32_e32 v72, v72
	v_cndmask_b32_e32 v73, v117, v118, vcc
	v_mul_f32_e32 v73, v73, v74
	v_mul_f32_e32 v73, 0x3fb8aa3b, v73
	v_exp_f32_e32 v73, v73
	v_cvt_pk_bf16_f32 v141, v75, v75
	v_cvt_pk_bf16_f32 v79, v79, v79
	v_pk_mul_f32 v[68:69], v[72:73], v[68:69]
	v_or_b32_e32 v72, 0x62, v104
	v_sub_u32_e32 v72, v87, v72
	v_sub_u32_e32 v73, 0, v72
	v_max_i32_e32 v73, v72, v73
	v_cvt_f32_u32_e32 v73, v73
	v_cmp_gt_i32_e32 vcc, 0, v72
	v_cvt_pk_bf16_f32 v150, v68, v68
	s_nop 0
	v_cndmask_b32_e32 v72, v117, v118, vcc
	v_mul_f32_e32 v72, v72, v73
	v_or_b32_e32 v73, 0x63, v104
	v_sub_u32_e32 v73, v87, v73
	v_sub_u32_e32 v74, 0, v73
	v_max_i32_e32 v74, v73, v74
	v_cvt_f32_u32_e32 v74, v74
	v_cmp_gt_i32_e32 vcc, 0, v73
	v_mul_f32_e32 v72, 0x3fb8aa3b, v72
	v_exp_f32_e32 v72, v72
	v_cndmask_b32_e32 v73, v117, v118, vcc
; DEVFI bfraw f2bf(float x) { unsigned u = __float_as_uint(x); u += 0x7fffu + ((u >> 16) & 1u); return (bfraw)(u >> 16); }
; #define SBAR() __builtin_amdgcn_sched_barrier(0)
; __global__ void __launch_bounds__(512) mega(Params p) {
;     ...
;             for (int j = 0; j < 4; ++j) { const int c = w * 16 + fq * 4 + j; const float xf = __expf(lgf * (float)(c + 1)), xb = __expf(lgb * (float)(128 - c));
; #pragma unroll
;               for (int ne = 0; ne < 8; ++ne) o[ne][j] = xf * af[ne][j] + xb * ab[ne][j]; } }
;     ...
;             for (int sx = 0; sx < 4; ++sx)
; #pragma unroll
;               for (int hf = 0; hf < 2; ++hf)
; #pragma unroll
;                 for (int j = 0; j < 4; ++j) { const int n = 2 * sx + hf, mm = n * 16 + fq * 4 + j, diff = cc - mm;
;                   const float Dm = (diff >= 0) ? __expf(lgf * (float)diff) : __expf(lgb * (float)(-diff));
;                   pf[sx][hf * 4 + j] = (short)f2bf(sc[n][j] * Dm); } }
;           { const char* vl = shm + 32768 + fr * 256 + (fq & 1) * 8;
; #pragma unroll
;             for (int n2 = 0; n2 < 4; ++n2) { s16x4 lo[2][4], hi[2][4];
; #pragma unroll
;               for (int q2 = 0; q2 < 2; ++q2)
; #pragma unroll
;                 for (int sx = 0; sx < 4; ++sx) { lo[q2][sx] = *(const s16x4*)(vl + (n2 * 2 + q2) * 4096 + ((((sx * 4 + (fq >> 1)) ^ fr) & 15) << 4));
;                   hi[q2][sx] = *(const s16x4*)(vl + (n2 * 2 + q2) * 4096 + ((((sx * 4 + 2 + (fq >> 1)) ^ fr) & 15) << 4)); }
;               SBAR();
; #pragma unroll
;               for (int q2 = 0; q2 < 2; ++q2)
; #pragma unroll
;                 for (int sx = 0; sx < 4; ++sx) { const bf16x8 B = {lo[q2][sx][0], lo[q2][sx][1], lo[q2][sx][2], lo[q2][sx][3], hi[q2][sx][0], hi[q2][sx][1], hi[q2][sx][2], hi[q2][sx][3]};
;                   o[n2 * 2 + q2] = __builtin_amdgcn_mfma_f32_16x16x32_bf16(pf[sx], B, o[n2 * 2 + q2], 0, 0, 0); }
;               SBAR(); } }
	v_mul_f32_e32 v73, v73, v74
	v_mul_f32_e32 v73, 0x3fb8aa3b, v73
	v_exp_f32_e32 v73, v73
	s_nop 0
	v_pk_mul_f32 v[70:71], v[72:73], v[70:71]
	v_or_b32_e32 v72, 0x70, v104
	v_sub_u32_e32 v72, v87, v72
	v_sub_u32_e32 v73, 0, v72
	v_max_i32_e32 v73, v72, v73
	v_cvt_f32_u32_e32 v73, v73
	v_cmp_gt_i32_e32 vcc, 0, v72
	v_cvt_pk_bf16_f32 v146, v70, v70
	s_nop 0
	v_cndmask_b32_e32 v72, v117, v118, vcc
	v_mul_f32_e32 v72, v72, v73
	v_or_b32_e32 v73, 0x71, v104
	v_sub_u32_e32 v73, v87, v73
	v_sub_u32_e32 v74, 0, v73
	v_max_i32_e32 v74, v73, v74
	v_cvt_f32_u32_e32 v74, v74
	v_cmp_gt_i32_e32 vcc, 0, v73
	v_mul_f32_e32 v72, 0x3fb8aa3b, v72
	v_exp_f32_e32 v72, v72
	v_cndmask_b32_e32 v73, v117, v118, vcc
	v_mul_f32_e32 v73, v73, v74
	v_mul_f32_e32 v73, 0x3fb8aa3b, v73
	v_exp_f32_e32 v73, v73
	s_nop 0
	v_pk_mul_f32 v[64:65], v[72:73], v[64:65]
	v_or_b32_e32 v72, 0x72, v104
	v_sub_u32_e32 v72, v87, v72
	v_sub_u32_e32 v73, 0, v72
	v_max_i32_e32 v73, v72, v73
	v_cvt_f32_u32_e32 v73, v73
	v_cmp_gt_i32_e32 vcc, 0, v72
	s_nop 1
	v_cndmask_b32_e32 v72, v117, v118, vcc
	v_mul_f32_e32 v72, v72, v73
	v_or_b32_e32 v73, 0x73, v104
	v_sub_u32_e32 v73, v87, v73
	v_sub_u32_e32 v74, 0, v73
	v_max_i32_e32 v74, v73, v74
	v_cvt_f32_u32_e32 v74, v74
	v_cmp_gt_i32_e32 vcc, 0, v73
	v_mul_f32_e32 v72, 0x3fb8aa3b, v72
	v_exp_f32_e32 v72, v72
	v_cndmask_b32_e32 v73, v117, v118, vcc
	v_mul_f32_e32 v73, v73, v74
	v_mul_f32_e32 v73, 0x3fb8aa3b, v73
	v_exp_f32_e32 v73, v73
	v_cvt_pk_bf16_f32 v151, v64, v64
	v_cvt_pk_bf16_f32 v152, v65, v65
	v_lshrrev_b32_e32 v64, 1, v116
	v_pk_mul_f32 v[66:67], v[72:73], v[66:67]
	v_bfe_u32 v65, v119, 1, 1
	v_cvt_pk_bf16_f32 v148, v66, v66
	v_and_or_b32 v64, v64, 8, v120
	v_bitop3_b32 v66, v65, v116, 15 bitop3:0x78
	v_lshl_or_b32 v153, v66, 4, v64
	v_bitop3_b32 v66, v65, v115, 2 bitop3:0x36
	v_lshl_or_b32 v154, v66, 4, v64
	v_bitop3_b32 v66, v65, v115, 4 bitop3:0x36
	v_lshl_or_b32 v155, v66, 4, v64
	v_bitop3_b32 v66, v65, v115, 6 bitop3:0x36
	v_lshl_or_b32 v156, v66, 4, v64
	v_bitop3_b32 v66, v65, v115, 8 bitop3:0x36
	v_lshl_or_b32 v157, v66, 4, v64
	v_bitop3_b32 v66, v65, v115, 10 bitop3:0x36
	v_lshl_or_b32 v158, v66, 4, v64
	v_bitop3_b32 v66, v65, v115, 12 bitop3:0x36
	v_bitop3_b32 v65, v65, v115, 14 bitop3:0x36
	v_lshl_or_b32 v159, v66, 4, v64
	v_lshl_or_b32 v160, v65, 4, v64
	v_cvt_pk_bf16_f32 v147, v71, v71
	ds_read2st64_b64 v[74:77], v153 offset0:64 offset1:72
	ds_read2st64_b64 v[100:103], v154 offset0:64 offset1:72
	ds_read2st64_b64 v[116:119], v155 offset0:64 offset1:72
	ds_read2st64_b64 v[120:123], v156 offset0:64 offset1:72
	ds_read2st64_b64 v[124:127], v157 offset0:64 offset1:72
	ds_read2st64_b64 v[128:131], v158 offset0:64 offset1:72
	ds_read2st64_b64 v[132:135], v159 offset0:64 offset1:72
	ds_read2st64_b64 v[136:139], v160 offset0:64 offset1:72
	v_cvt_pk_bf16_f32 v149, v67, v67
	v_cvt_pk_bf16_f32 v87, v69, v69
	v_perm_b32 v67, v93, v91, s58
	v_perm_b32 v65, v89, v88, s58
	v_perm_b32 v66, v95, v94, s58
	v_perm_b32 v64, v92, v90, s58
	v_pk_mul_f32 v[62:63], v[112:113], v[62:63]
	v_pk_mul_f32 v[60:61], v[108:109], v[60:61]
	s_waitcnt lgkmcnt(7)
	v_mov_b32_e32 v68, v74
	v_mov_b32_e32 v69, v75
	s_waitcnt lgkmcnt(6)
	v_mov_b32_e32 v70, v100
	v_mov_b32_e32 v71, v101
	v_pk_fma_f32 v[30:31], v[110:111], v[30:31], v[62:63]
	v_pk_fma_f32 v[28:29], v[106:107], v[28:29], v[60:61]
	v_perm_b32 v63, v97, v83, s58
	v_perm_b32 v61, v81, v80, s58
	v_perm_b32 v62, v99, v98, s58
	v_perm_b32 v60, v96, v82, s58
	v_mfma_f32_16x16x32_bf16 v[28:31], v[64:67], v[68:71], v[28:31]
	v_mul_f32_e64 v58, v112, v58
	v_mul_f32_e64 v59, v113, v59
	v_pk_mul_f32 v[56:57], v[108:109], v[56:57]
	v_mov_b32_e32 v100, v76
	v_mov_b32_e32 v101, v77
	v_pk_fma_f32 v[2:3], v[110:111], v[2:3], v[58:59]
	v_pk_fma_f32 v[0:1], v[106:107], v[0:1], v[56:57]
	s_waitcnt lgkmcnt(5)
	v_mov_b32_e32 v68, v116
	v_mov_b32_e32 v69, v117
	v_mfma_f32_16x16x32_bf16 v[0:3], v[64:67], v[100:103], v[0:3]
	s_waitcnt lgkmcnt(4)
	v_mov_b32_e32 v70, v120
	v_mov_b32_e32 v71, v121
	v_mov_b32_e32 v120, v118
	v_mov_b32_e32 v121, v119
	v_mfma_f32_16x16x32_bf16 v[28:31], v[60:63], v[68:71], v[28:31]
	v_perm_b32 v71, v141, v140, s58
	v_perm_b32 v69, v79, v78, s58
	v_perm_b32 v70, v145, v144, s58
	v_perm_b32 v68, v143, v142, s58
	v_mfma_f32_16x16x32_bf16 v[0:3], v[60:63], v[120:123], v[0:3]
	s_waitcnt lgkmcnt(3)
	v_mov_b32_e32 v72, v124
	v_mov_b32_e32 v73, v125
	s_waitcnt lgkmcnt(2)
	v_mov_b32_e32 v74, v128
	v_mov_b32_e32 v75, v129
	v_mov_b32_e32 v128, v126
	v_mov_b32_e32 v129, v127
	v_mfma_f32_16x16x32_bf16 v[28:31], v[68:71], v[72:75], v[28:31]
	v_perm_b32 v75, v149, v148, s58
	v_perm_b32 v73, v147, v146, s58
	v_perm_b32 v74, v152, v151, s58
	v_perm_b32 v72, v87, v150, s58
	v_mfma_f32_16x16x32_bf16 v[0:3], v[68:71], v[128:131], v[0:3]
	s_waitcnt lgkmcnt(1)
	v_mov_b32_e32 v78, v132
	v_mov_b32_e32 v79, v133
	s_waitcnt lgkmcnt(0)
	v_mov_b32_e32 v80, v136
	v_mov_b32_e32 v81, v137
	v_mov_b32_e32 v136, v134
	v_mov_b32_e32 v137, v135
	v_mfma_f32_16x16x32_bf16 v[28:31], v[72:75], v[78:81], v[28:31]
	s_nop 0
	v_mfma_f32_16x16x32_bf16 v[0:3], v[72:75], v[136:139], v[0:3]
	ds_read2st64_b64 v[56:59], v153 offset0:80 offset1:88
	ds_read2st64_b64 v[76:79], v154 offset0:80 offset1:88
	ds_read2st64_b64 v[80:83], v155 offset0:80 offset1:88
	ds_read2st64_b64 v[88:91], v156 offset0:80 offset1:88
	ds_read2st64_b64 v[92:95], v157 offset0:80 offset1:88
	ds_read2st64_b64 v[96:99], v158 offset0:80 offset1:88
	ds_read2st64_b64 v[100:103], v159 offset0:80 offset1:88
	ds_read2st64_b64 v[116:119], v160 offset0:80 offset1:88
	v_pk_mul_f32 v[54:55], v[112:113], v[54:55]
	v_pk_mul_f32 v[52:53], v[108:109], v[52:53]
	v_pk_mul_f32 v[50:51], v[112:113], v[50:51]
	v_pk_mul_f32 v[48:49], v[108:109], v[48:49]
	s_waitcnt lgkmcnt(7)
; #define SBAR() __builtin_amdgcn_sched_barrier(0)
; __global__ void __launch_bounds__(512) mega(Params p) {
;     ...
;             for (int j = 0; j < 4; ++j) { const int c = w * 16 + fq * 4 + j; const float xf = __expf(lgf * (float)(c + 1)), xb = __expf(lgb * (float)(128 - c));
; #pragma unroll
;               for (int ne = 0; ne < 8; ++ne) o[ne][j] = xf * af[ne][j] + xb * ab[ne][j]; } }
;     ...
;           { const char* vl = shm + 32768 + fr * 256 + (fq & 1) * 8;
; #pragma unroll
;             for (int n2 = 0; n2 < 4; ++n2) { s16x4 lo[2][4], hi[2][4];
; #pragma unroll
;               for (int q2 = 0; q2 < 2; ++q2)
; #pragma unroll
;                 for (int sx = 0; sx < 4; ++sx) { lo[q2][sx] = *(const s16x4*)(vl + (n2 * 2 + q2) * 4096 + ((((sx * 4 + (fq >> 1)) ^ fr) & 15) << 4));
;                   hi[q2][sx] = *(const s16x4*)(vl + (n2 * 2 + q2) * 4096 + ((((sx * 4 + 2 + (fq >> 1)) ^ fr) & 15) << 4)); }
;               SBAR();
; #pragma unroll
;               for (int q2 = 0; q2 < 2; ++q2)
; #pragma unroll
;                 for (int sx = 0; sx < 4; ++sx) { const bf16x8 B = {lo[q2][sx][0], lo[q2][sx][1], lo[q2][sx][2], lo[q2][sx][3], hi[q2][sx][0], hi[q2][sx][1], hi[q2][sx][2], hi[q2][sx][3]};
;                   o[n2 * 2 + q2] = __builtin_amdgcn_mfma_f32_16x16x32_bf16(pf[sx], B, o[n2 * 2 + q2], 0, 0, 0); }
;               SBAR(); } }
	v_mov_b32_e32 v120, v56
	v_mov_b32_e32 v121, v57
	s_waitcnt lgkmcnt(6)
	v_mov_b32_e32 v122, v76
	v_mov_b32_e32 v123, v77
	v_pk_fma_f32 v[6:7], v[110:111], v[6:7], v[54:55]
	v_pk_fma_f32 v[4:5], v[106:107], v[4:5], v[52:53]
	v_mov_b32_e32 v76, v58
	v_mov_b32_e32 v77, v59
	v_pk_fma_f32 v[10:11], v[110:111], v[10:11], v[50:51]
	v_pk_fma_f32 v[8:9], v[106:107], v[8:9], v[48:49]
	v_mfma_f32_16x16x32_bf16 v[4:7], v[64:67], v[120:123], v[4:7]
	s_waitcnt lgkmcnt(5)
	v_mov_b32_e32 v52, v80
	v_mov_b32_e32 v53, v81
	s_waitcnt lgkmcnt(4)
	v_mov_b32_e32 v54, v88
	v_mfma_f32_16x16x32_bf16 v[8:11], v[64:67], v[76:79], v[8:11]
	v_mov_b32_e32 v55, v89
	v_mov_b32_e32 v88, v82
	v_mov_b32_e32 v89, v83
	v_mfma_f32_16x16x32_bf16 v[4:7], v[60:63], v[52:55], v[4:7]
	s_waitcnt lgkmcnt(3)
	v_mov_b32_e32 v52, v92
	v_mov_b32_e32 v53, v93
	s_waitcnt lgkmcnt(2)
	v_mov_b32_e32 v54, v96
	v_mfma_f32_16x16x32_bf16 v[8:11], v[60:63], v[88:91], v[8:11]
	v_mov_b32_e32 v55, v97
	v_mov_b32_e32 v96, v94
	v_mov_b32_e32 v97, v95
	v_mfma_f32_16x16x32_bf16 v[4:7], v[68:71], v[52:55], v[4:7]
	s_waitcnt lgkmcnt(1)
	v_mov_b32_e32 v52, v100
	v_mov_b32_e32 v53, v101
	s_waitcnt lgkmcnt(0)
	v_mov_b32_e32 v54, v116
	v_mfma_f32_16x16x32_bf16 v[8:11], v[68:71], v[96:99], v[8:11]
	v_mov_b32_e32 v55, v117
	v_mov_b32_e32 v116, v102
	v_mov_b32_e32 v117, v103
	v_mfma_f32_16x16x32_bf16 v[4:7], v[72:75], v[52:55], v[4:7]
	s_nop 0
	v_mfma_f32_16x16x32_bf16 v[8:11], v[72:75], v[116:119], v[8:11]
	ds_read2st64_b64 v[48:51], v153 offset0:96 offset1:104
	ds_read2st64_b64 v[52:55], v154 offset0:96 offset1:104
	ds_read2st64_b64 v[56:59], v155 offset0:96 offset1:104
	ds_read2st64_b64 v[76:79], v156 offset0:96 offset1:104
	ds_read2st64_b64 v[80:83], v157 offset0:96 offset1:104
	ds_read2st64_b64 v[88:91], v158 offset0:96 offset1:104
	ds_read2st64_b64 v[92:95], v159 offset0:96 offset1:104
	ds_read2st64_b64 v[96:99], v160 offset0:96 offset1:104
	v_pk_mul_f32 v[46:47], v[112:113], v[46:47]
	v_pk_mul_f32 v[44:45], v[108:109], v[44:45]
	v_pk_mul_f32 v[42:43], v[112:113], v[42:43]
	v_pk_mul_f32 v[40:41], v[108:109], v[40:41]
	s_waitcnt lgkmcnt(7)
	v_mov_b32_e32 v100, v48
	v_mov_b32_e32 v101, v49
	s_waitcnt lgkmcnt(6)
	v_mov_b32_e32 v102, v52
	v_mov_b32_e32 v103, v53
	v_pk_fma_f32 v[14:15], v[110:111], v[14:15], v[46:47]
	v_pk_fma_f32 v[12:13], v[106:107], v[12:13], v[44:45]
	v_mov_b32_e32 v52, v50
	v_mov_b32_e32 v53, v51
	v_pk_fma_f32 v[18:19], v[110:111], v[18:19], v[42:43]
	v_pk_fma_f32 v[16:17], v[106:107], v[16:17], v[40:41]
	v_mfma_f32_16x16x32_bf16 v[12:15], v[64:67], v[100:103], v[12:15]
	s_waitcnt lgkmcnt(5)
	v_mov_b32_e32 v44, v56
	v_mov_b32_e32 v45, v57
	s_waitcnt lgkmcnt(4)
	v_mov_b32_e32 v46, v76
	v_mfma_f32_16x16x32_bf16 v[16:19], v[64:67], v[52:55], v[16:19]
	v_mov_b32_e32 v47, v77
	v_mov_b32_e32 v76, v58
	v_mov_b32_e32 v77, v59
	v_mfma_f32_16x16x32_bf16 v[12:15], v[60:63], v[44:47], v[12:15]
	s_waitcnt lgkmcnt(3)
	v_mov_b32_e32 v44, v80
	v_mov_b32_e32 v45, v81
	s_waitcnt lgkmcnt(2)
	v_mov_b32_e32 v46, v88
	v_mfma_f32_16x16x32_bf16 v[16:19], v[60:63], v[76:79], v[16:19]
	v_mov_b32_e32 v47, v89
	v_mov_b32_e32 v88, v82
	v_mov_b32_e32 v89, v83
	v_mfma_f32_16x16x32_bf16 v[12:15], v[68:71], v[44:47], v[12:15]
	s_waitcnt lgkmcnt(1)
	v_mov_b32_e32 v44, v92
	v_mov_b32_e32 v45, v93
	s_waitcnt lgkmcnt(0)
	v_mov_b32_e32 v46, v96
	v_mfma_f32_16x16x32_bf16 v[16:19], v[68:71], v[88:91], v[16:19]
	v_mov_b32_e32 v47, v97
	v_mov_b32_e32 v96, v94
	v_mov_b32_e32 v97, v95
	v_mfma_f32_16x16x32_bf16 v[12:15], v[72:75], v[44:47], v[12:15]
	s_nop 0
	v_mfma_f32_16x16x32_bf16 v[16:19], v[72:75], v[96:99], v[16:19]
	ds_read2st64_b64 v[40:43], v153 offset0:112 offset1:120
	ds_read2st64_b64 v[44:47], v154 offset0:112 offset1:120
	ds_read2st64_b64 v[48:51], v155 offset0:112 offset1:120
	ds_read2st64_b64 v[52:55], v156 offset0:112 offset1:120
	ds_read2st64_b64 v[56:59], v157 offset0:112 offset1:120
	ds_read2st64_b64 v[76:79], v158 offset0:112 offset1:120
	ds_read2st64_b64 v[80:83], v159 offset0:112 offset1:120
	ds_read2st64_b64 v[88:91], v160 offset0:112 offset1:120
	v_pk_mul_f32 v[38:39], v[112:113], v[38:39]
	v_pk_mul_f32 v[36:37], v[108:109], v[36:37]
	v_pk_mul_f32 v[34:35], v[112:113], v[34:35]
	v_pk_mul_f32 v[32:33], v[108:109], v[32:33]
	s_waitcnt lgkmcnt(7)
	v_mov_b32_e32 v92, v40
	v_mov_b32_e32 v93, v41
	s_waitcnt lgkmcnt(6)
	v_mov_b32_e32 v94, v44
	v_mov_b32_e32 v95, v45
	v_pk_fma_f32 v[22:23], v[110:111], v[22:23], v[38:39]
	v_pk_fma_f32 v[20:21], v[106:107], v[20:21], v[36:37]
	v_mov_b32_e32 v44, v42
	v_mov_b32_e32 v45, v43
	v_pk_fma_f32 v[26:27], v[110:111], v[26:27], v[34:35]
	v_pk_fma_f32 v[24:25], v[106:107], v[24:25], v[32:33]
	v_mfma_f32_16x16x32_bf16 v[20:23], v[64:67], v[92:95], v[20:23]
	s_waitcnt lgkmcnt(5)
	v_mov_b32_e32 v36, v48
	v_mov_b32_e32 v37, v49
	s_waitcnt lgkmcnt(4)
	v_mov_b32_e32 v38, v52
	v_mfma_f32_16x16x32_bf16 v[24:27], v[64:67], v[44:47], v[24:27]
	v_mov_b32_e32 v39, v53
	v_mov_b32_e32 v52, v50
	v_mov_b32_e32 v53, v51
	v_mfma_f32_16x16x32_bf16 v[20:23], v[60:63], v[36:39], v[20:23]
	s_waitcnt lgkmcnt(3)
	v_mov_b32_e32 v36, v56
	v_mov_b32_e32 v37, v57
	s_waitcnt lgkmcnt(2)
	v_mov_b32_e32 v38, v76
	v_mfma_f32_16x16x32_bf16 v[24:27], v[60:63], v[52:55], v[24:27]
	v_mov_b32_e32 v39, v77
	v_mov_b32_e32 v76, v58
	v_mov_b32_e32 v77, v59
	v_mfma_f32_16x16x32_bf16 v[20:23], v[68:71], v[36:39], v[20:23]
	s_waitcnt lgkmcnt(1)
	v_mov_b32_e32 v36, v80
	v_mov_b32_e32 v37, v81
	s_waitcnt lgkmcnt(0)
; DEVFI float bf2f(bfraw h) { return __uint_as_float(((unsigned)h) << 16); }
; DEVFI bfraw f2bf(float x) { unsigned u = __float_as_uint(x); u += 0x7fffu + ((u >> 16) & 1u); return (bfraw)(u >> 16); }
; #define RG ((bfraw*)(kargs()->ws + O_RG))
; #define RO ((bfraw*)(kargs()->ws + O_RO))
; __global__ void __launch_bounds__(512) mega(Params p) {
;     ...
;           float gw[8];
; #pragma unroll
;           for (int ne = 0; ne < 8; ++ne) gw[ne] = gn_w[head * 128 + ne * 16 + fr];
; #pragma unroll
;           for (int j = 0; j < 4; ++j) { float s1 = 0;
; #pragma unroll
;             for (int ne = 0; ne < 8; ++ne) s1 += o[ne][j];
;             const float mean = red16(s1) * (1.f / 128.f); float s2 = 0;
; #pragma unroll
;             for (int ne = 0; ne < 8; ++ne) { const float dd = o[ne][j] - mean; s2 += dd * dd; }
;             const float rstd = 1.f / sqrtf(red16(s2) * (1.f / 128.f) + LN_EPS);
;             const long tok = tok0 + w * 16 + fq * 4 + j;
;             const bfraw* gp = RG + tok * 1024 + head * 128 + fr; bfraw* op = RO + tok * 1024 + head * 128 + fr;
; #pragma unroll
;             for (int ne = 0; ne < 8; ++ne) op[ne * 16] = f2bf((o[ne][j] - mean) * rstd * gw[ne] * bf2f(gp[ne * 16])); }
	v_mov_b32_e32 v38, v88
	v_mfma_f32_16x16x32_bf16 v[24:27], v[68:71], v[76:79], v[24:27]
	v_mov_b32_e32 v39, v89
	v_mov_b32_e32 v88, v82
	v_mov_b32_e32 v89, v83
	v_mfma_f32_16x16x32_bf16 v[20:23], v[72:75], v[36:39], v[20:23]
	s_nop 0
	v_mfma_f32_16x16x32_bf16 v[24:27], v[72:75], v[88:91], v[24:27]
	s_mov_b64 s[2:3], s[0:1]
	s_load_dwordx2 s[4:5], s[2:3], 0x50
	s_lshl_b64 s[2:3], s[54:55], 2
	v_lshlrev_b32_e32 v32, 2, v115
	v_lshl_or_b32 v32, s17, 9, v32
	v_or_b32_e32 v104, s7, v104
	s_waitcnt lgkmcnt(0)
	s_add_u32 s4, s4, s2
	s_addc_u32 s5, s5, s3
	global_load_dword v43, v32, s[4:5]
	s_mov_b64 s[4:5], s[0:1]
	s_load_dwordx2 s[4:5], s[4:5], 0x50
	v_lshlrev_b32_e32 v176, 1, v115
	s_waitcnt lgkmcnt(0)
	s_add_u32 s4, s4, s2
	s_addc_u32 s5, s5, s3
	global_load_dword v36, v32, s[4:5] offset:64
	s_mov_b64 s[4:5], s[0:1]
	s_load_dwordx2 s[4:5], s[4:5], 0x50
	s_waitcnt lgkmcnt(0)
	s_add_u32 s4, s4, s2
	s_addc_u32 s5, s5, s3
	global_load_dword v37, v32, s[4:5] offset:128
	s_mov_b64 s[4:5], s[0:1]
	s_load_dwordx2 s[4:5], s[4:5], 0x50
	s_waitcnt lgkmcnt(0)
	s_add_u32 s4, s4, s2
	s_addc_u32 s5, s5, s3
	global_load_dword v38, v32, s[4:5] offset:192
	s_mov_b64 s[4:5], s[0:1]
	s_load_dwordx2 s[4:5], s[4:5], 0x50
	s_waitcnt lgkmcnt(0)
	s_add_u32 s4, s4, s2
	s_addc_u32 s5, s5, s3
	global_load_dword v39, v32, s[4:5] offset:256
	s_mov_b64 s[4:5], s[0:1]
	s_load_dwordx2 s[4:5], s[4:5], 0x50
	s_waitcnt lgkmcnt(0)
	s_add_u32 s4, s4, s2
	s_addc_u32 s5, s5, s3
	global_load_dword v41, v32, s[4:5] offset:320
	s_mov_b64 s[4:5], s[0:1]
	s_load_dwordx2 s[4:5], s[4:5], 0x50
	s_waitcnt lgkmcnt(0)
	s_add_u32 s4, s4, s2
	s_addc_u32 s5, s5, s3
	global_load_dword v40, v32, s[4:5] offset:384
	s_mov_b64 s[4:5], s[0:1]
	s_load_dwordx2 s[4:5], s[4:5], 0x50
	s_waitcnt lgkmcnt(0)
	s_add_u32 s2, s4, s2
	s_addc_u32 s3, s5, s3
	global_load_dword v42, v32, s[2:3] offset:448
	v_add_f32_e32 v32, 0, v28
	v_add_f32_e32 v32, v32, v0
	v_add_f32_e32 v32, v32, v4
	v_add_f32_e32 v32, v32, v8
	s_mov_b32 s2, -1
	v_add_f32_e32 v32, v32, v12
	v_add_f32_e32 v32, v32, v16
	v_mbcnt_lo_u32_b32 v33, s2, 0
	v_mbcnt_hi_u32_b32 v33, s2, v33
	v_add_f32_e32 v32, v32, v20
	v_lshlrev_b32_e32 v33, 2, v33
	v_add_f32_e32 v32, v32, v24
	v_xor_b32_e32 v34, 4, v33
	s_nop 1
	v_mov_b32_dpp v34, v32 quad_perm:[1,0,3,2] row_mask:0xf bank_mask:0xf
	s_mov_b32 s2, -1
	s_add_i32 s16, s16, s28
	s_add_u32 s8, s8, s72
	s_waitcnt lgkmcnt(0)
	v_add_f32_e32 v32, v32, v34
	v_xor_b32_e32 v34, 8, v33
	s_nop 1
	v_mov_b32_dpp v34, v32 quad_perm:[2,3,0,1] row_mask:0xf bank_mask:0xf
	s_addc_u32 s9, s9, s73
	s_add_i32 s6, s6, s59
	s_cmpk_gt_i32 s16, 0x3ff
	s_waitcnt lgkmcnt(0)
	v_add_f32_e32 v32, v32, v34
	v_xor_b32_e32 v34, 16, v33
	s_nop 1
	v_mov_b32_dpp v34, v32 row_half_mirror row_mask:0xf bank_mask:0xf
	s_nop 1
	v_mov_b32_dpp v34, v34 quad_perm:[3,2,1,0] row_mask:0xf bank_mask:0xf
	v_xor_b32_e32 v33, 32, v33
	s_waitcnt lgkmcnt(0)
	v_add_f32_e32 v32, v32, v34
	s_nop 1
	v_mov_b32_dpp v33, v32 row_ror:8 row_mask:0xf bank_mask:0xf
	s_waitcnt lgkmcnt(0)
	v_add_f32_e32 v32, v32, v33
	v_fmamk_f32 v45, v32, 0xbc000000, v0
	v_fmamk_f32 v50, v32, 0xbc000000, v28
	v_mul_f32_e32 v33, v45, v45
	v_fmac_f32_e32 v33, v50, v50
	v_fmamk_f32 v44, v32, 0xbc000000, v4
	v_fmac_f32_e32 v33, v44, v44
	v_fmamk_f32 v28, v32, 0xbc000000, v8
	v_fmac_f32_e32 v33, v28, v28
	v_fmamk_f32 v12, v32, 0xbc000000, v12
	v_fmac_f32_e32 v33, v12, v12
	v_fmamk_f32 v8, v32, 0xbc000000, v16
	v_mbcnt_lo_u32_b32 v16, s2, 0
	v_fmac_f32_e32 v33, v8, v8
	v_fmamk_f32 v4, v32, 0xbc000000, v20
	v_mbcnt_hi_u32_b32 v16, s2, v16
	v_fmac_f32_e32 v33, v4, v4
	v_fmamk_f32 v0, v32, 0xbc000000, v24
	v_lshlrev_b32_e32 v16, 2, v16
	v_fmac_f32_e32 v33, v0, v0
	v_xor_b32_e32 v20, 4, v16
	s_nop 1
	v_mov_b32_dpp v20, v33 quad_perm:[1,0,3,2] row_mask:0xf bank_mask:0xf
	v_xor_b32_e32 v24, 8, v16
	s_waitcnt lgkmcnt(0)
	v_add_f32_e32 v20, v33, v20
	s_nop 1
	v_mov_b32_dpp v24, v20 quad_perm:[2,3,0,1] row_mask:0xf bank_mask:0xf
	s_waitcnt lgkmcnt(0)
	v_add_f32_e32 v20, v20, v24
	v_xor_b32_e32 v24, 16, v16
	s_nop 1
	v_mov_b32_dpp v24, v20 row_half_mirror row_mask:0xf bank_mask:0xf
	s_nop 1
	v_mov_b32_dpp v24, v24 quad_perm:[3,2,1,0] row_mask:0xf bank_mask:0xf
	v_xor_b32_e32 v16, 32, v16
	s_waitcnt lgkmcnt(0)
	v_add_f32_e32 v20, v20, v24
	s_nop 1
	v_mov_b32_dpp v16, v20 row_ror:8 row_mask:0xf bank_mask:0xf
	s_waitcnt lgkmcnt(0)
	v_add_f32_e32 v16, v20, v16
	v_fmamk_f32 v16, v16, 0x3c000000, v183
	v_cmp_gt_f32_e32 vcc, s30, v16
	v_mul_f32_e32 v20, 0x4f800000, v16
	s_nop 0
	v_cndmask_b32_e32 v16, v16, v20, vcc
	v_sqrt_f32_e32 v20, v16
	s_nop 0
	v_add_u32_e32 v24, -1, v20
	v_fma_f32 v32, -v24, v20, v16
	v_cmp_ge_f32_e64 s[4:5], 0, v32
	v_add_u32_e32 v32, 1, v20
	s_nop 0
	v_cndmask_b32_e64 v24, v20, v24, s[4:5]
	v_fma_f32 v20, -v32, v20, v16
	v_cmp_lt_f32_e64 s[4:5], 0, v20
	s_nop 1
	v_cndmask_b32_e64 v20, v24, v32, s[4:5]
	v_mul_f32_e32 v24, 0x37800000, v20
	v_cndmask_b32_e32 v20, v20, v24, vcc
	v_cmp_class_f32_e32 vcc, v16, v222
	s_nop 1
	v_cndmask_b32_e32 v16, v20, v16, vcc
	s_mov_b64 s[2:3], s[0:1]
	s_load_dwordx2 s[2:3], s[2:3], 0xe8
	v_lshlrev_b64 v[34:35], 11, v[104:105]
	v_rcp_f32_e32 v24, v16
	s_nop 0
	v_fma_f32 v20, -v16, v24, 1.0
	v_fma_f32 v20, v20, v24, v24
	s_waitcnt lgkmcnt(0)
	v_lshl_add_u64 v[32:33], s[2:3], 0, v[34:35]
	v_lshl_add_u64 v[32:33], v[32:33], 0, s[12:13]
	v_lshl_add_u64 v[46:47], v[32:33], 0, v[176:177]
	v_lshl_add_u64 v[32:33], v[46:47], 0, s[42:43]
	v_add_co_u32_e32 v46, vcc, s68, v46
	s_mov_b64 s[2:3], s[0:1]
	s_nop 0
	v_addc_co_u32_e32 v47, vcc, 0, v47, vcc
	global_load_ushort v24, v[46:47], off
	global_load_ushort v184, v[32:33], off offset:32
	global_load_ushort v185, v[32:33], off offset:64
	global_load_ushort v186, v[32:33], off offset:96
	global_load_ushort v187, v[32:33], off offset:128
	global_load_ushort v188, v[32:33], off offset:160
	global_load_ushort v189, v[32:33], off offset:192
	global_load_ushort v190, v[32:33], off offset:224
	s_load_dwordx2 s[2:3], s[2:3], 0xe8
	v_div_fixup_f32 v16, v20, v16, 1.0
	v_mul_f32_e32 v20, v16, v50
	s_waitcnt vmcnt(8)
; DEVFI float bf2f(bfraw h) { return __uint_as_float(((unsigned)h) << 16); }
; DEVFI bfraw f2bf(float x) { unsigned u = __float_as_uint(x); u += 0x7fffu + ((u >> 16) & 1u); return (bfraw)(u >> 16); }
; #define RG ((bfraw*)(kargs()->ws + O_RG))
; #define RO ((bfraw*)(kargs()->ws + O_RO))
; __global__ void __launch_bounds__(512) mega(Params p) {
;     ...
;           for (int j = 0; j < 4; ++j) { float s1 = 0;
; #pragma unroll
;             for (int ne = 0; ne < 8; ++ne) s1 += o[ne][j];
;             const float mean = red16(s1) * (1.f / 128.f); float s2 = 0;
; #pragma unroll
;             for (int ne = 0; ne < 8; ++ne) { const float dd = o[ne][j] - mean; s2 += dd * dd; }
;             const float rstd = 1.f / sqrtf(red16(s2) * (1.f / 128.f) + LN_EPS);
;             const long tok = tok0 + w * 16 + fq * 4 + j;
;             const bfraw* gp = RG + tok * 1024 + head * 128 + fr; bfraw* op = RO + tok * 1024 + head * 128 + fr;
; #pragma unroll
;             for (int ne = 0; ne < 8; ++ne) op[ne * 16] = f2bf((o[ne][j] - mean) * rstd * gw[ne] * bf2f(gp[ne * 16])); }
	v_mul_f32_e32 v20, v20, v43
	v_mul_f32_e32 v12, v16, v12
	s_waitcnt lgkmcnt(0)
	v_lshl_add_u64 v[34:35], s[2:3], 0, v[34:35]
	v_lshl_add_u64 v[34:35], v[34:35], 0, s[12:13]
	v_lshl_add_u64 v[48:49], v[34:35], 0, v[176:177]
	v_add_co_u32_e32 v46, vcc, s69, v48
	v_lshl_add_u64 v[34:35], v[48:49], 0, s[50:51]
	s_nop 0
	v_addc_co_u32_e32 v47, vcc, 0, v49, vcc
	s_waitcnt vmcnt(4)
	v_mul_f32_e32 v12, v12, v39
	v_mul_f32_e32 v8, v16, v8
	s_waitcnt vmcnt(3)
	v_mul_f32_e32 v8, v8, v41
	v_mul_f32_e32 v4, v16, v4
	s_waitcnt vmcnt(2)
	v_mul_f32_e32 v4, v4, v40
	v_mul_f32_e32 v0, v16, v0
	s_waitcnt vmcnt(1)
	v_mul_f32_e32 v0, v0, v42
	s_mov_b32 s2, -1
	v_or_b32_e32 v104, s7, v86
	s_waitcnt vmcnt(0)
	v_lshlrev_b32_e32 v24, 16, v24
	v_mul_f32_e32 v20, v20, v24
	v_cvt_pk_bf16_f32 v20, v20, v20
	global_store_short_d16_hi v[46:47], v20, off
	v_mul_f32_e32 v20, v16, v45
	v_mul_f32_e32 v20, v20, v36
	v_lshlrev_b32_e32 v24, 16, v184
	v_mul_f32_e32 v20, v20, v24
	v_cvt_pk_bf16_f32 v20, v20, v20
	global_store_short_d16_hi v[34:35], v20, off offset:32
	v_mul_f32_e32 v20, v16, v44
	v_mul_f32_e32 v20, v20, v37
	v_lshlrev_b32_e32 v24, 16, v185
	v_mul_f32_e32 v20, v20, v24
	v_cvt_pk_bf16_f32 v20, v20, v20
	global_store_short_d16_hi v[34:35], v20, off offset:64
	v_mul_f32_e32 v20, v16, v28
	v_mul_f32_e32 v20, v20, v38
	v_lshlrev_b32_e32 v24, 16, v186
	v_mul_f32_e32 v20, v20, v24
	v_cvt_pk_bf16_f32 v20, v20, v20
	global_store_short_d16_hi v[34:35], v20, off offset:96
	v_lshlrev_b32_e32 v20, 16, v187
	v_mul_f32_e32 v12, v12, v20
	v_cvt_pk_bf16_f32 v12, v12, v12
	global_store_short_d16_hi v[34:35], v12, off offset:128
	v_lshlrev_b32_e32 v12, 16, v188
	v_mul_f32_e32 v8, v8, v12
	v_cvt_pk_bf16_f32 v8, v8, v8
	global_store_short_d16_hi v[34:35], v8, off offset:160
	v_lshlrev_b32_e32 v8, 16, v189
	v_mul_f32_e32 v4, v4, v8
	v_cvt_pk_bf16_f32 v4, v4, v4
	global_store_short_d16_hi v[34:35], v4, off offset:192
	v_lshlrev_b32_e32 v4, 16, v190
	v_mul_f32_e32 v0, v0, v4
	v_cvt_pk_bf16_f32 v0, v0, v0
	global_store_short_d16_hi v[34:35], v0, off offset:224
	v_add_f32_e32 v0, 0, v29
	v_add_f32_e32 v0, v0, v1
	v_add_f32_e32 v0, v0, v5
	v_add_f32_e32 v0, v0, v9
	v_add_f32_e32 v0, v0, v13
	v_add_f32_e32 v0, v0, v17
	v_mbcnt_lo_u32_b32 v4, s2, 0
	v_mbcnt_hi_u32_b32 v4, s2, v4
	v_add_f32_e32 v0, v0, v21
	v_lshlrev_b32_e32 v4, 2, v4
	v_add_f32_e32 v0, v0, v25
	v_xor_b32_e32 v8, 4, v4
	s_nop 1
	v_mov_b32_dpp v8, v0 quad_perm:[1,0,3,2] row_mask:0xf bank_mask:0xf
	s_mov_b32 s2, -1
	s_waitcnt lgkmcnt(0)
	v_add_f32_e32 v0, v0, v8
	v_xor_b32_e32 v8, 8, v4
	s_nop 1
	v_mov_b32_dpp v8, v0 quad_perm:[2,3,0,1] row_mask:0xf bank_mask:0xf
	s_waitcnt lgkmcnt(0)
	v_add_f32_e32 v0, v0, v8
	v_xor_b32_e32 v8, 16, v4
	s_nop 1
	v_mov_b32_dpp v8, v0 row_half_mirror row_mask:0xf bank_mask:0xf
	s_nop 1
	v_mov_b32_dpp v8, v8 quad_perm:[3,2,1,0] row_mask:0xf bank_mask:0xf
	v_xor_b32_e32 v4, 32, v4
	s_waitcnt lgkmcnt(0)
	v_add_f32_e32 v0, v0, v8
	s_nop 1
	v_mov_b32_dpp v4, v0 row_ror:8 row_mask:0xf bank_mask:0xf
	s_waitcnt lgkmcnt(0)
	v_add_f32_e32 v0, v0, v4
	v_fmamk_f32 v24, v0, 0xbc000000, v1
	v_fmamk_f32 v34, v0, 0xbc000000, v29
	v_mul_f32_e32 v1, v24, v24
	v_fmac_f32_e32 v1, v34, v34
	v_fmamk_f32 v20, v0, 0xbc000000, v5
	v_fmac_f32_e32 v1, v20, v20
	v_fmamk_f32 v16, v0, 0xbc000000, v9
	v_fmac_f32_e32 v1, v16, v16
	v_fmamk_f32 v13, v0, 0xbc000000, v13
	v_fmac_f32_e32 v1, v13, v13
	v_fmamk_f32 v12, v0, 0xbc000000, v17
	v_fmamk_f32 v9, v0, 0xbc000000, v21
	v_fmamk_f32 v8, v0, 0xbc000000, v25
	v_mbcnt_lo_u32_b32 v0, s2, 0
	v_fmac_f32_e32 v1, v12, v12
	v_mbcnt_hi_u32_b32 v0, s2, v0
	v_fmac_f32_e32 v1, v9, v9
	v_lshlrev_b32_e32 v0, 2, v0
	v_fmac_f32_e32 v1, v8, v8
	v_xor_b32_e32 v4, 4, v0
	s_nop 1
	v_mov_b32_dpp v4, v1 quad_perm:[1,0,3,2] row_mask:0xf bank_mask:0xf
	s_waitcnt lgkmcnt(0)
	v_add_f32_e32 v1, v1, v4
	v_xor_b32_e32 v4, 8, v0
	s_nop 1
	v_mov_b32_dpp v4, v1 quad_perm:[2,3,0,1] row_mask:0xf bank_mask:0xf
	s_waitcnt lgkmcnt(0)
	v_add_f32_e32 v1, v1, v4
	v_xor_b32_e32 v4, 16, v0
	s_nop 1
	v_mov_b32_dpp v4, v1 row_half_mirror row_mask:0xf bank_mask:0xf
	s_nop 1
	v_mov_b32_dpp v4, v4 quad_perm:[3,2,1,0] row_mask:0xf bank_mask:0xf
	v_xor_b32_e32 v0, 32, v0
	s_waitcnt lgkmcnt(0)
	v_add_f32_e32 v1, v1, v4
	s_nop 1
	v_mov_b32_dpp v0, v1 row_ror:8 row_mask:0xf bank_mask:0xf
	s_waitcnt lgkmcnt(0)
	v_add_f32_e32 v0, v1, v0
	v_fmamk_f32 v0, v0, 0x3c000000, v183
	v_cmp_gt_f32_e32 vcc, s30, v0
	v_mul_f32_e32 v1, 0x4f800000, v0
	s_nop 0
	v_cndmask_b32_e32 v0, v0, v1, vcc
	v_sqrt_f32_e32 v1, v0
	s_nop 0
	v_add_u32_e32 v4, -1, v1
	v_fma_f32 v5, -v4, v1, v0
	v_cmp_ge_f32_e64 s[4:5], 0, v5
	v_add_u32_e32 v5, 1, v1
	s_nop 0
	v_cndmask_b32_e64 v4, v1, v4, s[4:5]
	v_fma_f32 v1, -v5, v1, v0
	v_cmp_lt_f32_e64 s[4:5], 0, v1
	s_nop 1
	v_cndmask_b32_e64 v1, v4, v5, s[4:5]
	v_mul_f32_e32 v4, 0x37800000, v1
	v_cndmask_b32_e32 v1, v1, v4, vcc
	v_cmp_class_f32_e32 vcc, v0, v222
	s_nop 1
	v_cndmask_b32_e32 v0, v1, v0, vcc
	s_mov_b64 s[2:3], s[0:1]
	s_load_dwordx2 s[2:3], s[2:3], 0xe8
	v_rcp_f32_e32 v4, v0
	s_nop 0
	v_fma_f32 v1, -v0, v4, 1.0
	v_fma_f32 v1, v1, v4, v4
	v_lshlrev_b64 v[4:5], 11, v[104:105]
	v_div_fixup_f32 v17, v1, v0, 1.0
	s_waitcnt lgkmcnt(0)
	v_lshl_add_u64 v[0:1], s[2:3], 0, v[4:5]
	v_lshl_add_u64 v[0:1], v[0:1], 0, s[12:13]
	v_lshl_add_u64 v[28:29], v[0:1], 0, v[176:177]
	v_lshl_add_u64 v[0:1], v[28:29], 0, s[42:43]
	v_add_co_u32_e32 v28, vcc, s68, v28
	s_mov_b64 s[2:3], s[0:1]
	s_nop 0
	v_addc_co_u32_e32 v29, vcc, 0, v29, vcc
	global_load_ushort v25, v[28:29], off
	global_load_ushort v184, v[0:1], off offset:32
	global_load_ushort v185, v[0:1], off offset:64
	global_load_ushort v186, v[0:1], off offset:96
	global_load_ushort v187, v[0:1], off offset:128
	global_load_ushort v188, v[0:1], off offset:160
	global_load_ushort v189, v[0:1], off offset:192
	global_load_ushort v190, v[0:1], off offset:224
	s_load_dwordx2 s[2:3], s[2:3], 0xe8
	v_mul_f32_e32 v21, v17, v34
	v_mul_f32_e32 v21, v21, v43
	v_mul_f32_e32 v20, v17, v20
	v_mul_f32_e32 v20, v20, v37
	s_waitcnt lgkmcnt(0)
; DEVFI float bf2f(bfraw h) { return __uint_as_float(((unsigned)h) << 16); }
; DEVFI bfraw f2bf(float x) { unsigned u = __float_as_uint(x); u += 0x7fffu + ((u >> 16) & 1u); return (bfraw)(u >> 16); }
; #define RG ((bfraw*)(kargs()->ws + O_RG))
; #define RO ((bfraw*)(kargs()->ws + O_RO))
; __global__ void __launch_bounds__(512) mega(Params p) {
;     ...
;           for (int j = 0; j < 4; ++j) { float s1 = 0;
; #pragma unroll
;             for (int ne = 0; ne < 8; ++ne) s1 += o[ne][j];
;             const float mean = red16(s1) * (1.f / 128.f); float s2 = 0;
; #pragma unroll
;             for (int ne = 0; ne < 8; ++ne) { const float dd = o[ne][j] - mean; s2 += dd * dd; }
;             const float rstd = 1.f / sqrtf(red16(s2) * (1.f / 128.f) + LN_EPS);
;             const long tok = tok0 + w * 16 + fq * 4 + j;
;             const bfraw* gp = RG + tok * 1024 + head * 128 + fr; bfraw* op = RO + tok * 1024 + head * 128 + fr;
; #pragma unroll
;             for (int ne = 0; ne < 8; ++ne) op[ne * 16] = f2bf((o[ne][j] - mean) * rstd * gw[ne] * bf2f(gp[ne * 16])); }
	v_lshl_add_u64 v[4:5], s[2:3], 0, v[4:5]
	v_lshl_add_u64 v[4:5], v[4:5], 0, s[12:13]
	v_lshl_add_u64 v[32:33], v[4:5], 0, v[176:177]
	v_add_co_u32_e32 v28, vcc, s69, v32
	v_lshl_add_u64 v[4:5], v[32:33], 0, s[50:51]
	s_nop 0
	v_addc_co_u32_e32 v29, vcc, 0, v33, vcc
	v_mul_f32_e32 v16, v17, v16
	v_mul_f32_e32 v16, v16, v38
	v_mul_f32_e32 v13, v17, v13
	v_mul_f32_e32 v13, v13, v39
	v_mul_f32_e32 v12, v17, v12
	v_mul_f32_e32 v12, v12, v41
	v_mul_f32_e32 v9, v17, v9
	v_mul_f32_e32 v9, v9, v40
	v_mul_f32_e32 v8, v17, v8
	v_mul_f32_e32 v8, v8, v42
	s_mov_b32 s2, -1
	v_or_b32_e32 v104, s7, v85
	s_waitcnt vmcnt(0)
	v_lshlrev_b32_e32 v25, 16, v25
	v_mul_f32_e32 v21, v21, v25
	v_bfe_u32 v25, v21, 16, 1
	v_add3_u32 v21, v21, v25, s82
	global_store_short_d16_hi v[28:29], v21, off
	v_mul_f32_e32 v21, v17, v24
	v_mul_f32_e32 v21, v21, v36
	v_lshlrev_b32_e32 v24, 16, v184
	v_mul_f32_e32 v21, v21, v24
	v_cvt_pk_bf16_f32 v21, v21, v21
	global_store_short_d16_hi v[4:5], v21, off offset:32
	v_lshlrev_b32_e32 v21, 16, v185
	v_mul_f32_e32 v20, v20, v21
	v_cvt_pk_bf16_f32 v20, v20, v20
	global_store_short_d16_hi v[4:5], v20, off offset:64
	v_lshlrev_b32_e32 v20, 16, v186
	v_mul_f32_e32 v16, v16, v20
	v_cvt_pk_bf16_f32 v16, v16, v16
	global_store_short_d16_hi v[4:5], v16, off offset:96
	v_lshlrev_b32_e32 v16, 16, v187
	v_mul_f32_e32 v13, v13, v16
	v_cvt_pk_bf16_f32 v13, v13, v13
	global_store_short_d16_hi v[4:5], v13, off offset:128
	v_lshlrev_b32_e32 v13, 16, v188
	v_mul_f32_e32 v12, v12, v13
	v_cvt_pk_bf16_f32 v12, v12, v12
	global_store_short_d16_hi v[4:5], v12, off offset:160
	v_lshlrev_b32_e32 v12, 16, v189
	v_mul_f32_e32 v9, v9, v12
	v_cvt_pk_bf16_f32 v9, v9, v9
	global_store_short_d16_hi v[4:5], v9, off offset:192
	v_lshlrev_b32_e32 v0, 16, v190
	v_mul_f32_e32 v0, v8, v0
	v_cvt_pk_bf16_f32 v0, v0, v0
	global_store_short_d16_hi v[4:5], v0, off offset:224
	v_add_f32_e32 v0, 0, v30
	v_add_f32_e32 v0, v0, v2
	v_add_f32_e32 v0, v0, v6
	v_add_f32_e32 v0, v0, v10
	v_add_f32_e32 v0, v0, v14
	v_add_f32_e32 v0, v0, v18
	v_mbcnt_lo_u32_b32 v1, s2, 0
	v_mbcnt_hi_u32_b32 v1, s2, v1
	v_add_f32_e32 v0, v0, v22
	v_lshlrev_b32_e32 v1, 2, v1
	v_add_f32_e32 v0, v0, v26
	v_xor_b32_e32 v4, 4, v1
	s_nop 1
	v_mov_b32_dpp v4, v0 quad_perm:[1,0,3,2] row_mask:0xf bank_mask:0xf
	s_mov_b32 s2, -1
	s_waitcnt lgkmcnt(0)
	v_add_f32_e32 v0, v0, v4
	v_xor_b32_e32 v4, 8, v1
	s_nop 1
	v_mov_b32_dpp v4, v0 quad_perm:[2,3,0,1] row_mask:0xf bank_mask:0xf
	s_waitcnt lgkmcnt(0)
	v_add_f32_e32 v0, v0, v4
	v_xor_b32_e32 v4, 16, v1
	s_nop 1
	v_mov_b32_dpp v4, v0 row_half_mirror row_mask:0xf bank_mask:0xf
	s_nop 1
	v_mov_b32_dpp v4, v4 quad_perm:[3,2,1,0] row_mask:0xf bank_mask:0xf
	v_xor_b32_e32 v1, 32, v1
	s_waitcnt lgkmcnt(0)
	v_add_f32_e32 v0, v0, v4
	s_nop 1
	v_mov_b32_dpp v1, v0 row_ror:8 row_mask:0xf bank_mask:0xf
	s_waitcnt lgkmcnt(0)
	v_add_f32_e32 v0, v0, v1
	v_fmamk_f32 v13, v0, 0xbc000000, v2
	v_fmamk_f32 v24, v0, 0xbc000000, v30
	v_mul_f32_e32 v1, v13, v13
	v_fmac_f32_e32 v1, v24, v24
	v_fmamk_f32 v12, v0, 0xbc000000, v6
	v_fmac_f32_e32 v1, v12, v12
	v_fmamk_f32 v10, v0, 0xbc000000, v10
	v_fmac_f32_e32 v1, v10, v10
	v_fmamk_f32 v9, v0, 0xbc000000, v14
	v_fmac_f32_e32 v1, v9, v9
	v_fmamk_f32 v8, v0, 0xbc000000, v18
	v_fmamk_f32 v6, v0, 0xbc000000, v22
	v_fmamk_f32 v2, v0, 0xbc000000, v26
	v_mbcnt_lo_u32_b32 v0, s2, 0
	v_fmac_f32_e32 v1, v8, v8
	v_mbcnt_hi_u32_b32 v0, s2, v0
	v_fmac_f32_e32 v1, v6, v6
	v_lshlrev_b32_e32 v0, 2, v0
	v_fmac_f32_e32 v1, v2, v2
	v_xor_b32_e32 v4, 4, v0
	s_nop 1
	v_mov_b32_dpp v4, v1 quad_perm:[1,0,3,2] row_mask:0xf bank_mask:0xf
	s_waitcnt lgkmcnt(0)
	v_add_f32_e32 v1, v1, v4
	v_xor_b32_e32 v4, 8, v0
	s_nop 1
	v_mov_b32_dpp v4, v1 quad_perm:[2,3,0,1] row_mask:0xf bank_mask:0xf
	s_waitcnt lgkmcnt(0)
	v_add_f32_e32 v1, v1, v4
	v_xor_b32_e32 v4, 16, v0
	s_nop 1
	v_mov_b32_dpp v4, v1 row_half_mirror row_mask:0xf bank_mask:0xf
	s_nop 1
	v_mov_b32_dpp v4, v4 quad_perm:[3,2,1,0] row_mask:0xf bank_mask:0xf
	v_xor_b32_e32 v0, 32, v0
	s_waitcnt lgkmcnt(0)
	v_add_f32_e32 v1, v1, v4
	s_nop 1
	v_mov_b32_dpp v0, v1 row_ror:8 row_mask:0xf bank_mask:0xf
	s_waitcnt lgkmcnt(0)
	v_add_f32_e32 v0, v1, v0
	v_fmamk_f32 v0, v0, 0x3c000000, v183
	v_cmp_gt_f32_e32 vcc, s30, v0
	v_mul_f32_e32 v1, 0x4f800000, v0
	s_nop 0
	v_cndmask_b32_e32 v0, v0, v1, vcc
	v_sqrt_f32_e32 v1, v0
	s_nop 0
	v_add_u32_e32 v4, -1, v1
	v_fma_f32 v5, -v4, v1, v0
	v_cmp_ge_f32_e64 s[4:5], 0, v5
	v_add_u32_e32 v5, 1, v1
	s_nop 0
	v_cndmask_b32_e64 v4, v1, v4, s[4:5]
	v_fma_f32 v1, -v5, v1, v0
	v_cmp_lt_f32_e64 s[4:5], 0, v1
	s_nop 1
	v_cndmask_b32_e64 v1, v4, v5, s[4:5]
	v_mul_f32_e32 v4, 0x37800000, v1
	v_cndmask_b32_e32 v1, v1, v4, vcc
	v_cmp_class_f32_e32 vcc, v0, v222
	s_nop 1
	v_cndmask_b32_e32 v0, v1, v0, vcc
	s_mov_b64 s[2:3], s[0:1]
	s_load_dwordx2 s[2:3], s[2:3], 0xe8
	v_rcp_f32_e32 v4, v0
	s_nop 0
	v_fma_f32 v1, -v0, v4, 1.0
	v_fma_f32 v1, v1, v4, v4
	v_lshlrev_b64 v[4:5], 11, v[104:105]
	v_div_fixup_f32 v14, v1, v0, 1.0
	s_waitcnt lgkmcnt(0)
	v_lshl_add_u64 v[0:1], s[2:3], 0, v[4:5]
	v_lshl_add_u64 v[0:1], v[0:1], 0, s[12:13]
	v_lshl_add_u64 v[16:17], v[0:1], 0, v[176:177]
	v_lshl_add_u64 v[0:1], v[16:17], 0, s[42:43]
	v_add_co_u32_e32 v16, vcc, s68, v16
	s_mov_b64 s[2:3], s[0:1]
	s_nop 0
	v_addc_co_u32_e32 v17, vcc, 0, v17, vcc
	global_load_ushort v16, v[16:17], off
	global_load_ushort v184, v[0:1], off offset:32
	global_load_ushort v185, v[0:1], off offset:64
	global_load_ushort v186, v[0:1], off offset:96
	global_load_ushort v187, v[0:1], off offset:128
	global_load_ushort v188, v[0:1], off offset:160
	global_load_ushort v189, v[0:1], off offset:192
	global_load_ushort v190, v[0:1], off offset:224
	s_load_dwordx2 s[2:3], s[2:3], 0xe8
	v_mul_f32_e32 v18, v14, v24
	v_mul_f32_e32 v18, v18, v43
	v_mul_f32_e32 v13, v14, v13
	v_mul_f32_e32 v13, v13, v36
	s_waitcnt lgkmcnt(0)
; DEVFI float bf2f(bfraw h) { return __uint_as_float(((unsigned)h) << 16); }
; DEVFI bfraw f2bf(float x) { unsigned u = __float_as_uint(x); u += 0x7fffu + ((u >> 16) & 1u); return (bfraw)(u >> 16); }
; #define RG ((bfraw*)(kargs()->ws + O_RG))
; #define RO ((bfraw*)(kargs()->ws + O_RO))
; __global__ void __launch_bounds__(512) mega(Params p) {
;     ...
;           for (int j = 0; j < 4; ++j) { float s1 = 0;
; #pragma unroll
;             for (int ne = 0; ne < 8; ++ne) s1 += o[ne][j];
;             const float mean = red16(s1) * (1.f / 128.f); float s2 = 0;
; #pragma unroll
;             for (int ne = 0; ne < 8; ++ne) { const float dd = o[ne][j] - mean; s2 += dd * dd; }
;             const float rstd = 1.f / sqrtf(red16(s2) * (1.f / 128.f) + LN_EPS);
;             const long tok = tok0 + w * 16 + fq * 4 + j;
;             const bfraw* gp = RG + tok * 1024 + head * 128 + fr; bfraw* op = RO + tok * 1024 + head * 128 + fr;
; #pragma unroll
;             for (int ne = 0; ne < 8; ++ne) op[ne * 16] = f2bf((o[ne][j] - mean) * rstd * gw[ne] * bf2f(gp[ne * 16])); }
	v_lshl_add_u64 v[4:5], s[2:3], 0, v[4:5]
	v_lshl_add_u64 v[4:5], v[4:5], 0, s[12:13]
	v_lshl_add_u64 v[20:21], v[4:5], 0, v[176:177]
	v_lshl_add_u64 v[4:5], v[20:21], 0, s[50:51]
	v_mul_f32_e32 v12, v14, v12
	v_mul_f32_e32 v12, v12, v37
	v_mul_f32_e32 v10, v14, v10
	v_mul_f32_e32 v10, v10, v38
	v_mul_f32_e32 v9, v14, v9
	v_mul_f32_e32 v9, v9, v39
	v_mul_f32_e32 v8, v14, v8
	v_mul_f32_e32 v8, v8, v41
	v_mul_f32_e32 v6, v14, v6
	v_mul_f32_e32 v6, v6, v40
	v_mul_f32_e32 v2, v14, v2
	v_mul_f32_e32 v2, v2, v42
	s_mov_b32 s2, -1
	v_or_b32_e32 v104, s7, v84
	s_waitcnt vmcnt(0)
	v_lshlrev_b32_e32 v16, 16, v16
	v_mul_f32_e32 v16, v18, v16
	v_cvt_pk_bf16_f32 v18, v16, v16
	v_add_co_u32_e32 v16, vcc, s69, v20
	s_nop 1
	v_addc_co_u32_e32 v17, vcc, 0, v21, vcc
	global_store_short_d16_hi v[16:17], v18, off
	v_lshlrev_b32_e32 v16, 16, v184
	v_mul_f32_e32 v13, v13, v16
	v_bfe_u32 v16, v13, 16, 1
	v_add3_u32 v13, v13, v16, s82
	global_store_short_d16_hi v[4:5], v13, off offset:32
	v_lshlrev_b32_e32 v13, 16, v185
	v_mul_f32_e32 v12, v12, v13
	v_cvt_pk_bf16_f32 v12, v12, v12
	global_store_short_d16_hi v[4:5], v12, off offset:64
	v_lshlrev_b32_e32 v12, 16, v186
	v_mul_f32_e32 v10, v10, v12
	v_cvt_pk_bf16_f32 v10, v10, v10
	global_store_short_d16_hi v[4:5], v10, off offset:96
	v_lshlrev_b32_e32 v10, 16, v187
	v_mul_f32_e32 v9, v9, v10
	v_bfe_u32 v10, v9, 16, 1
	v_add3_u32 v9, v9, v10, s82
	global_store_short_d16_hi v[4:5], v9, off offset:128
	v_lshlrev_b32_e32 v9, 16, v188
	v_mul_f32_e32 v8, v8, v9
	v_cvt_pk_bf16_f32 v8, v8, v8
	global_store_short_d16_hi v[4:5], v8, off offset:160
	v_lshlrev_b32_e32 v8, 16, v189
	v_mul_f32_e32 v6, v6, v8
	v_cvt_pk_bf16_f32 v6, v6, v6
	global_store_short_d16_hi v[4:5], v6, off offset:192
	v_lshlrev_b32_e32 v0, 16, v190
	v_mul_f32_e32 v0, v2, v0
	v_cvt_pk_bf16_f32 v0, v0, v0
	global_store_short_d16_hi v[4:5], v0, off offset:224
	v_add_f32_e32 v0, 0, v31
	v_add_f32_e32 v0, v0, v3
	v_add_f32_e32 v0, v0, v7
	v_add_f32_e32 v0, v0, v11
	v_add_f32_e32 v0, v0, v15
	v_add_f32_e32 v0, v0, v19
	v_mbcnt_lo_u32_b32 v1, s2, 0
	v_mbcnt_hi_u32_b32 v1, s2, v1
	v_add_f32_e32 v0, v0, v23
	v_lshlrev_b32_e32 v1, 2, v1
	v_add_f32_e32 v0, v0, v27
	v_xor_b32_e32 v2, 4, v1
	s_nop 1
	v_mov_b32_dpp v2, v0 quad_perm:[1,0,3,2] row_mask:0xf bank_mask:0xf
	s_mov_b32 s2, -1
	s_waitcnt lgkmcnt(0)
	v_add_f32_e32 v0, v0, v2
	v_xor_b32_e32 v2, 8, v1
	s_nop 1
	v_mov_b32_dpp v2, v0 quad_perm:[2,3,0,1] row_mask:0xf bank_mask:0xf
	s_waitcnt lgkmcnt(0)
	v_add_f32_e32 v0, v0, v2
	v_xor_b32_e32 v2, 16, v1
	s_nop 1
	v_mov_b32_dpp v2, v0 row_half_mirror row_mask:0xf bank_mask:0xf
	s_nop 1
	v_mov_b32_dpp v2, v2 quad_perm:[3,2,1,0] row_mask:0xf bank_mask:0xf
	v_xor_b32_e32 v1, 32, v1
	s_waitcnt lgkmcnt(0)
	v_add_f32_e32 v0, v0, v2
	s_nop 1
	v_mov_b32_dpp v1, v0 row_ror:8 row_mask:0xf bank_mask:0xf
	s_waitcnt lgkmcnt(0)
	v_add_f32_e32 v0, v0, v1
	v_fmac_f32_e32 v3, 0xbc000000, v0
	v_fmac_f32_e32 v31, 0xbc000000, v0
	v_mul_f32_e32 v1, v3, v3
	v_fmac_f32_e32 v1, v31, v31
	v_fmac_f32_e32 v7, 0xbc000000, v0
	v_fmac_f32_e32 v1, v7, v7
	v_fmac_f32_e32 v11, 0xbc000000, v0
	v_fmac_f32_e32 v1, v11, v11
	v_fmac_f32_e32 v15, 0xbc000000, v0
	v_fmac_f32_e32 v1, v15, v15
	v_fmac_f32_e32 v19, 0xbc000000, v0
	v_fmac_f32_e32 v23, 0xbc000000, v0
	v_fmac_f32_e32 v27, 0xbc000000, v0
	v_mbcnt_lo_u32_b32 v0, s2, 0
	v_fmac_f32_e32 v1, v19, v19
	v_mbcnt_hi_u32_b32 v0, s2, v0
	v_fmac_f32_e32 v1, v23, v23
	v_lshlrev_b32_e32 v0, 2, v0
	v_fmac_f32_e32 v1, v27, v27
	v_xor_b32_e32 v2, 4, v0
	s_nop 1
	v_mov_b32_dpp v2, v1 quad_perm:[1,0,3,2] row_mask:0xf bank_mask:0xf
	s_waitcnt lgkmcnt(0)
	v_add_f32_e32 v1, v1, v2
	v_xor_b32_e32 v2, 8, v0
	s_nop 1
	v_mov_b32_dpp v2, v1 quad_perm:[2,3,0,1] row_mask:0xf bank_mask:0xf
	s_waitcnt lgkmcnt(0)
; DEVFI float bf2f(bfraw h) { return __uint_as_float(((unsigned)h) << 16); }
; DEVFI bfraw f2bf(float x) { unsigned u = __float_as_uint(x); u += 0x7fffu + ((u >> 16) & 1u); return (bfraw)(u >> 16); }
; #define RG ((bfraw*)(kargs()->ws + O_RG))
; #define RO ((bfraw*)(kargs()->ws + O_RO))
; __global__ void __launch_bounds__(512) mega(Params p) {
;     ...
;           for (int j = 0; j < 4; ++j) { float s1 = 0;
; #pragma unroll
;             for (int ne = 0; ne < 8; ++ne) s1 += o[ne][j];
;             const float mean = red16(s1) * (1.f / 128.f); float s2 = 0;
; #pragma unroll
;             for (int ne = 0; ne < 8; ++ne) { const float dd = o[ne][j] - mean; s2 += dd * dd; }
;             const float rstd = 1.f / sqrtf(red16(s2) * (1.f / 128.f) + LN_EPS);
;             const long tok = tok0 + w * 16 + fq * 4 + j;
;             const bfraw* gp = RG + tok * 1024 + head * 128 + fr; bfraw* op = RO + tok * 1024 + head * 128 + fr;
; #pragma unroll
;             for (int ne = 0; ne < 8; ++ne) op[ne * 16] = f2bf((o[ne][j] - mean) * rstd * gw[ne] * bf2f(gp[ne * 16])); }
;         }
	v_add_f32_e32 v1, v1, v2
	v_xor_b32_e32 v2, 16, v0
	s_nop 1
	v_mov_b32_dpp v2, v1 row_half_mirror row_mask:0xf bank_mask:0xf
	s_nop 1
	v_mov_b32_dpp v2, v2 quad_perm:[3,2,1,0] row_mask:0xf bank_mask:0xf
	v_xor_b32_e32 v0, 32, v0
	s_waitcnt lgkmcnt(0)
	v_add_f32_e32 v1, v1, v2
	s_nop 1
	v_mov_b32_dpp v0, v1 row_ror:8 row_mask:0xf bank_mask:0xf
	s_waitcnt lgkmcnt(0)
	v_add_f32_e32 v0, v1, v0
	v_fmamk_f32 v0, v0, 0x3c000000, v183
	v_cmp_gt_f32_e32 vcc, s30, v0
	v_mul_f32_e32 v1, 0x4f800000, v0
	s_nop 0
	v_cndmask_b32_e32 v0, v0, v1, vcc
	v_sqrt_f32_e32 v1, v0
	s_nop 0
	v_add_u32_e32 v2, -1, v1
	v_fma_f32 v4, -v2, v1, v0
	v_cmp_ge_f32_e64 s[4:5], 0, v4
	v_add_u32_e32 v4, 1, v1
	s_nop 0
	v_cndmask_b32_e64 v2, v1, v2, s[4:5]
	v_fma_f32 v1, -v4, v1, v0
	v_cmp_lt_f32_e64 s[4:5], 0, v1
	s_nop 1
	v_cndmask_b32_e64 v1, v2, v4, s[4:5]
	v_mul_f32_e32 v2, 0x37800000, v1
	v_cndmask_b32_e32 v1, v1, v2, vcc
	v_cmp_class_f32_e32 vcc, v0, v222
	s_nop 1
	v_cndmask_b32_e32 v0, v1, v0, vcc
	s_mov_b64 s[2:3], s[0:1]
	s_load_dwordx2 s[2:3], s[2:3], 0xe8
	v_rcp_f32_e32 v2, v0
	s_nop 0
	v_fma_f32 v1, -v0, v2, 1.0
	v_fma_f32 v1, v1, v2, v2
	v_lshlrev_b64 v[4:5], 11, v[104:105]
	v_div_fixup_f32 v2, v1, v0, 1.0
	s_waitcnt lgkmcnt(0)
	v_lshl_add_u64 v[0:1], s[2:3], 0, v[4:5]
	v_lshl_add_u64 v[0:1], v[0:1], 0, s[12:13]
	v_lshl_add_u64 v[8:9], v[0:1], 0, v[176:177]
	v_lshl_add_u64 v[0:1], v[8:9], 0, s[42:43]
	v_add_co_u32_e32 v8, vcc, s68, v8
	s_mov_b64 s[2:3], s[0:1]
	s_nop 0
	v_addc_co_u32_e32 v9, vcc, 0, v9, vcc
	global_load_ushort v8, v[8:9], off
	global_load_ushort v184, v[0:1], off offset:32
	global_load_ushort v185, v[0:1], off offset:64
	global_load_ushort v186, v[0:1], off offset:96
	global_load_ushort v187, v[0:1], off offset:128
	global_load_ushort v188, v[0:1], off offset:160
	global_load_ushort v189, v[0:1], off offset:192
	global_load_ushort v190, v[0:1], off offset:224
	s_load_dwordx2 s[2:3], s[2:3], 0xe8
	v_mul_f32_e32 v6, v2, v31
	v_mul_f32_e32 v6, v6, v43
	v_mul_f32_e32 v3, v2, v3
	v_mul_f32_e32 v3, v3, v36
	s_waitcnt lgkmcnt(0)
	v_lshl_add_u64 v[4:5], s[2:3], 0, v[4:5]
	v_lshl_add_u64 v[4:5], v[4:5], 0, s[12:13]
	v_lshl_add_u64 v[12:13], v[4:5], 0, v[176:177]
	v_lshl_add_u64 v[4:5], v[12:13], 0, s[50:51]
	s_waitcnt vmcnt(0)
	v_lshlrev_b32_e32 v8, 16, v8
	v_mul_f32_e32 v6, v6, v8
	v_cvt_pk_bf16_f32 v6, v6, v6
	v_add_co_u32_e32 v8, vcc, s69, v12
	s_nop 1
	v_addc_co_u32_e32 v9, vcc, 0, v13, vcc
	global_store_short_d16_hi v[8:9], v6, off
	v_lshlrev_b32_e32 v6, 16, v184
	v_mul_f32_e32 v3, v3, v6
	v_cvt_pk_bf16_f32 v3, v3, v3
	global_store_short_d16_hi v[4:5], v3, off offset:32
	v_mul_f32_e32 v3, v2, v7
	v_mul_f32_e32 v3, v3, v37
	v_lshlrev_b32_e32 v6, 16, v185
	v_mul_f32_e32 v3, v3, v6
	v_cvt_pk_bf16_f32 v3, v3, v3
	global_store_short_d16_hi v[4:5], v3, off offset:64
	v_mul_f32_e32 v3, v2, v11
	v_mul_f32_e32 v3, v3, v38
	v_lshlrev_b32_e32 v6, 16, v186
	v_mul_f32_e32 v3, v3, v6
	v_cvt_pk_bf16_f32 v3, v3, v3
	global_store_short_d16_hi v[4:5], v3, off offset:96
	v_mul_f32_e32 v3, v2, v15
	v_mul_f32_e32 v3, v3, v39
	v_lshlrev_b32_e32 v6, 16, v187
	v_mul_f32_e32 v3, v3, v6
	v_cvt_pk_bf16_f32 v3, v3, v3
	global_store_short_d16_hi v[4:5], v3, off offset:128
	v_mul_f32_e32 v3, v2, v19
	v_mul_f32_e32 v3, v3, v41
	v_lshlrev_b32_e32 v6, 16, v188
	v_mul_f32_e32 v3, v3, v6
	v_cvt_pk_bf16_f32 v3, v3, v3
	global_store_short_d16_hi v[4:5], v3, off offset:160
	v_mul_f32_e32 v3, v2, v23
	v_mul_f32_e32 v3, v3, v40
	v_mul_f32_e32 v2, v2, v27
	v_mul_f32_e32 v2, v2, v42
	v_lshlrev_b32_e32 v6, 16, v189
	v_mul_f32_e32 v3, v3, v6
	v_bfe_u32 v6, v3, 16, 1
	v_add3_u32 v3, v3, v6, s82
	global_store_short_d16_hi v[4:5], v3, off offset:192
	v_lshlrev_b32_e32 v0, 16, v190
	v_mul_f32_e32 v0, v2, v0
	v_bfe_u32 v1, v0, 16, 1
	v_add3_u32 v0, v0, v1, s82
	global_store_short_d16_hi v[4:5], v0, off offset:224
	s_cbranch_scc0 .LBB0_2481
